# GEMM MFMA blocks: priority window (s_setprio 0/1) after every 8 MFMAs instead of every 16, on top of attention P.V priority
# speedup vs baseline: 1.0010x; 1.0010x over previous
.LBB0_122:
	ds_read_b128 v[152:155], v148
	ds_read_b128 v[156:159], v148 offset:1024
	ds_read_b128 v[160:163], v148 offset:2048
	ds_read_b128 v[164:167], v148 offset:3072
	ds_read_b128 v[168:171], v149
	ds_read_b128 v[172:175], v149 offset:1024
	ds_read_b128 v[176:179], v149 offset:2048
	ds_read_b128 v[180:183], v149 offset:3072
	s_add_u32 s44, s36, 0xfff80080
	s_addc_u32 s45, s37, -1
	s_cmp_eq_u32 s54, 28
	s_cselect_b32 s53, s25, s45
	s_cselect_b32 s52, s48, s44
	s_cselect_b32 s45, s23, s51
	s_cselect_b32 s44, s49, s50
	v_lshl_add_u64 v[216:217], s[36:37], 0, v[140:141]
	s_add_i32 m0, s18, 0xc000
	ds_read_b128 v[184:187], v150
	ds_read_b128 v[188:191], v150 offset:1024
	ds_read_b128 v[192:195], v150 offset:2048
	ds_read_b128 v[196:199], v150 offset:3072
	ds_read_b128 v[200:203], v150 offset:4096
	ds_read_b128 v[204:207], v150 offset:5120
	ds_read_b128 v[208:211], v150 offset:6144
	ds_read_b128 v[212:215], v150 offset:7168
	global_load_lds_dwordx4 v[216:217], off
	v_lshl_add_u64 v[216:217], s[36:37], 0, v[138:139]
	s_add_i32 m0, s18, 0xe000
	s_nop 0
	global_load_lds_dwordx4 v[216:217], off
	s_waitcnt vmcnt(8)
	s_waitcnt lgkmcnt(0)
	s_setprio 1
	s_barrier
	v_mfma_f32_16x16x32_bf16 v[126:129], v[152:155], v[184:187], v[126:129]
	v_mfma_f32_16x16x32_bf16 v[122:125], v[160:163], v[184:187], v[122:125]
	v_mfma_f32_16x16x32_bf16 v[110:113], v[152:155], v[192:195], v[110:113]
	v_mfma_f32_16x16x32_bf16 v[106:109], v[160:163], v[192:195], v[106:109]
	v_mfma_f32_16x16x32_bf16 v[94:97], v[152:155], v[200:203], v[94:97]
	v_mfma_f32_16x16x32_bf16 v[90:93], v[160:163], v[200:203], v[90:93]
	v_mfma_f32_16x16x32_bf16 v[78:81], v[152:155], v[208:211], v[78:81]
	v_mfma_f32_16x16x32_bf16 v[74:77], v[160:163], v[208:211], v[74:77]
	s_setprio 0
	s_setprio 1
	v_mfma_f32_16x16x32_bf16 v[126:129], v[156:159], v[188:191], v[126:129]
	v_mfma_f32_16x16x32_bf16 v[122:125], v[164:167], v[188:191], v[122:125]
	v_mfma_f32_16x16x32_bf16 v[110:113], v[156:159], v[196:199], v[110:113]
	v_mfma_f32_16x16x32_bf16 v[106:109], v[164:167], v[196:199], v[106:109]
	v_mfma_f32_16x16x32_bf16 v[94:97], v[156:159], v[204:207], v[94:97]
	v_mfma_f32_16x16x32_bf16 v[90:93], v[164:167], v[204:207], v[90:93]
	v_mfma_f32_16x16x32_bf16 v[78:81], v[156:159], v[212:215], v[78:81]
	v_mfma_f32_16x16x32_bf16 v[74:77], v[164:167], v[212:215], v[74:77]
	s_setprio 0
	s_setprio 1
	v_mfma_f32_16x16x32_bf16 v[118:121], v[168:171], v[184:187], v[118:121]
	v_mfma_f32_16x16x32_bf16 v[114:117], v[176:179], v[184:187], v[114:117]
	v_mfma_f32_16x16x32_bf16 v[102:105], v[168:171], v[192:195], v[102:105]
	v_mfma_f32_16x16x32_bf16 v[98:101], v[176:179], v[192:195], v[98:101]
	v_mfma_f32_16x16x32_bf16 v[86:89], v[168:171], v[200:203], v[86:89]
	v_mfma_f32_16x16x32_bf16 v[82:85], v[176:179], v[200:203], v[82:85]
	v_mfma_f32_16x16x32_bf16 v[70:73], v[168:171], v[208:211], v[70:73]
	v_mfma_f32_16x16x32_bf16 v[66:69], v[176:179], v[208:211], v[66:69]
	s_setprio 0
	s_setprio 1
	v_mfma_f32_16x16x32_bf16 v[118:121], v[172:175], v[188:191], v[118:121]
	v_mfma_f32_16x16x32_bf16 v[114:117], v[180:183], v[188:191], v[114:117]
	v_mfma_f32_16x16x32_bf16 v[102:105], v[172:175], v[196:199], v[102:105]
	v_mfma_f32_16x16x32_bf16 v[98:101], v[180:183], v[196:199], v[98:101]
	v_mfma_f32_16x16x32_bf16 v[86:89], v[172:175], v[204:207], v[86:89]
	v_mfma_f32_16x16x32_bf16 v[82:85], v[180:183], v[204:207], v[82:85]
	v_mfma_f32_16x16x32_bf16 v[70:73], v[172:175], v[212:215], v[70:73]
	v_mfma_f32_16x16x32_bf16 v[66:69], v[180:183], v[212:215], v[66:69]
	s_barrier
	s_setprio 0
	s_add_i32 s55, s42, s13
	v_lshl_add_u64 v[216:217], s[44:45], 0, v[134:135]
	s_mov_b32 m0, s55
	ds_read_b128 v[184:187], v150 offset:16384
	ds_read_b128 v[188:191], v150 offset:17408
	ds_read_b128 v[192:195], v150 offset:18432
	ds_read_b128 v[196:199], v150 offset:19456
	ds_read_b128 v[200:203], v150 offset:20480
	ds_read_b128 v[204:207], v150 offset:21504
	ds_read_b128 v[208:211], v150 offset:22528
	ds_read_b128 v[212:215], v150 offset:23552
	global_load_lds_dwordx4 v[216:217], off
	s_add_i32 m0, s55, 0x2000
	s_add_u32 s68, s44, 0x80000
	v_lshl_add_u64 v[218:219], s[44:45], 0, v[130:131]
	s_addc_u32 s69, s45, 0
	s_add_i32 s55, s43, s13
	global_load_lds_dwordx4 v[218:219], off
	v_lshl_add_u64 v[220:221], s[68:69], 0, v[134:135]
	s_mov_b32 m0, s55
	v_lshl_add_u64 v[222:223], s[52:53], 0, v[132:133]
	global_load_lds_dwordx4 v[220:221], off
	v_lshl_add_u64 v[220:221], s[68:69], 0, v[130:131]
	s_add_i32 m0, s55, 0x2000
	s_nop 0
	global_load_lds_dwordx4 v[220:221], off
	v_lshl_add_u64 v[220:221], s[52:53], 0, v[136:137]
	s_mov_b32 m0, s18
	s_nop 0
	global_load_lds_dwordx4 v[220:221], off
	s_mov_b32 m0, s19
	s_nop 0
	global_load_lds_dwordx4 v[222:223], off
	s_waitcnt vmcnt(8)
	s_waitcnt lgkmcnt(0)
	s_setprio 1
	s_barrier
	v_mfma_f32_16x16x32_bf16 v[62:65], v[152:155], v[184:187], v[62:65]
	v_mfma_f32_16x16x32_bf16 v[58:61], v[160:163], v[184:187], v[58:61]
	v_mfma_f32_16x16x32_bf16 v[46:49], v[152:155], v[192:195], v[46:49]
	v_mfma_f32_16x16x32_bf16 v[42:45], v[160:163], v[192:195], v[42:45]
	v_mfma_f32_16x16x32_bf16 v[30:33], v[152:155], v[200:203], v[30:33]
	v_mfma_f32_16x16x32_bf16 v[26:29], v[160:163], v[200:203], v[26:29]
	v_mfma_f32_16x16x32_bf16 v[14:17], v[152:155], v[208:211], v[14:17]
	v_mfma_f32_16x16x32_bf16 v[10:13], v[160:163], v[208:211], v[10:13]
	s_setprio 0
	s_setprio 1
	v_mfma_f32_16x16x32_bf16 v[62:65], v[156:159], v[188:191], v[62:65]
	v_mfma_f32_16x16x32_bf16 v[58:61], v[164:167], v[188:191], v[58:61]
	v_mfma_f32_16x16x32_bf16 v[46:49], v[156:159], v[196:199], v[46:49]
	v_mfma_f32_16x16x32_bf16 v[42:45], v[164:167], v[196:199], v[42:45]
	v_mfma_f32_16x16x32_bf16 v[30:33], v[156:159], v[204:207], v[30:33]
	v_mfma_f32_16x16x32_bf16 v[26:29], v[164:167], v[204:207], v[26:29]
	v_mfma_f32_16x16x32_bf16 v[14:17], v[156:159], v[212:215], v[14:17]
	v_mfma_f32_16x16x32_bf16 v[10:13], v[164:167], v[212:215], v[10:13]
	s_setprio 0
	s_setprio 1
	v_mfma_f32_16x16x32_bf16 v[54:57], v[168:171], v[184:187], v[54:57]
	v_mfma_f32_16x16x32_bf16 v[50:53], v[176:179], v[184:187], v[50:53]
	v_mfma_f32_16x16x32_bf16 v[38:41], v[168:171], v[192:195], v[38:41]
	v_mfma_f32_16x16x32_bf16 v[34:37], v[176:179], v[192:195], v[34:37]
	v_mfma_f32_16x16x32_bf16 v[22:25], v[168:171], v[200:203], v[22:25]
	v_mfma_f32_16x16x32_bf16 v[18:21], v[176:179], v[200:203], v[18:21]
	v_mfma_f32_16x16x32_bf16 v[6:9], v[168:171], v[208:211], v[6:9]
	v_mfma_f32_16x16x32_bf16 v[2:5], v[176:179], v[208:211], v[2:5]
	s_setprio 0
	s_setprio 1
	v_mfma_f32_16x16x32_bf16 v[54:57], v[172:175], v[188:191], v[54:57]
	v_mfma_f32_16x16x32_bf16 v[50:53], v[180:183], v[188:191], v[50:53]
	v_mfma_f32_16x16x32_bf16 v[38:41], v[172:175], v[196:199], v[38:41]
	v_mfma_f32_16x16x32_bf16 v[34:37], v[180:183], v[196:199], v[34:37]
	v_mfma_f32_16x16x32_bf16 v[22:25], v[172:175], v[204:207], v[22:25]
	v_mfma_f32_16x16x32_bf16 v[18:21], v[180:183], v[204:207], v[18:21]
	v_mfma_f32_16x16x32_bf16 v[6:9], v[172:175], v[212:215], v[6:9]
	v_mfma_f32_16x16x32_bf16 v[2:5], v[180:183], v[212:215], v[2:5]
	s_barrier
	s_setprio 0
	s_add_i32 s55, 0, 0x18000
	v_add_u32_e32 v151, s55, v147
	s_add_i32 s68, 0, 0x1c000
	ds_read_b128 v[152:155], v151
	ds_read_b128 v[156:159], v151 offset:1024
	ds_read_b128 v[160:163], v151 offset:2048
	ds_read_b128 v[164:167], v151 offset:3072
	v_add_u32_e32 v151, s68, v147
	ds_read_b128 v[168:171], v151
	ds_read_b128 v[172:175], v151 offset:1024
	ds_read_b128 v[176:179], v151 offset:2048
	ds_read_b128 v[180:183], v151 offset:3072
	s_add_u32 s52, s52, 0x80000
	s_addc_u32 s53, s53, 0
	s_mov_b32 m0, s31
	v_lshl_add_u64 v[224:225], s[52:53], 0, v[136:137]
	ds_read_b128 v[184:187], v150 offset:32768
	ds_read_b128 v[188:191], v150 offset:33792
	ds_read_b128 v[192:195], v150 offset:34816
	ds_read_b128 v[196:199], v150 offset:35840
	ds_read_b128 v[200:203], v150 offset:36864
	ds_read_b128 v[204:207], v150 offset:37888
	ds_read_b128 v[208:211], v150 offset:38912
	ds_read_b128 v[212:215], v150 offset:39936
	global_load_lds_dwordx4 v[224:225], off
	v_lshl_add_u64 v[224:225], s[52:53], 0, v[132:133]
	s_mov_b32 m0, s33
	s_nop 0
	global_load_lds_dwordx4 v[224:225], off
	s_waitcnt vmcnt(8)
	s_waitcnt lgkmcnt(0)
	s_setprio 1
	s_barrier
	v_mfma_f32_16x16x32_bf16 v[126:129], v[152:155], v[184:187], v[126:129]
	v_mfma_f32_16x16x32_bf16 v[122:125], v[160:163], v[184:187], v[122:125]
	v_mfma_f32_16x16x32_bf16 v[110:113], v[152:155], v[192:195], v[110:113]
	v_mfma_f32_16x16x32_bf16 v[106:109], v[160:163], v[192:195], v[106:109]
	v_mfma_f32_16x16x32_bf16 v[94:97], v[152:155], v[200:203], v[94:97]
	v_mfma_f32_16x16x32_bf16 v[90:93], v[160:163], v[200:203], v[90:93]
	v_mfma_f32_16x16x32_bf16 v[78:81], v[152:155], v[208:211], v[78:81]
	v_mfma_f32_16x16x32_bf16 v[74:77], v[160:163], v[208:211], v[74:77]
	s_setprio 0
	s_setprio 1
	v_mfma_f32_16x16x32_bf16 v[126:129], v[156:159], v[188:191], v[126:129]
	v_mfma_f32_16x16x32_bf16 v[122:125], v[164:167], v[188:191], v[122:125]
	v_mfma_f32_16x16x32_bf16 v[110:113], v[156:159], v[196:199], v[110:113]
	v_mfma_f32_16x16x32_bf16 v[106:109], v[164:167], v[196:199], v[106:109]
	v_mfma_f32_16x16x32_bf16 v[94:97], v[156:159], v[204:207], v[94:97]
	v_mfma_f32_16x16x32_bf16 v[90:93], v[164:167], v[204:207], v[90:93]
	v_mfma_f32_16x16x32_bf16 v[78:81], v[156:159], v[212:215], v[78:81]
	v_mfma_f32_16x16x32_bf16 v[74:77], v[164:167], v[212:215], v[74:77]
	s_setprio 0
	s_setprio 1
	v_mfma_f32_16x16x32_bf16 v[118:121], v[168:171], v[184:187], v[118:121]
	v_mfma_f32_16x16x32_bf16 v[114:117], v[176:179], v[184:187], v[114:117]
	v_mfma_f32_16x16x32_bf16 v[102:105], v[168:171], v[192:195], v[102:105]
	v_mfma_f32_16x16x32_bf16 v[98:101], v[176:179], v[192:195], v[98:101]
	v_mfma_f32_16x16x32_bf16 v[86:89], v[168:171], v[200:203], v[86:89]
	v_mfma_f32_16x16x32_bf16 v[82:85], v[176:179], v[200:203], v[82:85]
	v_mfma_f32_16x16x32_bf16 v[70:73], v[168:171], v[208:211], v[70:73]
	v_mfma_f32_16x16x32_bf16 v[66:69], v[176:179], v[208:211], v[66:69]
	s_setprio 0
	s_setprio 1
	v_mfma_f32_16x16x32_bf16 v[118:121], v[172:175], v[188:191], v[118:121]
	v_mfma_f32_16x16x32_bf16 v[114:117], v[180:183], v[188:191], v[114:117]
	v_mfma_f32_16x16x32_bf16 v[102:105], v[172:175], v[196:199], v[102:105]
	v_mfma_f32_16x16x32_bf16 v[98:101], v[180:183], v[196:199], v[98:101]
	v_mfma_f32_16x16x32_bf16 v[86:89], v[172:175], v[204:207], v[86:89]
	v_mfma_f32_16x16x32_bf16 v[82:85], v[180:183], v[204:207], v[82:85]
	v_mfma_f32_16x16x32_bf16 v[70:73], v[172:175], v[212:215], v[70:73]
	v_mfma_f32_16x16x32_bf16 v[66:69], v[180:183], v[212:215], v[66:69]
	s_barrier
	s_setprio 0
	s_add_i32 s52, s55, s13
	v_lshl_add_u64 v[216:217], v[216:217], 0, s[16:17]
	s_mov_b32 m0, s52
	ds_read_b128 v[184:187], v150 offset:49152
	ds_read_b128 v[188:191], v150 offset:50176
	ds_read_b128 v[192:195], v150 offset:51200
	ds_read_b128 v[196:199], v150 offset:52224
	ds_read_b128 v[200:203], v150 offset:53248
	ds_read_b128 v[204:207], v150 offset:54272
	ds_read_b128 v[208:211], v150 offset:55296
	ds_read_b128 v[212:215], v150 offset:56320
	global_load_lds_dwordx4 v[216:217], off
	s_add_i32 m0, s52, 0x2000
	s_add_u32 s44, s44, 0x80080
	v_lshl_add_u64 v[216:217], v[218:219], 0, s[16:17]
	s_addc_u32 s45, s45, 0
	s_add_i32 s52, s68, s13
	global_load_lds_dwordx4 v[216:217], off
	v_lshl_add_u64 v[216:217], s[44:45], 0, v[134:135]
	s_mov_b32 m0, s52
	s_nop 0
	global_load_lds_dwordx4 v[216:217], off
	v_lshl_add_u64 v[216:217], s[44:45], 0, v[130:131]
	s_add_i32 m0, s52, 0x2000
	s_nop 0
	global_load_lds_dwordx4 v[216:217], off
	v_lshl_add_u64 v[216:217], v[220:221], 0, s[16:17]
	s_mov_b32 m0, s38
	s_nop 0
	global_load_lds_dwordx4 v[216:217], off
	v_lshl_add_u64 v[216:217], v[222:223], 0, s[16:17]
	s_mov_b32 m0, s39
	s_nop 0
	global_load_lds_dwordx4 v[216:217], off
	s_waitcnt vmcnt(8)
	s_waitcnt lgkmcnt(0)
	s_setprio 1
	s_barrier
	v_mfma_f32_16x16x32_bf16 v[62:65], v[152:155], v[184:187], v[62:65]
	v_mfma_f32_16x16x32_bf16 v[58:61], v[160:163], v[184:187], v[58:61]
	v_mfma_f32_16x16x32_bf16 v[46:49], v[152:155], v[192:195], v[46:49]
	v_mfma_f32_16x16x32_bf16 v[42:45], v[160:163], v[192:195], v[42:45]
	v_mfma_f32_16x16x32_bf16 v[30:33], v[152:155], v[200:203], v[30:33]
	v_mfma_f32_16x16x32_bf16 v[26:29], v[160:163], v[200:203], v[26:29]
	v_mfma_f32_16x16x32_bf16 v[14:17], v[152:155], v[208:211], v[14:17]
	v_mfma_f32_16x16x32_bf16 v[10:13], v[160:163], v[208:211], v[10:13]
	s_setprio 0
	s_setprio 1
	v_mfma_f32_16x16x32_bf16 v[62:65], v[156:159], v[188:191], v[62:65]
	v_mfma_f32_16x16x32_bf16 v[58:61], v[164:167], v[188:191], v[58:61]
	v_mfma_f32_16x16x32_bf16 v[46:49], v[156:159], v[196:199], v[46:49]
	v_mfma_f32_16x16x32_bf16 v[42:45], v[164:167], v[196:199], v[42:45]
	v_mfma_f32_16x16x32_bf16 v[30:33], v[156:159], v[204:207], v[30:33]
	v_mfma_f32_16x16x32_bf16 v[26:29], v[164:167], v[204:207], v[26:29]
	v_mfma_f32_16x16x32_bf16 v[14:17], v[156:159], v[212:215], v[14:17]
	v_mfma_f32_16x16x32_bf16 v[10:13], v[164:167], v[212:215], v[10:13]
	s_setprio 0
	s_setprio 1
	v_mfma_f32_16x16x32_bf16 v[54:57], v[168:171], v[184:187], v[54:57]
	v_mfma_f32_16x16x32_bf16 v[50:53], v[176:179], v[184:187], v[50:53]
	v_mfma_f32_16x16x32_bf16 v[38:41], v[168:171], v[192:195], v[38:41]
	v_mfma_f32_16x16x32_bf16 v[34:37], v[176:179], v[192:195], v[34:37]
	v_mfma_f32_16x16x32_bf16 v[22:25], v[168:171], v[200:203], v[22:25]
	v_mfma_f32_16x16x32_bf16 v[18:21], v[176:179], v[200:203], v[18:21]
	v_mfma_f32_16x16x32_bf16 v[6:9], v[168:171], v[208:211], v[6:9]
	v_mfma_f32_16x16x32_bf16 v[2:5], v[176:179], v[208:211], v[2:5]
	s_setprio 0
	s_setprio 1
	v_mfma_f32_16x16x32_bf16 v[54:57], v[172:175], v[188:191], v[54:57]
	v_mfma_f32_16x16x32_bf16 v[50:53], v[180:183], v[188:191], v[50:53]
	v_mfma_f32_16x16x32_bf16 v[38:41], v[172:175], v[196:199], v[38:41]
	v_mfma_f32_16x16x32_bf16 v[34:37], v[180:183], v[196:199], v[34:37]
	v_mfma_f32_16x16x32_bf16 v[22:25], v[172:175], v[204:207], v[22:25]
	v_mfma_f32_16x16x32_bf16 v[18:21], v[180:183], v[204:207], v[18:21]
	v_mfma_f32_16x16x32_bf16 v[6:9], v[172:175], v[212:215], v[6:9]
	v_mfma_f32_16x16x32_bf16 v[2:5], v[180:183], v[212:215], v[2:5]
	s_barrier
	s_setprio 0
	s_add_i32 s54, s54, 2
	s_add_u32 s50, s50, 0x100
	s_addc_u32 s51, s51, 0
	s_add_u32 s36, s36, 0x100
	s_addc_u32 s37, s37, 0
	s_cmp_gt_u32 s54, 29
	s_cbranch_scc0 .LBB0_122
	s_and_b64 vcc, exec, s[20:21]
	s_cbranch_vccz .LBB0_125
	s_barrier

.LBB0_139:
	ds_read_b128 v[150:153], v146
	ds_read_b128 v[154:157], v146 offset:1024
	ds_read_b128 v[158:161], v146 offset:2048
	ds_read_b128 v[162:165], v146 offset:3072
	ds_read_b128 v[166:169], v147
	ds_read_b128 v[170:173], v147 offset:1024
	ds_read_b128 v[174:177], v147 offset:2048
	ds_read_b128 v[178:181], v147 offset:3072
	s_add_u32 s44, s36, 0xfff80080
	s_addc_u32 s45, s37, -1
	s_cmp_eq_u32 s68, 28
	s_cselect_b32 s53, s23, s45
	s_cselect_b32 s52, s50, s44
	s_cselect_b32 s45, s21, s55
	s_cselect_b32 s44, s51, s54
	v_lshl_add_u64 v[142:143], s[36:37], 0, v[140:141]
	s_add_i32 m0, s34, 0xc000
	ds_read_b128 v[182:185], v148
	ds_read_b128 v[186:189], v148 offset:1024
	ds_read_b128 v[190:193], v148 offset:2048
	ds_read_b128 v[194:197], v148 offset:3072
	ds_read_b128 v[198:201], v148 offset:4096
	ds_read_b128 v[202:205], v148 offset:5120
	ds_read_b128 v[206:209], v148 offset:6144
	ds_read_b128 v[210:213], v148 offset:7168
	global_load_lds_dwordx4 v[142:143], off
	v_lshl_add_u64 v[142:143], s[36:37], 0, v[138:139]
	s_add_i32 m0, s34, 0xe000
	s_nop 0
	global_load_lds_dwordx4 v[142:143], off
	s_waitcnt vmcnt(8)
	s_waitcnt lgkmcnt(0)
	s_setprio 1
	s_barrier
	v_mfma_f32_16x16x32_bf16 v[126:129], v[150:153], v[182:185], v[126:129]
	v_mfma_f32_16x16x32_bf16 v[122:125], v[158:161], v[182:185], v[122:125]
	v_mfma_f32_16x16x32_bf16 v[118:121], v[150:153], v[190:193], v[118:121]
	v_mfma_f32_16x16x32_bf16 v[110:113], v[158:161], v[190:193], v[110:113]
	v_mfma_f32_16x16x32_bf16 v[102:105], v[150:153], v[198:201], v[102:105]
	v_mfma_f32_16x16x32_bf16 v[94:97], v[158:161], v[198:201], v[94:97]
	v_mfma_f32_16x16x32_bf16 v[86:89], v[150:153], v[206:209], v[86:89]
	v_mfma_f32_16x16x32_bf16 v[78:81], v[158:161], v[206:209], v[78:81]
	s_setprio 0
	s_setprio 1
	v_mfma_f32_16x16x32_bf16 v[126:129], v[154:157], v[186:189], v[126:129]
	v_mfma_f32_16x16x32_bf16 v[122:125], v[162:165], v[186:189], v[122:125]
	v_mfma_f32_16x16x32_bf16 v[118:121], v[154:157], v[194:197], v[118:121]
	v_mfma_f32_16x16x32_bf16 v[110:113], v[162:165], v[194:197], v[110:113]
	v_mfma_f32_16x16x32_bf16 v[102:105], v[154:157], v[202:205], v[102:105]
	v_mfma_f32_16x16x32_bf16 v[94:97], v[162:165], v[202:205], v[94:97]
	v_mfma_f32_16x16x32_bf16 v[86:89], v[154:157], v[210:213], v[86:89]
	v_mfma_f32_16x16x32_bf16 v[78:81], v[162:165], v[210:213], v[78:81]
	s_setprio 0
	s_setprio 1
	v_mfma_f32_16x16x32_bf16 v[114:117], v[166:169], v[182:185], v[114:117]
	v_mfma_f32_16x16x32_bf16 v[106:109], v[174:177], v[182:185], v[106:109]
	v_mfma_f32_16x16x32_bf16 v[98:101], v[166:169], v[190:193], v[98:101]
	v_mfma_f32_16x16x32_bf16 v[90:93], v[174:177], v[190:193], v[90:93]
	v_mfma_f32_16x16x32_bf16 v[82:85], v[166:169], v[198:201], v[82:85]
	v_mfma_f32_16x16x32_bf16 v[74:77], v[174:177], v[198:201], v[74:77]
	v_mfma_f32_16x16x32_bf16 v[70:73], v[166:169], v[206:209], v[70:73]
	v_mfma_f32_16x16x32_bf16 v[66:69], v[174:177], v[206:209], v[66:69]
	s_setprio 0
	s_setprio 1
	v_mfma_f32_16x16x32_bf16 v[114:117], v[170:173], v[186:189], v[114:117]
	v_mfma_f32_16x16x32_bf16 v[106:109], v[178:181], v[186:189], v[106:109]
	v_mfma_f32_16x16x32_bf16 v[98:101], v[170:173], v[194:197], v[98:101]
	v_mfma_f32_16x16x32_bf16 v[90:93], v[178:181], v[194:197], v[90:93]
	v_mfma_f32_16x16x32_bf16 v[82:85], v[170:173], v[202:205], v[82:85]
	v_mfma_f32_16x16x32_bf16 v[74:77], v[178:181], v[202:205], v[74:77]
	v_mfma_f32_16x16x32_bf16 v[70:73], v[170:173], v[210:213], v[70:73]
	v_mfma_f32_16x16x32_bf16 v[66:69], v[178:181], v[210:213], v[66:69]
	s_barrier
	s_setprio 0
	s_add_i32 s69, s48, s19
	v_lshl_add_u64 v[142:143], s[44:45], 0, v[134:135]
	s_mov_b32 m0, s69
	ds_read_b128 v[182:185], v148 offset:16384
	ds_read_b128 v[186:189], v148 offset:17408
	ds_read_b128 v[190:193], v148 offset:18432
	ds_read_b128 v[194:197], v148 offset:19456
	ds_read_b128 v[198:201], v148 offset:20480
	ds_read_b128 v[202:205], v148 offset:21504
	ds_read_b128 v[206:209], v148 offset:22528
	ds_read_b128 v[210:213], v148 offset:23552
	global_load_lds_dwordx4 v[142:143], off
	s_add_i32 m0, s69, 0x2000
	s_add_u32 s70, s44, 0x80000
	v_lshl_add_u64 v[214:215], s[44:45], 0, v[130:131]
	s_addc_u32 s71, s45, 0
	s_add_i32 s69, s49, s19
	global_load_lds_dwordx4 v[214:215], off
	v_lshl_add_u64 v[216:217], s[70:71], 0, v[134:135]
	s_mov_b32 m0, s69
	v_lshl_add_u64 v[218:219], s[52:53], 0, v[132:133]
	global_load_lds_dwordx4 v[216:217], off
	v_lshl_add_u64 v[216:217], s[70:71], 0, v[130:131]
	s_add_i32 m0, s69, 0x2000
	s_nop 0
	global_load_lds_dwordx4 v[216:217], off
	v_lshl_add_u64 v[216:217], s[52:53], 0, v[136:137]
	s_mov_b32 m0, s34
	s_nop 0
	global_load_lds_dwordx4 v[216:217], off
	s_mov_b32 m0, s35
	s_nop 0
	global_load_lds_dwordx4 v[218:219], off
	s_waitcnt vmcnt(8)
	s_waitcnt lgkmcnt(0)
	s_setprio 1
	s_barrier
	v_mfma_f32_16x16x32_bf16 v[62:65], v[150:153], v[182:185], v[62:65]
	v_mfma_f32_16x16x32_bf16 v[58:61], v[158:161], v[182:185], v[58:61]
	v_mfma_f32_16x16x32_bf16 v[54:57], v[150:153], v[190:193], v[54:57]
	v_mfma_f32_16x16x32_bf16 v[46:49], v[158:161], v[190:193], v[46:49]
	v_mfma_f32_16x16x32_bf16 v[38:41], v[150:153], v[198:201], v[38:41]
	v_mfma_f32_16x16x32_bf16 v[30:33], v[158:161], v[198:201], v[30:33]
	v_mfma_f32_16x16x32_bf16 v[22:25], v[150:153], v[206:209], v[22:25]
	v_mfma_f32_16x16x32_bf16 v[14:17], v[158:161], v[206:209], v[14:17]
	s_setprio 0
	s_setprio 1
	v_mfma_f32_16x16x32_bf16 v[62:65], v[154:157], v[186:189], v[62:65]
	v_mfma_f32_16x16x32_bf16 v[58:61], v[162:165], v[186:189], v[58:61]
	v_mfma_f32_16x16x32_bf16 v[54:57], v[154:157], v[194:197], v[54:57]
	v_mfma_f32_16x16x32_bf16 v[46:49], v[162:165], v[194:197], v[46:49]
	v_mfma_f32_16x16x32_bf16 v[38:41], v[154:157], v[202:205], v[38:41]
	v_mfma_f32_16x16x32_bf16 v[30:33], v[162:165], v[202:205], v[30:33]
	v_mfma_f32_16x16x32_bf16 v[22:25], v[154:157], v[210:213], v[22:25]
	v_mfma_f32_16x16x32_bf16 v[14:17], v[162:165], v[210:213], v[14:17]
	s_setprio 0
	s_setprio 1
	v_mfma_f32_16x16x32_bf16 v[50:53], v[166:169], v[182:185], v[50:53]
	v_mfma_f32_16x16x32_bf16 v[42:45], v[174:177], v[182:185], v[42:45]
	v_mfma_f32_16x16x32_bf16 v[34:37], v[166:169], v[190:193], v[34:37]
	v_mfma_f32_16x16x32_bf16 v[26:29], v[174:177], v[190:193], v[26:29]
	v_mfma_f32_16x16x32_bf16 v[18:21], v[166:169], v[198:201], v[18:21]
	v_mfma_f32_16x16x32_bf16 v[10:13], v[174:177], v[198:201], v[10:13]
	v_mfma_f32_16x16x32_bf16 v[6:9], v[166:169], v[206:209], v[6:9]
	v_mfma_f32_16x16x32_bf16 v[2:5], v[174:177], v[206:209], v[2:5]
	s_setprio 0
	s_setprio 1
	v_mfma_f32_16x16x32_bf16 v[50:53], v[170:173], v[186:189], v[50:53]
	v_mfma_f32_16x16x32_bf16 v[42:45], v[178:181], v[186:189], v[42:45]
	v_mfma_f32_16x16x32_bf16 v[34:37], v[170:173], v[194:197], v[34:37]
	v_mfma_f32_16x16x32_bf16 v[26:29], v[178:181], v[194:197], v[26:29]
	v_mfma_f32_16x16x32_bf16 v[18:21], v[170:173], v[202:205], v[18:21]
	v_mfma_f32_16x16x32_bf16 v[10:13], v[178:181], v[202:205], v[10:13]
	v_mfma_f32_16x16x32_bf16 v[6:9], v[170:173], v[210:213], v[6:9]
	v_mfma_f32_16x16x32_bf16 v[2:5], v[178:181], v[210:213], v[2:5]
	s_barrier
	s_setprio 0
	s_add_i32 s69, 0, 0x18000
	v_add_u32_e32 v149, s69, v145
	s_add_i32 s70, 0, 0x1c000
	ds_read_b128 v[150:153], v149
	ds_read_b128 v[154:157], v149 offset:1024
	ds_read_b128 v[158:161], v149 offset:2048
	ds_read_b128 v[162:165], v149 offset:3072
	v_add_u32_e32 v149, s70, v145
	ds_read_b128 v[166:169], v149
	ds_read_b128 v[170:173], v149 offset:1024
	ds_read_b128 v[174:177], v149 offset:2048
	ds_read_b128 v[178:181], v149 offset:3072
	s_add_u32 s52, s52, 0x80000
	s_addc_u32 s53, s53, 0
	s_mov_b32 m0, s38
	v_lshl_add_u64 v[220:221], s[52:53], 0, v[136:137]
	ds_read_b128 v[182:185], v148 offset:32768
	ds_read_b128 v[186:189], v148 offset:33792
	ds_read_b128 v[190:193], v148 offset:34816
	ds_read_b128 v[194:197], v148 offset:35840
	ds_read_b128 v[198:201], v148 offset:36864
	ds_read_b128 v[202:205], v148 offset:37888
	ds_read_b128 v[206:209], v148 offset:38912
	ds_read_b128 v[210:213], v148 offset:39936
	global_load_lds_dwordx4 v[220:221], off
	v_lshl_add_u64 v[220:221], s[52:53], 0, v[132:133]
	s_mov_b32 m0, s39
	s_nop 0
	global_load_lds_dwordx4 v[220:221], off
	s_waitcnt vmcnt(8)
	s_waitcnt lgkmcnt(0)
	s_setprio 1
	s_barrier
	v_mfma_f32_16x16x32_bf16 v[126:129], v[150:153], v[182:185], v[126:129]
	v_mfma_f32_16x16x32_bf16 v[122:125], v[158:161], v[182:185], v[122:125]
	v_mfma_f32_16x16x32_bf16 v[118:121], v[150:153], v[190:193], v[118:121]
	v_mfma_f32_16x16x32_bf16 v[110:113], v[158:161], v[190:193], v[110:113]
	v_mfma_f32_16x16x32_bf16 v[102:105], v[150:153], v[198:201], v[102:105]
	v_mfma_f32_16x16x32_bf16 v[94:97], v[158:161], v[198:201], v[94:97]
	v_mfma_f32_16x16x32_bf16 v[86:89], v[150:153], v[206:209], v[86:89]
	v_mfma_f32_16x16x32_bf16 v[78:81], v[158:161], v[206:209], v[78:81]
	s_setprio 0
	s_setprio 1
	v_mfma_f32_16x16x32_bf16 v[126:129], v[154:157], v[186:189], v[126:129]
	v_mfma_f32_16x16x32_bf16 v[122:125], v[162:165], v[186:189], v[122:125]
	v_mfma_f32_16x16x32_bf16 v[118:121], v[154:157], v[194:197], v[118:121]
	v_mfma_f32_16x16x32_bf16 v[110:113], v[162:165], v[194:197], v[110:113]
	v_mfma_f32_16x16x32_bf16 v[102:105], v[154:157], v[202:205], v[102:105]
	v_mfma_f32_16x16x32_bf16 v[94:97], v[162:165], v[202:205], v[94:97]
	v_mfma_f32_16x16x32_bf16 v[86:89], v[154:157], v[210:213], v[86:89]
	v_mfma_f32_16x16x32_bf16 v[78:81], v[162:165], v[210:213], v[78:81]
	s_setprio 0
	s_setprio 1
	v_mfma_f32_16x16x32_bf16 v[114:117], v[166:169], v[182:185], v[114:117]
	v_mfma_f32_16x16x32_bf16 v[106:109], v[174:177], v[182:185], v[106:109]
	v_mfma_f32_16x16x32_bf16 v[98:101], v[166:169], v[190:193], v[98:101]
	v_mfma_f32_16x16x32_bf16 v[90:93], v[174:177], v[190:193], v[90:93]
	v_mfma_f32_16x16x32_bf16 v[82:85], v[166:169], v[198:201], v[82:85]
	v_mfma_f32_16x16x32_bf16 v[74:77], v[174:177], v[198:201], v[74:77]
	v_mfma_f32_16x16x32_bf16 v[70:73], v[166:169], v[206:209], v[70:73]
	v_mfma_f32_16x16x32_bf16 v[66:69], v[174:177], v[206:209], v[66:69]
	s_setprio 0
	s_setprio 1
	v_mfma_f32_16x16x32_bf16 v[114:117], v[170:173], v[186:189], v[114:117]
	v_mfma_f32_16x16x32_bf16 v[106:109], v[178:181], v[186:189], v[106:109]
	v_mfma_f32_16x16x32_bf16 v[98:101], v[170:173], v[194:197], v[98:101]
	v_mfma_f32_16x16x32_bf16 v[90:93], v[178:181], v[194:197], v[90:93]
	v_mfma_f32_16x16x32_bf16 v[82:85], v[170:173], v[202:205], v[82:85]
	v_mfma_f32_16x16x32_bf16 v[74:77], v[178:181], v[202:205], v[74:77]
	v_mfma_f32_16x16x32_bf16 v[70:73], v[170:173], v[210:213], v[70:73]
	v_mfma_f32_16x16x32_bf16 v[66:69], v[178:181], v[210:213], v[66:69]
	s_barrier
	s_setprio 0
	s_add_i32 s52, s69, s19
	v_lshl_add_u64 v[142:143], v[142:143], 0, s[8:9]
	s_mov_b32 m0, s52
	ds_read_b128 v[182:185], v148 offset:49152
	ds_read_b128 v[186:189], v148 offset:50176
	ds_read_b128 v[190:193], v148 offset:51200
	ds_read_b128 v[194:197], v148 offset:52224
	ds_read_b128 v[198:201], v148 offset:53248
	ds_read_b128 v[202:205], v148 offset:54272
	ds_read_b128 v[206:209], v148 offset:55296
	ds_read_b128 v[210:213], v148 offset:56320
	global_load_lds_dwordx4 v[142:143], off
	s_add_i32 m0, s52, 0x2000
	s_add_u32 s44, s44, 0x80080
	v_lshl_add_u64 v[142:143], v[214:215], 0, s[8:9]
	s_addc_u32 s45, s45, 0
	s_add_i32 s52, s70, s19
	global_load_lds_dwordx4 v[142:143], off
	v_lshl_add_u64 v[142:143], s[44:45], 0, v[134:135]
	s_mov_b32 m0, s52
	s_nop 0
	global_load_lds_dwordx4 v[142:143], off
	v_lshl_add_u64 v[142:143], s[44:45], 0, v[130:131]
	s_add_i32 m0, s52, 0x2000
	s_nop 0
	global_load_lds_dwordx4 v[142:143], off
	v_lshl_add_u64 v[142:143], v[216:217], 0, s[8:9]
	s_mov_b32 m0, s42
	s_nop 0
	global_load_lds_dwordx4 v[142:143], off
	v_lshl_add_u64 v[142:143], v[218:219], 0, s[8:9]
	s_mov_b32 m0, s43
	s_nop 0
	global_load_lds_dwordx4 v[142:143], off
	s_waitcnt vmcnt(8)
	s_waitcnt lgkmcnt(0)
	s_setprio 1
	s_barrier
	v_mfma_f32_16x16x32_bf16 v[62:65], v[150:153], v[182:185], v[62:65]
	v_mfma_f32_16x16x32_bf16 v[58:61], v[158:161], v[182:185], v[58:61]
	v_mfma_f32_16x16x32_bf16 v[54:57], v[150:153], v[190:193], v[54:57]
	v_mfma_f32_16x16x32_bf16 v[46:49], v[158:161], v[190:193], v[46:49]
	v_mfma_f32_16x16x32_bf16 v[38:41], v[150:153], v[198:201], v[38:41]
	v_mfma_f32_16x16x32_bf16 v[30:33], v[158:161], v[198:201], v[30:33]
	v_mfma_f32_16x16x32_bf16 v[22:25], v[150:153], v[206:209], v[22:25]
	v_mfma_f32_16x16x32_bf16 v[14:17], v[158:161], v[206:209], v[14:17]
	s_setprio 0
	s_setprio 1
	v_mfma_f32_16x16x32_bf16 v[62:65], v[154:157], v[186:189], v[62:65]
	v_mfma_f32_16x16x32_bf16 v[58:61], v[162:165], v[186:189], v[58:61]
	v_mfma_f32_16x16x32_bf16 v[54:57], v[154:157], v[194:197], v[54:57]
	v_mfma_f32_16x16x32_bf16 v[46:49], v[162:165], v[194:197], v[46:49]
	v_mfma_f32_16x16x32_bf16 v[38:41], v[154:157], v[202:205], v[38:41]
	v_mfma_f32_16x16x32_bf16 v[30:33], v[162:165], v[202:205], v[30:33]
	v_mfma_f32_16x16x32_bf16 v[22:25], v[154:157], v[210:213], v[22:25]
	v_mfma_f32_16x16x32_bf16 v[14:17], v[162:165], v[210:213], v[14:17]
	s_setprio 0
	s_setprio 1
	v_mfma_f32_16x16x32_bf16 v[50:53], v[166:169], v[182:185], v[50:53]
	v_mfma_f32_16x16x32_bf16 v[42:45], v[174:177], v[182:185], v[42:45]
	v_mfma_f32_16x16x32_bf16 v[34:37], v[166:169], v[190:193], v[34:37]
	v_mfma_f32_16x16x32_bf16 v[26:29], v[174:177], v[190:193], v[26:29]
	v_mfma_f32_16x16x32_bf16 v[18:21], v[166:169], v[198:201], v[18:21]
	v_mfma_f32_16x16x32_bf16 v[10:13], v[174:177], v[198:201], v[10:13]
	v_mfma_f32_16x16x32_bf16 v[6:9], v[166:169], v[206:209], v[6:9]
	v_mfma_f32_16x16x32_bf16 v[2:5], v[174:177], v[206:209], v[2:5]
	s_setprio 0
	s_setprio 1
	v_mfma_f32_16x16x32_bf16 v[50:53], v[170:173], v[186:189], v[50:53]
	v_mfma_f32_16x16x32_bf16 v[42:45], v[178:181], v[186:189], v[42:45]
	v_mfma_f32_16x16x32_bf16 v[34:37], v[170:173], v[194:197], v[34:37]
	v_mfma_f32_16x16x32_bf16 v[26:29], v[178:181], v[194:197], v[26:29]
	v_mfma_f32_16x16x32_bf16 v[18:21], v[170:173], v[202:205], v[18:21]
	v_mfma_f32_16x16x32_bf16 v[10:13], v[178:181], v[202:205], v[10:13]
	v_mfma_f32_16x16x32_bf16 v[6:9], v[170:173], v[210:213], v[6:9]
	v_mfma_f32_16x16x32_bf16 v[2:5], v[178:181], v[210:213], v[2:5]
	s_barrier
	s_setprio 0
	s_add_i32 s68, s68, 2
	s_add_u32 s54, s54, 0x100
	s_addc_u32 s55, s55, 0
	s_add_u32 s36, s36, 0x100
	s_addc_u32 s37, s37, 0
	s_cmp_gt_u32 s68, 29
	s_cbranch_scc0 .LBB0_139
	s_and_b64 vcc, exec, s[16:17]
	s_cbranch_vccz .LBB0_142
	s_barrier

.LBB0_266:
	ds_read_b128 v[82:85], v188
	ds_read_b128 v[86:89], v188 offset:1024
	ds_read_b128 v[94:97], v188 offset:2048
	ds_read_b128 v[98:101], v188 offset:3072
	ds_read_b128 v[146:149], v189
	ds_read_b128 v[150:153], v189 offset:1024
	ds_read_b128 v[154:157], v189 offset:2048
	ds_read_b128 v[158:161], v189 offset:3072
	s_add_u32 s6, s44, 0x100
	s_addc_u32 s7, s45, 0
	s_cmpk_eq_i32 s70, 0x54
	s_cselect_b32 s55, s31, s7
	s_cselect_b32 s54, s30, s6
	s_cselect_b32 s53, s37, s69
	s_cselect_b32 s52, s36, s68
	v_lshl_add_u64 v[216:217], s[44:45], 0, v[172:173]
	s_add_i32 m0, s14, 0xc000
	ds_read_b128 v[178:181], v190
	ds_read_b128 v[182:185], v190 offset:1024
	ds_read_b128 v[192:195], v190 offset:2048
	ds_read_b128 v[196:199], v190 offset:3072
	ds_read_b128 v[200:203], v190 offset:4096
	ds_read_b128 v[204:207], v190 offset:5120
	ds_read_b128 v[208:211], v190 offset:6144
	ds_read_b128 v[212:215], v190 offset:7168
	global_load_lds_dwordx4 v[216:217], off
	v_lshl_add_u64 v[216:217], s[44:45], 0, v[170:171]
	s_add_i32 m0, s14, 0xe000
	s_nop 0
	global_load_lds_dwordx4 v[216:217], off
	s_waitcnt vmcnt(8)
	s_waitcnt lgkmcnt(0)
	s_setprio 1
	s_barrier
	v_mfma_f32_16x16x32_bf16 v[142:145], v[82:85], v[178:181], v[142:145]
	v_mfma_f32_16x16x32_bf16 v[138:141], v[94:97], v[178:181], v[138:141]
	v_mfma_f32_16x16x32_bf16 v[126:129], v[82:85], v[192:195], v[126:129]
	v_mfma_f32_16x16x32_bf16 v[122:125], v[94:97], v[192:195], v[122:125]
	v_mfma_f32_16x16x32_bf16 v[110:113], v[82:85], v[200:203], v[110:113]
	v_mfma_f32_16x16x32_bf16 v[106:109], v[94:97], v[200:203], v[106:109]
	v_mfma_f32_16x16x32_bf16 v[78:81], v[82:85], v[208:211], v[78:81]
	v_mfma_f32_16x16x32_bf16 v[74:77], v[94:97], v[208:211], v[74:77]
	s_setprio 0
	s_setprio 1
	v_mfma_f32_16x16x32_bf16 v[142:145], v[86:89], v[182:185], v[142:145]
	v_mfma_f32_16x16x32_bf16 v[138:141], v[98:101], v[182:185], v[138:141]
	v_mfma_f32_16x16x32_bf16 v[126:129], v[86:89], v[196:199], v[126:129]
	v_mfma_f32_16x16x32_bf16 v[122:125], v[98:101], v[196:199], v[122:125]
	v_mfma_f32_16x16x32_bf16 v[110:113], v[86:89], v[204:207], v[110:113]
	v_mfma_f32_16x16x32_bf16 v[106:109], v[98:101], v[204:207], v[106:109]
	v_mfma_f32_16x16x32_bf16 v[78:81], v[86:89], v[212:215], v[78:81]
	v_mfma_f32_16x16x32_bf16 v[74:77], v[98:101], v[212:215], v[74:77]
	s_setprio 0
	s_setprio 1
	v_mfma_f32_16x16x32_bf16 v[134:137], v[146:149], v[178:181], v[134:137]
	v_mfma_f32_16x16x32_bf16 v[130:133], v[154:157], v[178:181], v[130:133]
	v_mfma_f32_16x16x32_bf16 v[118:121], v[146:149], v[192:195], v[118:121]
	v_mfma_f32_16x16x32_bf16 v[114:117], v[154:157], v[192:195], v[114:117]
	v_mfma_f32_16x16x32_bf16 v[102:105], v[146:149], v[200:203], v[102:105]
	v_mfma_f32_16x16x32_bf16 v[90:93], v[154:157], v[200:203], v[90:93]
	v_mfma_f32_16x16x32_bf16 v[70:73], v[146:149], v[208:211], v[70:73]
	v_mfma_f32_16x16x32_bf16 v[66:69], v[154:157], v[208:211], v[66:69]
	s_setprio 0
	s_setprio 1
	v_mfma_f32_16x16x32_bf16 v[134:137], v[150:153], v[182:185], v[134:137]
	v_mfma_f32_16x16x32_bf16 v[130:133], v[158:161], v[182:185], v[130:133]
	v_mfma_f32_16x16x32_bf16 v[118:121], v[150:153], v[196:199], v[118:121]
	v_mfma_f32_16x16x32_bf16 v[114:117], v[158:161], v[196:199], v[114:117]
	v_mfma_f32_16x16x32_bf16 v[102:105], v[150:153], v[204:207], v[102:105]
	v_mfma_f32_16x16x32_bf16 v[90:93], v[158:161], v[204:207], v[90:93]
	v_mfma_f32_16x16x32_bf16 v[70:73], v[150:153], v[212:215], v[70:73]
	v_mfma_f32_16x16x32_bf16 v[66:69], v[158:161], v[212:215], v[66:69]
	s_barrier
	s_setprio 0
	s_add_i32 s44, s46, s13
	v_lshl_add_u64 v[216:217], s[52:53], 0, v[164:165]
	s_mov_b32 m0, s44
	ds_read_b128 v[178:181], v190 offset:16384
	ds_read_b128 v[182:185], v190 offset:17408
	ds_read_b128 v[192:195], v190 offset:18432
	ds_read_b128 v[196:199], v190 offset:19456
	ds_read_b128 v[200:203], v190 offset:20480
	ds_read_b128 v[204:207], v190 offset:21504
	ds_read_b128 v[208:211], v190 offset:22528
	ds_read_b128 v[212:215], v190 offset:23552
	global_load_lds_dwordx4 v[216:217], off
	s_add_i32 m0, s44, 0x2000
	s_add_u32 s44, s52, 0x160000
	v_lshl_add_u64 v[218:219], s[52:53], 0, v[168:169]
	s_addc_u32 s45, s53, 0
	s_add_i32 s71, s47, s13
	global_load_lds_dwordx4 v[218:219], off
	v_lshl_add_u64 v[220:221], s[44:45], 0, v[164:165]
	s_mov_b32 m0, s71
	v_lshl_add_u64 v[222:223], s[54:55], 0, v[166:167]
	global_load_lds_dwordx4 v[220:221], off
	v_lshl_add_u64 v[220:221], s[44:45], 0, v[168:169]
	s_add_i32 m0, s71, 0x2000
	s_nop 0
	global_load_lds_dwordx4 v[220:221], off
	v_lshl_add_u64 v[220:221], s[54:55], 0, v[162:163]
	s_mov_b32 m0, s14
	s_nop 0
	global_load_lds_dwordx4 v[220:221], off
	s_mov_b32 m0, s15
	s_nop 0
	global_load_lds_dwordx4 v[222:223], off
	s_waitcnt vmcnt(8)
	s_waitcnt lgkmcnt(0)
	s_setprio 1
	s_barrier
	v_mfma_f32_16x16x32_bf16 v[62:65], v[82:85], v[178:181], v[62:65]
	v_mfma_f32_16x16x32_bf16 v[58:61], v[94:97], v[178:181], v[58:61]
	v_mfma_f32_16x16x32_bf16 v[46:49], v[82:85], v[192:195], v[46:49]
	v_mfma_f32_16x16x32_bf16 v[42:45], v[94:97], v[192:195], v[42:45]
	v_mfma_f32_16x16x32_bf16 v[30:33], v[82:85], v[200:203], v[30:33]
	v_mfma_f32_16x16x32_bf16 v[26:29], v[94:97], v[200:203], v[26:29]
	v_mfma_f32_16x16x32_bf16 v[14:17], v[82:85], v[208:211], v[14:17]
	v_mfma_f32_16x16x32_bf16 v[10:13], v[94:97], v[208:211], v[10:13]
	s_setprio 0
	s_setprio 1
	v_mfma_f32_16x16x32_bf16 v[62:65], v[86:89], v[182:185], v[62:65]
	v_mfma_f32_16x16x32_bf16 v[58:61], v[98:101], v[182:185], v[58:61]
	v_mfma_f32_16x16x32_bf16 v[46:49], v[86:89], v[196:199], v[46:49]
	v_mfma_f32_16x16x32_bf16 v[42:45], v[98:101], v[196:199], v[42:45]
	v_mfma_f32_16x16x32_bf16 v[30:33], v[86:89], v[204:207], v[30:33]
	v_mfma_f32_16x16x32_bf16 v[26:29], v[98:101], v[204:207], v[26:29]
	v_mfma_f32_16x16x32_bf16 v[14:17], v[86:89], v[212:215], v[14:17]
	v_mfma_f32_16x16x32_bf16 v[10:13], v[98:101], v[212:215], v[10:13]
	s_setprio 0
	s_setprio 1
	v_mfma_f32_16x16x32_bf16 v[54:57], v[146:149], v[178:181], v[54:57]
	v_mfma_f32_16x16x32_bf16 v[50:53], v[154:157], v[178:181], v[50:53]
	v_mfma_f32_16x16x32_bf16 v[38:41], v[146:149], v[192:195], v[38:41]
	v_mfma_f32_16x16x32_bf16 v[34:37], v[154:157], v[192:195], v[34:37]
	v_mfma_f32_16x16x32_bf16 v[22:25], v[146:149], v[200:203], v[22:25]
	v_mfma_f32_16x16x32_bf16 v[18:21], v[154:157], v[200:203], v[18:21]
	v_mfma_f32_16x16x32_bf16 v[6:9], v[146:149], v[208:211], v[6:9]
	v_mfma_f32_16x16x32_bf16 v[2:5], v[154:157], v[208:211], v[2:5]
	s_setprio 0
	s_setprio 1
	v_mfma_f32_16x16x32_bf16 v[54:57], v[150:153], v[182:185], v[54:57]
	v_mfma_f32_16x16x32_bf16 v[50:53], v[158:161], v[182:185], v[50:53]
	v_mfma_f32_16x16x32_bf16 v[38:41], v[150:153], v[196:199], v[38:41]
	v_mfma_f32_16x16x32_bf16 v[34:37], v[158:161], v[196:199], v[34:37]
	v_mfma_f32_16x16x32_bf16 v[22:25], v[150:153], v[204:207], v[22:25]
	v_mfma_f32_16x16x32_bf16 v[18:21], v[158:161], v[204:207], v[18:21]
	v_mfma_f32_16x16x32_bf16 v[6:9], v[150:153], v[212:215], v[6:9]
	v_mfma_f32_16x16x32_bf16 v[2:5], v[158:161], v[212:215], v[2:5]
	s_barrier
	s_setprio 0
	s_add_i32 s71, 0, 0x18000
	s_add_i32 s72, 0, 0x1c000
	v_add_u32_e32 v98, s71, v187
	v_add_u32_e32 v158, s72, v187
	ds_read_b128 v[82:85], v98
	ds_read_b128 v[86:89], v98 offset:1024
	ds_read_b128 v[94:97], v98 offset:2048
	ds_read_b128 v[98:101], v98 offset:3072
	ds_read_b128 v[146:149], v158
	ds_read_b128 v[150:153], v158 offset:1024
	ds_read_b128 v[154:157], v158 offset:2048
	ds_read_b128 v[158:161], v158 offset:3072
	s_add_u32 s44, s54, 0x160000
	s_addc_u32 s45, s55, 0
	s_mov_b32 m0, s18
	v_lshl_add_u64 v[224:225], s[44:45], 0, v[162:163]
	ds_read_b128 v[178:181], v190 offset:32768
	ds_read_b128 v[182:185], v190 offset:33792
	ds_read_b128 v[192:195], v190 offset:34816
	ds_read_b128 v[196:199], v190 offset:35840
	ds_read_b128 v[200:203], v190 offset:36864
	ds_read_b128 v[204:207], v190 offset:37888
	ds_read_b128 v[208:211], v190 offset:38912
	ds_read_b128 v[212:215], v190 offset:39936
	global_load_lds_dwordx4 v[224:225], off
	v_lshl_add_u64 v[224:225], s[44:45], 0, v[166:167]
	s_mov_b32 m0, s19
	s_nop 0
	global_load_lds_dwordx4 v[224:225], off
	s_waitcnt vmcnt(8)
	s_waitcnt lgkmcnt(0)
	s_setprio 1
	s_barrier
	v_mfma_f32_16x16x32_bf16 v[142:145], v[82:85], v[178:181], v[142:145]
	v_mfma_f32_16x16x32_bf16 v[138:141], v[94:97], v[178:181], v[138:141]
	v_mfma_f32_16x16x32_bf16 v[126:129], v[82:85], v[192:195], v[126:129]
	v_mfma_f32_16x16x32_bf16 v[122:125], v[94:97], v[192:195], v[122:125]
	v_mfma_f32_16x16x32_bf16 v[110:113], v[82:85], v[200:203], v[110:113]
	v_mfma_f32_16x16x32_bf16 v[106:109], v[94:97], v[200:203], v[106:109]
	v_mfma_f32_16x16x32_bf16 v[78:81], v[82:85], v[208:211], v[78:81]
	v_mfma_f32_16x16x32_bf16 v[74:77], v[94:97], v[208:211], v[74:77]
	s_setprio 0
	s_setprio 1
	v_mfma_f32_16x16x32_bf16 v[142:145], v[86:89], v[182:185], v[142:145]
	v_mfma_f32_16x16x32_bf16 v[138:141], v[98:101], v[182:185], v[138:141]
	v_mfma_f32_16x16x32_bf16 v[126:129], v[86:89], v[196:199], v[126:129]
	v_mfma_f32_16x16x32_bf16 v[122:125], v[98:101], v[196:199], v[122:125]
	v_mfma_f32_16x16x32_bf16 v[110:113], v[86:89], v[204:207], v[110:113]
	v_mfma_f32_16x16x32_bf16 v[106:109], v[98:101], v[204:207], v[106:109]
	v_mfma_f32_16x16x32_bf16 v[78:81], v[86:89], v[212:215], v[78:81]
	v_mfma_f32_16x16x32_bf16 v[74:77], v[98:101], v[212:215], v[74:77]
	s_setprio 0
	s_setprio 1
	v_mfma_f32_16x16x32_bf16 v[134:137], v[146:149], v[178:181], v[134:137]
	v_mfma_f32_16x16x32_bf16 v[130:133], v[154:157], v[178:181], v[130:133]
	v_mfma_f32_16x16x32_bf16 v[118:121], v[146:149], v[192:195], v[118:121]
	v_mfma_f32_16x16x32_bf16 v[114:117], v[154:157], v[192:195], v[114:117]
	v_mfma_f32_16x16x32_bf16 v[102:105], v[146:149], v[200:203], v[102:105]
	v_mfma_f32_16x16x32_bf16 v[90:93], v[154:157], v[200:203], v[90:93]
	v_mfma_f32_16x16x32_bf16 v[70:73], v[146:149], v[208:211], v[70:73]
	v_mfma_f32_16x16x32_bf16 v[66:69], v[154:157], v[208:211], v[66:69]
	s_setprio 0
	s_setprio 1
	v_mfma_f32_16x16x32_bf16 v[134:137], v[150:153], v[182:185], v[134:137]
	v_mfma_f32_16x16x32_bf16 v[130:133], v[158:161], v[182:185], v[130:133]
	v_mfma_f32_16x16x32_bf16 v[118:121], v[150:153], v[196:199], v[118:121]
	v_mfma_f32_16x16x32_bf16 v[114:117], v[158:161], v[196:199], v[114:117]
	v_mfma_f32_16x16x32_bf16 v[102:105], v[150:153], v[204:207], v[102:105]
	v_mfma_f32_16x16x32_bf16 v[90:93], v[158:161], v[204:207], v[90:93]
	v_mfma_f32_16x16x32_bf16 v[70:73], v[150:153], v[212:215], v[70:73]
	v_mfma_f32_16x16x32_bf16 v[66:69], v[158:161], v[212:215], v[66:69]
	s_barrier
	s_setprio 0
	s_add_i32 s44, s71, s13
	v_lshl_add_u64 v[216:217], v[216:217], 0, s[26:27]
	s_mov_b32 m0, s44
	ds_read_b128 v[178:181], v190 offset:49152
	ds_read_b128 v[182:185], v190 offset:50176
	ds_read_b128 v[192:195], v190 offset:51200
	ds_read_b128 v[196:199], v190 offset:52224
	ds_read_b128 v[200:203], v190 offset:53248
	ds_read_b128 v[204:207], v190 offset:54272
	ds_read_b128 v[208:211], v190 offset:55296
	ds_read_b128 v[212:215], v190 offset:56320
	global_load_lds_dwordx4 v[216:217], off
	s_add_i32 m0, s44, 0x2000
	s_add_u32 s44, s52, 0x160080
	v_lshl_add_u64 v[216:217], v[218:219], 0, s[26:27]
	s_addc_u32 s45, s53, 0
	s_add_i32 s52, s72, s13
	global_load_lds_dwordx4 v[216:217], off
	v_lshl_add_u64 v[216:217], s[44:45], 0, v[164:165]
	s_mov_b32 m0, s52
	s_nop 0
	global_load_lds_dwordx4 v[216:217], off
	v_lshl_add_u64 v[216:217], s[44:45], 0, v[168:169]
	s_add_i32 m0, s52, 0x2000
	s_nop 0
	global_load_lds_dwordx4 v[216:217], off
	v_lshl_add_u64 v[216:217], v[220:221], 0, s[26:27]
	s_mov_b32 m0, s40
	s_nop 0
	global_load_lds_dwordx4 v[216:217], off
	v_lshl_add_u64 v[216:217], v[222:223], 0, s[26:27]
	s_mov_b32 m0, s41
	s_nop 0
	global_load_lds_dwordx4 v[216:217], off
	s_waitcnt vmcnt(8)
	s_waitcnt lgkmcnt(0)
	s_setprio 1
	s_barrier
	v_mfma_f32_16x16x32_bf16 v[62:65], v[82:85], v[178:181], v[62:65]
	v_mfma_f32_16x16x32_bf16 v[58:61], v[94:97], v[178:181], v[58:61]
	v_mfma_f32_16x16x32_bf16 v[46:49], v[82:85], v[192:195], v[46:49]
	v_mfma_f32_16x16x32_bf16 v[42:45], v[94:97], v[192:195], v[42:45]
	v_mfma_f32_16x16x32_bf16 v[30:33], v[82:85], v[200:203], v[30:33]
	v_mfma_f32_16x16x32_bf16 v[26:29], v[94:97], v[200:203], v[26:29]
	v_mfma_f32_16x16x32_bf16 v[14:17], v[82:85], v[208:211], v[14:17]
	v_mfma_f32_16x16x32_bf16 v[10:13], v[94:97], v[208:211], v[10:13]
	s_setprio 0
	s_setprio 1
	v_mfma_f32_16x16x32_bf16 v[62:65], v[86:89], v[182:185], v[62:65]
	v_mfma_f32_16x16x32_bf16 v[58:61], v[98:101], v[182:185], v[58:61]
	v_mfma_f32_16x16x32_bf16 v[46:49], v[86:89], v[196:199], v[46:49]
	v_mfma_f32_16x16x32_bf16 v[42:45], v[98:101], v[196:199], v[42:45]
	v_mfma_f32_16x16x32_bf16 v[30:33], v[86:89], v[204:207], v[30:33]
	v_mfma_f32_16x16x32_bf16 v[26:29], v[98:101], v[204:207], v[26:29]
	v_mfma_f32_16x16x32_bf16 v[14:17], v[86:89], v[212:215], v[14:17]
	v_mfma_f32_16x16x32_bf16 v[10:13], v[98:101], v[212:215], v[10:13]
	s_setprio 0
	s_setprio 1
	v_mfma_f32_16x16x32_bf16 v[54:57], v[146:149], v[178:181], v[54:57]
	v_mfma_f32_16x16x32_bf16 v[50:53], v[154:157], v[178:181], v[50:53]
	v_mfma_f32_16x16x32_bf16 v[38:41], v[146:149], v[192:195], v[38:41]
	v_mfma_f32_16x16x32_bf16 v[34:37], v[154:157], v[192:195], v[34:37]
	v_mfma_f32_16x16x32_bf16 v[22:25], v[146:149], v[200:203], v[22:25]
	v_mfma_f32_16x16x32_bf16 v[18:21], v[154:157], v[200:203], v[18:21]
	v_mfma_f32_16x16x32_bf16 v[6:9], v[146:149], v[208:211], v[6:9]
	v_mfma_f32_16x16x32_bf16 v[2:5], v[154:157], v[208:211], v[2:5]
	s_setprio 0
	s_setprio 1
	v_mfma_f32_16x16x32_bf16 v[54:57], v[150:153], v[182:185], v[54:57]
	v_mfma_f32_16x16x32_bf16 v[50:53], v[158:161], v[182:185], v[50:53]
	v_mfma_f32_16x16x32_bf16 v[38:41], v[150:153], v[196:199], v[38:41]
	v_mfma_f32_16x16x32_bf16 v[34:37], v[158:161], v[196:199], v[34:37]
	v_mfma_f32_16x16x32_bf16 v[22:25], v[150:153], v[204:207], v[22:25]
	v_mfma_f32_16x16x32_bf16 v[18:21], v[158:161], v[204:207], v[18:21]
	v_mfma_f32_16x16x32_bf16 v[6:9], v[150:153], v[212:215], v[6:9]
	v_mfma_f32_16x16x32_bf16 v[2:5], v[158:161], v[212:215], v[2:5]
	s_barrier
	s_setprio 0
	s_add_i32 s70, s70, 2
	s_add_u32 s68, s68, 0x100
	s_addc_u32 s69, s69, 0
	s_cmpk_gt_u32 s70, 0x55
	s_mov_b64 s[44:45], s[6:7]
	s_cbranch_scc0 .LBB0_266
	s_and_b64 vcc, exec, s[28:29]
	s_cbranch_vccz .LBB0_269
	s_barrier

.LBB0_632:
	ds_read_b128 v[146:149], v162
	ds_read_b128 v[150:153], v162 offset:1024
	ds_read_b128 v[154:157], v162 offset:2048
	ds_read_b128 v[168:171], v162 offset:3072
	ds_read_b128 v[172:175], v163
	ds_read_b128 v[176:179], v163 offset:1024
	ds_read_b128 v[180:183], v163 offset:2048
	ds_read_b128 v[184:187], v163 offset:3072
	s_add_u32 s15, s52, 0xfff80080
	s_addc_u32 s16, s53, -1
	s_cmp_eq_u32 s14, 28
	s_cselect_b32 s57, s7, s16
	s_cselect_b32 s56, s9, s15
	s_cselect_b32 s55, s10, s13
	s_cselect_b32 s54, s11, s12
	v_lshl_add_u64 v[158:159], s[52:53], 0, v[140:141]
	s_add_i32 m0, s39, 0xc000
	ds_read_b128 v[188:191], v164
	ds_read_b128 v[192:195], v164 offset:1024
	ds_read_b128 v[196:199], v164 offset:2048
	ds_read_b128 v[200:203], v164 offset:3072
	ds_read_b128 v[204:207], v164 offset:4096
	ds_read_b128 v[208:211], v164 offset:5120
	ds_read_b128 v[212:215], v164 offset:6144
	ds_read_b128 v[216:219], v164 offset:7168
	global_load_lds_dwordx4 v[158:159], off
	v_lshl_add_u64 v[158:159], s[52:53], 0, v[138:139]
	s_add_i32 m0, s39, 0xe000
	s_nop 0
	global_load_lds_dwordx4 v[158:159], off
	s_waitcnt vmcnt(8)
	s_waitcnt lgkmcnt(0)
	s_setprio 1
	s_barrier
	v_mfma_f32_16x16x32_bf16 v[126:129], v[146:149], v[188:191], v[126:129]
	v_mfma_f32_16x16x32_bf16 v[122:125], v[154:157], v[188:191], v[122:125]
	v_mfma_f32_16x16x32_bf16 v[110:113], v[146:149], v[196:199], v[110:113]
	v_mfma_f32_16x16x32_bf16 v[106:109], v[154:157], v[196:199], v[106:109]
	v_mfma_f32_16x16x32_bf16 v[94:97], v[146:149], v[204:207], v[94:97]
	v_mfma_f32_16x16x32_bf16 v[90:93], v[154:157], v[204:207], v[90:93]
	v_mfma_f32_16x16x32_bf16 v[78:81], v[146:149], v[212:215], v[78:81]
	v_mfma_f32_16x16x32_bf16 v[74:77], v[154:157], v[212:215], v[74:77]
	s_setprio 0
	s_setprio 1
	v_mfma_f32_16x16x32_bf16 v[126:129], v[150:153], v[192:195], v[126:129]
	v_mfma_f32_16x16x32_bf16 v[122:125], v[168:171], v[192:195], v[122:125]
	v_mfma_f32_16x16x32_bf16 v[110:113], v[150:153], v[200:203], v[110:113]
	v_mfma_f32_16x16x32_bf16 v[106:109], v[168:171], v[200:203], v[106:109]
	v_mfma_f32_16x16x32_bf16 v[94:97], v[150:153], v[208:211], v[94:97]
	v_mfma_f32_16x16x32_bf16 v[90:93], v[168:171], v[208:211], v[90:93]
	v_mfma_f32_16x16x32_bf16 v[78:81], v[150:153], v[216:219], v[78:81]
	v_mfma_f32_16x16x32_bf16 v[74:77], v[168:171], v[216:219], v[74:77]
	s_setprio 0
	s_setprio 1
	v_mfma_f32_16x16x32_bf16 v[118:121], v[172:175], v[188:191], v[118:121]
	v_mfma_f32_16x16x32_bf16 v[114:117], v[180:183], v[188:191], v[114:117]
	v_mfma_f32_16x16x32_bf16 v[102:105], v[172:175], v[196:199], v[102:105]
	v_mfma_f32_16x16x32_bf16 v[98:101], v[180:183], v[196:199], v[98:101]
	v_mfma_f32_16x16x32_bf16 v[86:89], v[172:175], v[204:207], v[86:89]
	v_mfma_f32_16x16x32_bf16 v[82:85], v[180:183], v[204:207], v[82:85]
	v_mfma_f32_16x16x32_bf16 v[70:73], v[172:175], v[212:215], v[70:73]
	v_mfma_f32_16x16x32_bf16 v[66:69], v[180:183], v[212:215], v[66:69]
	s_setprio 0
	s_setprio 1
	v_mfma_f32_16x16x32_bf16 v[118:121], v[176:179], v[192:195], v[118:121]
	v_mfma_f32_16x16x32_bf16 v[114:117], v[184:187], v[192:195], v[114:117]
	v_mfma_f32_16x16x32_bf16 v[102:105], v[176:179], v[200:203], v[102:105]
	v_mfma_f32_16x16x32_bf16 v[98:101], v[184:187], v[200:203], v[98:101]
	v_mfma_f32_16x16x32_bf16 v[86:89], v[176:179], v[208:211], v[86:89]
	v_mfma_f32_16x16x32_bf16 v[82:85], v[184:187], v[208:211], v[82:85]
	v_mfma_f32_16x16x32_bf16 v[70:73], v[176:179], v[216:219], v[70:73]
	v_mfma_f32_16x16x32_bf16 v[66:69], v[184:187], v[216:219], v[66:69]
	s_barrier
	s_setprio 0
	s_add_i32 s15, s75, s38
	v_lshl_add_u64 v[158:159], s[54:55], 0, v[132:133]
	s_mov_b32 m0, s15
	ds_read_b128 v[188:191], v164 offset:16384
	ds_read_b128 v[192:195], v164 offset:17408
	ds_read_b128 v[196:199], v164 offset:18432
	ds_read_b128 v[200:203], v164 offset:19456
	ds_read_b128 v[204:207], v164 offset:20480
	ds_read_b128 v[208:211], v164 offset:21504
	ds_read_b128 v[212:215], v164 offset:22528
	ds_read_b128 v[216:219], v164 offset:23552
	global_load_lds_dwordx4 v[158:159], off
	s_add_i32 m0, s15, 0x2000
	s_add_u32 s58, s54, 0x80000
	v_lshl_add_u64 v[220:221], s[54:55], 0, v[136:137]
	s_addc_u32 s59, s55, 0
	s_add_i32 s15, s76, s38
	global_load_lds_dwordx4 v[220:221], off
	v_lshl_add_u64 v[222:223], s[58:59], 0, v[132:133]
	s_mov_b32 m0, s15
	v_lshl_add_u64 v[224:225], s[56:57], 0, v[134:135]
	global_load_lds_dwordx4 v[222:223], off
	v_lshl_add_u64 v[222:223], s[58:59], 0, v[136:137]
	s_add_i32 m0, s15, 0x2000
	s_nop 0
	global_load_lds_dwordx4 v[222:223], off
	v_lshl_add_u64 v[222:223], s[56:57], 0, v[130:131]
	s_mov_b32 m0, s39
	s_nop 0
	global_load_lds_dwordx4 v[222:223], off
	s_mov_b32 m0, s46
	s_nop 0
	global_load_lds_dwordx4 v[224:225], off
	s_waitcnt vmcnt(8)
	s_waitcnt lgkmcnt(0)
	s_setprio 1
	s_barrier
	v_mfma_f32_16x16x32_bf16 v[62:65], v[146:149], v[188:191], v[62:65]
	v_mfma_f32_16x16x32_bf16 v[58:61], v[154:157], v[188:191], v[58:61]
	v_mfma_f32_16x16x32_bf16 v[46:49], v[146:149], v[196:199], v[46:49]
	v_mfma_f32_16x16x32_bf16 v[42:45], v[154:157], v[196:199], v[42:45]
	v_mfma_f32_16x16x32_bf16 v[30:33], v[146:149], v[204:207], v[30:33]
	v_mfma_f32_16x16x32_bf16 v[26:29], v[154:157], v[204:207], v[26:29]
	v_mfma_f32_16x16x32_bf16 v[14:17], v[146:149], v[212:215], v[14:17]
	v_mfma_f32_16x16x32_bf16 v[10:13], v[154:157], v[212:215], v[10:13]
	s_setprio 0
	s_setprio 1
	v_mfma_f32_16x16x32_bf16 v[62:65], v[150:153], v[192:195], v[62:65]
	v_mfma_f32_16x16x32_bf16 v[58:61], v[168:171], v[192:195], v[58:61]
	v_mfma_f32_16x16x32_bf16 v[46:49], v[150:153], v[200:203], v[46:49]
	v_mfma_f32_16x16x32_bf16 v[42:45], v[168:171], v[200:203], v[42:45]
	v_mfma_f32_16x16x32_bf16 v[30:33], v[150:153], v[208:211], v[30:33]
	v_mfma_f32_16x16x32_bf16 v[26:29], v[168:171], v[208:211], v[26:29]
	v_mfma_f32_16x16x32_bf16 v[14:17], v[150:153], v[216:219], v[14:17]
	v_mfma_f32_16x16x32_bf16 v[10:13], v[168:171], v[216:219], v[10:13]
	s_setprio 0
	s_setprio 1
	v_mfma_f32_16x16x32_bf16 v[54:57], v[172:175], v[188:191], v[54:57]
	v_mfma_f32_16x16x32_bf16 v[50:53], v[180:183], v[188:191], v[50:53]
	v_mfma_f32_16x16x32_bf16 v[38:41], v[172:175], v[196:199], v[38:41]
	v_mfma_f32_16x16x32_bf16 v[34:37], v[180:183], v[196:199], v[34:37]
	v_mfma_f32_16x16x32_bf16 v[22:25], v[172:175], v[204:207], v[22:25]
	v_mfma_f32_16x16x32_bf16 v[18:21], v[180:183], v[204:207], v[18:21]
	v_mfma_f32_16x16x32_bf16 v[6:9], v[172:175], v[212:215], v[6:9]
	v_mfma_f32_16x16x32_bf16 v[2:5], v[180:183], v[212:215], v[2:5]
	s_setprio 0
	s_setprio 1
	v_mfma_f32_16x16x32_bf16 v[54:57], v[176:179], v[192:195], v[54:57]
	v_mfma_f32_16x16x32_bf16 v[50:53], v[184:187], v[192:195], v[50:53]
	v_mfma_f32_16x16x32_bf16 v[38:41], v[176:179], v[200:203], v[38:41]
	v_mfma_f32_16x16x32_bf16 v[34:37], v[184:187], v[200:203], v[34:37]
	v_mfma_f32_16x16x32_bf16 v[22:25], v[176:179], v[208:211], v[22:25]
	v_mfma_f32_16x16x32_bf16 v[18:21], v[184:187], v[208:211], v[18:21]
	v_mfma_f32_16x16x32_bf16 v[6:9], v[176:179], v[216:219], v[6:9]
	v_mfma_f32_16x16x32_bf16 v[2:5], v[184:187], v[216:219], v[2:5]
	s_barrier
	s_setprio 0
	s_add_i32 s15, 0, 0x18000
	v_add_u32_e32 v167, s15, v161
	s_add_i32 s16, 0, 0x1c000
	ds_read_b128 v[146:149], v167
	ds_read_b128 v[150:153], v167 offset:1024
	ds_read_b128 v[154:157], v167 offset:2048
	ds_read_b128 v[168:171], v167 offset:3072
	v_add_u32_e32 v167, s16, v161
	ds_read_b128 v[172:175], v167
	ds_read_b128 v[176:179], v167 offset:1024
	ds_read_b128 v[180:183], v167 offset:2048
	ds_read_b128 v[184:187], v167 offset:3072
	s_add_u32 s56, s56, 0x80000
	s_addc_u32 s57, s57, 0
	s_mov_b32 m0, s47
	v_lshl_add_u64 v[226:227], s[56:57], 0, v[130:131]
	ds_read_b128 v[188:191], v164 offset:32768
	ds_read_b128 v[192:195], v164 offset:33792
	ds_read_b128 v[196:199], v164 offset:34816
	ds_read_b128 v[200:203], v164 offset:35840
	ds_read_b128 v[204:207], v164 offset:36864
	ds_read_b128 v[208:211], v164 offset:37888
	ds_read_b128 v[212:215], v164 offset:38912
	ds_read_b128 v[216:219], v164 offset:39936
	global_load_lds_dwordx4 v[226:227], off
	v_lshl_add_u64 v[226:227], s[56:57], 0, v[134:135]
	s_mov_b32 m0, s48
	s_nop 0
	global_load_lds_dwordx4 v[226:227], off
	s_waitcnt vmcnt(8)
	s_waitcnt lgkmcnt(0)
	s_setprio 1
	s_barrier
	v_mfma_f32_16x16x32_bf16 v[126:129], v[146:149], v[188:191], v[126:129]
	v_mfma_f32_16x16x32_bf16 v[122:125], v[154:157], v[188:191], v[122:125]
	v_mfma_f32_16x16x32_bf16 v[110:113], v[146:149], v[196:199], v[110:113]
	v_mfma_f32_16x16x32_bf16 v[106:109], v[154:157], v[196:199], v[106:109]
	v_mfma_f32_16x16x32_bf16 v[94:97], v[146:149], v[204:207], v[94:97]
	v_mfma_f32_16x16x32_bf16 v[90:93], v[154:157], v[204:207], v[90:93]
	v_mfma_f32_16x16x32_bf16 v[78:81], v[146:149], v[212:215], v[78:81]
	v_mfma_f32_16x16x32_bf16 v[74:77], v[154:157], v[212:215], v[74:77]
	s_setprio 0
	s_setprio 1
	v_mfma_f32_16x16x32_bf16 v[126:129], v[150:153], v[192:195], v[126:129]
	v_mfma_f32_16x16x32_bf16 v[122:125], v[168:171], v[192:195], v[122:125]
	v_mfma_f32_16x16x32_bf16 v[110:113], v[150:153], v[200:203], v[110:113]
	v_mfma_f32_16x16x32_bf16 v[106:109], v[168:171], v[200:203], v[106:109]
	v_mfma_f32_16x16x32_bf16 v[94:97], v[150:153], v[208:211], v[94:97]
	v_mfma_f32_16x16x32_bf16 v[90:93], v[168:171], v[208:211], v[90:93]
	v_mfma_f32_16x16x32_bf16 v[78:81], v[150:153], v[216:219], v[78:81]
	v_mfma_f32_16x16x32_bf16 v[74:77], v[168:171], v[216:219], v[74:77]
	s_setprio 0
	s_setprio 1
	v_mfma_f32_16x16x32_bf16 v[118:121], v[172:175], v[188:191], v[118:121]
	v_mfma_f32_16x16x32_bf16 v[114:117], v[180:183], v[188:191], v[114:117]
	v_mfma_f32_16x16x32_bf16 v[102:105], v[172:175], v[196:199], v[102:105]
	v_mfma_f32_16x16x32_bf16 v[98:101], v[180:183], v[196:199], v[98:101]
	v_mfma_f32_16x16x32_bf16 v[86:89], v[172:175], v[204:207], v[86:89]
	v_mfma_f32_16x16x32_bf16 v[82:85], v[180:183], v[204:207], v[82:85]
	v_mfma_f32_16x16x32_bf16 v[70:73], v[172:175], v[212:215], v[70:73]
	v_mfma_f32_16x16x32_bf16 v[66:69], v[180:183], v[212:215], v[66:69]
	s_setprio 0
	s_setprio 1
	v_mfma_f32_16x16x32_bf16 v[118:121], v[176:179], v[192:195], v[118:121]
	v_mfma_f32_16x16x32_bf16 v[114:117], v[184:187], v[192:195], v[114:117]
	v_mfma_f32_16x16x32_bf16 v[102:105], v[176:179], v[200:203], v[102:105]
	v_mfma_f32_16x16x32_bf16 v[98:101], v[184:187], v[200:203], v[98:101]
	v_mfma_f32_16x16x32_bf16 v[86:89], v[176:179], v[208:211], v[86:89]
	v_mfma_f32_16x16x32_bf16 v[82:85], v[184:187], v[208:211], v[82:85]
	v_mfma_f32_16x16x32_bf16 v[70:73], v[176:179], v[216:219], v[70:73]
	v_mfma_f32_16x16x32_bf16 v[66:69], v[184:187], v[216:219], v[66:69]
	s_barrier
	s_setprio 0
	s_add_i32 s15, s15, s38
	v_lshl_add_u64 v[158:159], v[158:159], 0, s[24:25]
	s_mov_b32 m0, s15
	ds_read_b128 v[188:191], v164 offset:49152
	ds_read_b128 v[192:195], v164 offset:50176
	ds_read_b128 v[196:199], v164 offset:51200
	ds_read_b128 v[200:203], v164 offset:52224
	ds_read_b128 v[204:207], v164 offset:53248
	ds_read_b128 v[208:211], v164 offset:54272
	ds_read_b128 v[212:215], v164 offset:55296
	ds_read_b128 v[216:219], v164 offset:56320
	global_load_lds_dwordx4 v[158:159], off
	s_add_i32 m0, s15, 0x2000
	s_add_u32 s54, s54, 0x80080
	v_lshl_add_u64 v[158:159], v[220:221], 0, s[24:25]
	s_addc_u32 s55, s55, 0
	s_add_i32 s15, s16, s38
	global_load_lds_dwordx4 v[158:159], off
	v_lshl_add_u64 v[158:159], s[54:55], 0, v[132:133]
	s_mov_b32 m0, s15
	s_nop 0
	global_load_lds_dwordx4 v[158:159], off
	v_lshl_add_u64 v[158:159], s[54:55], 0, v[136:137]
	s_add_i32 m0, s15, 0x2000
	s_nop 0
	global_load_lds_dwordx4 v[158:159], off
	v_lshl_add_u64 v[158:159], v[222:223], 0, s[24:25]
	s_mov_b32 m0, s71
	s_nop 0
	global_load_lds_dwordx4 v[158:159], off
	v_lshl_add_u64 v[158:159], v[224:225], 0, s[24:25]
	s_mov_b32 m0, s72
	s_nop 0
	global_load_lds_dwordx4 v[158:159], off
	s_waitcnt vmcnt(8)
	s_waitcnt lgkmcnt(0)
	s_setprio 1
	s_barrier
	v_mfma_f32_16x16x32_bf16 v[62:65], v[146:149], v[188:191], v[62:65]
	v_mfma_f32_16x16x32_bf16 v[58:61], v[154:157], v[188:191], v[58:61]
	v_mfma_f32_16x16x32_bf16 v[46:49], v[146:149], v[196:199], v[46:49]
	v_mfma_f32_16x16x32_bf16 v[42:45], v[154:157], v[196:199], v[42:45]
	v_mfma_f32_16x16x32_bf16 v[30:33], v[146:149], v[204:207], v[30:33]
	v_mfma_f32_16x16x32_bf16 v[26:29], v[154:157], v[204:207], v[26:29]
	v_mfma_f32_16x16x32_bf16 v[14:17], v[146:149], v[212:215], v[14:17]
	v_mfma_f32_16x16x32_bf16 v[10:13], v[154:157], v[212:215], v[10:13]
	s_setprio 0
	s_setprio 1
	v_mfma_f32_16x16x32_bf16 v[62:65], v[150:153], v[192:195], v[62:65]
	v_mfma_f32_16x16x32_bf16 v[58:61], v[168:171], v[192:195], v[58:61]
	v_mfma_f32_16x16x32_bf16 v[46:49], v[150:153], v[200:203], v[46:49]
	v_mfma_f32_16x16x32_bf16 v[42:45], v[168:171], v[200:203], v[42:45]
	v_mfma_f32_16x16x32_bf16 v[30:33], v[150:153], v[208:211], v[30:33]
	v_mfma_f32_16x16x32_bf16 v[26:29], v[168:171], v[208:211], v[26:29]
	v_mfma_f32_16x16x32_bf16 v[14:17], v[150:153], v[216:219], v[14:17]
	v_mfma_f32_16x16x32_bf16 v[10:13], v[168:171], v[216:219], v[10:13]
	s_setprio 0
	s_setprio 1
	v_mfma_f32_16x16x32_bf16 v[54:57], v[172:175], v[188:191], v[54:57]
	v_mfma_f32_16x16x32_bf16 v[50:53], v[180:183], v[188:191], v[50:53]
	v_mfma_f32_16x16x32_bf16 v[38:41], v[172:175], v[196:199], v[38:41]
	v_mfma_f32_16x16x32_bf16 v[34:37], v[180:183], v[196:199], v[34:37]
	v_mfma_f32_16x16x32_bf16 v[22:25], v[172:175], v[204:207], v[22:25]
	v_mfma_f32_16x16x32_bf16 v[18:21], v[180:183], v[204:207], v[18:21]
	v_mfma_f32_16x16x32_bf16 v[6:9], v[172:175], v[212:215], v[6:9]
	v_mfma_f32_16x16x32_bf16 v[2:5], v[180:183], v[212:215], v[2:5]
	s_setprio 0
	s_setprio 1
	v_mfma_f32_16x16x32_bf16 v[54:57], v[176:179], v[192:195], v[54:57]
	v_mfma_f32_16x16x32_bf16 v[50:53], v[184:187], v[192:195], v[50:53]
	v_mfma_f32_16x16x32_bf16 v[38:41], v[176:179], v[200:203], v[38:41]
	v_mfma_f32_16x16x32_bf16 v[34:37], v[184:187], v[200:203], v[34:37]
	v_mfma_f32_16x16x32_bf16 v[22:25], v[176:179], v[208:211], v[22:25]
	v_mfma_f32_16x16x32_bf16 v[18:21], v[184:187], v[208:211], v[18:21]
	v_mfma_f32_16x16x32_bf16 v[6:9], v[176:179], v[216:219], v[6:9]
	v_mfma_f32_16x16x32_bf16 v[2:5], v[184:187], v[216:219], v[2:5]
	s_barrier
	s_setprio 0
	s_add_i32 s14, s14, 2
	s_add_u32 s12, s12, 0x100
	s_addc_u32 s13, s13, 0
	s_add_u32 s52, s52, 0x100
	s_addc_u32 s53, s53, 0
	s_cmp_gt_u32 s14, 29
	s_cbranch_scc0 .LBB0_632
	s_and_b64 vcc, exec, s[26:27]
	s_cbranch_vccz .LBB0_635
	s_barrier

.LBB0_1130:
	ds_read_b128 v[86:89], v166
	ds_read_b128 v[90:93], v166 offset:1024
	ds_read_b128 v[98:101], v166 offset:2048
	ds_read_b128 v[106:109], v166 offset:3072
	ds_read_b128 v[170:173], v167
	ds_read_b128 v[174:177], v167 offset:1024
	ds_read_b128 v[178:181], v167 offset:2048
	ds_read_b128 v[182:185], v167 offset:3072
	s_add_u32 s62, s60, 0xfff80080
	s_addc_u32 s63, s61, -1
	s_cmp_eq_u32 s70, 28
	s_cselect_b32 s65, s53, s63
	s_cselect_b32 s64, s66, s62
	s_cselect_b32 s63, s45, s69
	s_cselect_b32 s62, s67, s68
	v_lshl_add_u64 v[162:163], s[60:61], 0, v[156:157]
	s_add_i32 m0, s14, 0xc000
	ds_read_b128 v[186:189], v168
	ds_read_b128 v[190:193], v168 offset:1024
	ds_read_b128 v[194:197], v168 offset:2048
	ds_read_b128 v[198:201], v168 offset:3072
	ds_read_b128 v[202:205], v168 offset:4096
	ds_read_b128 v[206:209], v168 offset:5120
	ds_read_b128 v[210:213], v168 offset:6144
	ds_read_b128 v[214:217], v168 offset:7168
	global_load_lds_dwordx4 v[162:163], off
	v_lshl_add_u64 v[162:163], s[60:61], 0, v[154:155]
	s_add_i32 m0, s14, 0xe000
	s_nop 0
	global_load_lds_dwordx4 v[162:163], off
	s_waitcnt vmcnt(8)
	s_waitcnt lgkmcnt(0)
	s_setprio 1
	s_barrier
	v_mfma_f32_16x16x32_bf16 v[142:145], v[86:89], v[186:189], v[142:145]
	v_mfma_f32_16x16x32_bf16 v[134:137], v[98:101], v[186:189], v[134:137]
	v_mfma_f32_16x16x32_bf16 v[126:129], v[86:89], v[194:197], v[126:129]
	v_mfma_f32_16x16x32_bf16 v[118:121], v[98:101], v[194:197], v[118:121]
	v_mfma_f32_16x16x32_bf16 v[110:113], v[86:89], v[202:205], v[110:113]
	v_mfma_f32_16x16x32_bf16 v[94:97], v[98:101], v[202:205], v[94:97]
	v_mfma_f32_16x16x32_bf16 v[78:81], v[86:89], v[210:213], v[78:81]
	v_mfma_f32_16x16x32_bf16 v[70:73], v[98:101], v[210:213], v[70:73]
	s_setprio 0
	s_setprio 1
	v_mfma_f32_16x16x32_bf16 v[142:145], v[90:93], v[190:193], v[142:145]
	v_mfma_f32_16x16x32_bf16 v[134:137], v[106:109], v[190:193], v[134:137]
	v_mfma_f32_16x16x32_bf16 v[126:129], v[90:93], v[198:201], v[126:129]
	v_mfma_f32_16x16x32_bf16 v[118:121], v[106:109], v[198:201], v[118:121]
	v_mfma_f32_16x16x32_bf16 v[110:113], v[90:93], v[206:209], v[110:113]
	v_mfma_f32_16x16x32_bf16 v[94:97], v[106:109], v[206:209], v[94:97]
	v_mfma_f32_16x16x32_bf16 v[78:81], v[90:93], v[214:217], v[78:81]
	v_mfma_f32_16x16x32_bf16 v[70:73], v[106:109], v[214:217], v[70:73]
	s_setprio 0
	s_setprio 1
	v_mfma_f32_16x16x32_bf16 v[138:141], v[170:173], v[186:189], v[138:141]
	v_mfma_f32_16x16x32_bf16 v[130:133], v[178:181], v[186:189], v[130:133]
	v_mfma_f32_16x16x32_bf16 v[122:125], v[170:173], v[194:197], v[122:125]
	v_mfma_f32_16x16x32_bf16 v[114:117], v[178:181], v[194:197], v[114:117]
	v_mfma_f32_16x16x32_bf16 v[102:105], v[170:173], v[202:205], v[102:105]
	v_mfma_f32_16x16x32_bf16 v[82:85], v[178:181], v[202:205], v[82:85]
	v_mfma_f32_16x16x32_bf16 v[74:77], v[170:173], v[210:213], v[74:77]
	v_mfma_f32_16x16x32_bf16 v[66:69], v[178:181], v[210:213], v[66:69]
	s_setprio 0
	s_setprio 1
	v_mfma_f32_16x16x32_bf16 v[138:141], v[174:177], v[190:193], v[138:141]
	v_mfma_f32_16x16x32_bf16 v[130:133], v[182:185], v[190:193], v[130:133]
	v_mfma_f32_16x16x32_bf16 v[122:125], v[174:177], v[198:201], v[122:125]
	v_mfma_f32_16x16x32_bf16 v[114:117], v[182:185], v[198:201], v[114:117]
	v_mfma_f32_16x16x32_bf16 v[102:105], v[174:177], v[206:209], v[102:105]
	v_mfma_f32_16x16x32_bf16 v[82:85], v[182:185], v[206:209], v[82:85]
	v_mfma_f32_16x16x32_bf16 v[74:77], v[174:177], v[214:217], v[74:77]
	v_mfma_f32_16x16x32_bf16 v[66:69], v[182:185], v[214:217], v[66:69]
	s_barrier
	s_setprio 0
	s_add_i32 s71, s49, s11
	v_lshl_add_u64 v[162:163], s[62:63], 0, v[150:151]
	s_mov_b32 m0, s71
	ds_read_b128 v[186:189], v168 offset:16384
	ds_read_b128 v[190:193], v168 offset:17408
	ds_read_b128 v[194:197], v168 offset:18432
	ds_read_b128 v[198:201], v168 offset:19456
	ds_read_b128 v[202:205], v168 offset:20480
	ds_read_b128 v[206:209], v168 offset:21504
	ds_read_b128 v[210:213], v168 offset:22528
	ds_read_b128 v[214:217], v168 offset:23552
	global_load_lds_dwordx4 v[162:163], off
	s_add_i32 m0, s71, 0x2000
	s_add_u32 s72, s62, 0x80000
	v_lshl_add_u64 v[218:219], s[62:63], 0, v[146:147]
	s_addc_u32 s73, s63, 0
	s_add_i32 s71, s50, s11
	global_load_lds_dwordx4 v[218:219], off
	v_lshl_add_u64 v[220:221], s[72:73], 0, v[150:151]
	s_mov_b32 m0, s71
	v_lshl_add_u64 v[222:223], s[64:65], 0, v[148:149]
	global_load_lds_dwordx4 v[220:221], off
	v_lshl_add_u64 v[220:221], s[72:73], 0, v[146:147]
	s_add_i32 m0, s71, 0x2000
	s_nop 0
	global_load_lds_dwordx4 v[220:221], off
	v_lshl_add_u64 v[220:221], s[64:65], 0, v[152:153]
	s_mov_b32 m0, s14
	s_nop 0
	global_load_lds_dwordx4 v[220:221], off
	s_mov_b32 m0, s15
	s_nop 0
	global_load_lds_dwordx4 v[222:223], off
	s_waitcnt vmcnt(8)
	s_waitcnt lgkmcnt(0)
	s_setprio 1
	s_barrier
	v_mfma_f32_16x16x32_bf16 v[62:65], v[86:89], v[186:189], v[62:65]
	v_mfma_f32_16x16x32_bf16 v[54:57], v[98:101], v[186:189], v[54:57]
	v_mfma_f32_16x16x32_bf16 v[46:49], v[86:89], v[194:197], v[46:49]
	v_mfma_f32_16x16x32_bf16 v[38:41], v[98:101], v[194:197], v[38:41]
	v_mfma_f32_16x16x32_bf16 v[30:33], v[86:89], v[202:205], v[30:33]
	v_mfma_f32_16x16x32_bf16 v[22:25], v[98:101], v[202:205], v[22:25]
	v_mfma_f32_16x16x32_bf16 v[14:17], v[86:89], v[210:213], v[14:17]
	v_mfma_f32_16x16x32_bf16 v[6:9], v[98:101], v[210:213], v[6:9]
	s_setprio 0
	s_setprio 1
	v_mfma_f32_16x16x32_bf16 v[62:65], v[90:93], v[190:193], v[62:65]
	v_mfma_f32_16x16x32_bf16 v[54:57], v[106:109], v[190:193], v[54:57]
	v_mfma_f32_16x16x32_bf16 v[46:49], v[90:93], v[198:201], v[46:49]
	v_mfma_f32_16x16x32_bf16 v[38:41], v[106:109], v[198:201], v[38:41]
	v_mfma_f32_16x16x32_bf16 v[30:33], v[90:93], v[206:209], v[30:33]
	v_mfma_f32_16x16x32_bf16 v[22:25], v[106:109], v[206:209], v[22:25]
	v_mfma_f32_16x16x32_bf16 v[14:17], v[90:93], v[214:217], v[14:17]
	v_mfma_f32_16x16x32_bf16 v[6:9], v[106:109], v[214:217], v[6:9]
	s_setprio 0
	s_setprio 1
	v_mfma_f32_16x16x32_bf16 v[58:61], v[170:173], v[186:189], v[58:61]
	v_mfma_f32_16x16x32_bf16 v[50:53], v[178:181], v[186:189], v[50:53]
	v_mfma_f32_16x16x32_bf16 v[42:45], v[170:173], v[194:197], v[42:45]
	v_mfma_f32_16x16x32_bf16 v[34:37], v[178:181], v[194:197], v[34:37]
	v_mfma_f32_16x16x32_bf16 v[26:29], v[170:173], v[202:205], v[26:29]
	v_mfma_f32_16x16x32_bf16 v[18:21], v[178:181], v[202:205], v[18:21]
	v_mfma_f32_16x16x32_bf16 v[10:13], v[170:173], v[210:213], v[10:13]
	v_mfma_f32_16x16x32_bf16 v[2:5], v[178:181], v[210:213], v[2:5]
	s_setprio 0
	s_setprio 1
	v_mfma_f32_16x16x32_bf16 v[58:61], v[174:177], v[190:193], v[58:61]
	v_mfma_f32_16x16x32_bf16 v[50:53], v[182:185], v[190:193], v[50:53]
	v_mfma_f32_16x16x32_bf16 v[42:45], v[174:177], v[198:201], v[42:45]
	v_mfma_f32_16x16x32_bf16 v[34:37], v[182:185], v[198:201], v[34:37]
	v_mfma_f32_16x16x32_bf16 v[26:29], v[174:177], v[206:209], v[26:29]
	v_mfma_f32_16x16x32_bf16 v[18:21], v[182:185], v[206:209], v[18:21]
	v_mfma_f32_16x16x32_bf16 v[10:13], v[174:177], v[214:217], v[10:13]
	v_mfma_f32_16x16x32_bf16 v[2:5], v[182:185], v[214:217], v[2:5]
	s_barrier
	s_setprio 0
	s_add_i32 s71, 0, 0x18000
	s_add_i32 s72, 0, 0x1c000
	v_add_u32_e32 v106, s71, v165
	v_add_u32_e32 v182, s72, v165
	ds_read_b128 v[86:89], v106
	ds_read_b128 v[90:93], v106 offset:1024
	ds_read_b128 v[98:101], v106 offset:2048
	ds_read_b128 v[106:109], v106 offset:3072
	ds_read_b128 v[170:173], v182
	ds_read_b128 v[174:177], v182 offset:1024
	ds_read_b128 v[178:181], v182 offset:2048
	ds_read_b128 v[182:185], v182 offset:3072
	s_add_u32 s64, s64, 0x80000
	s_addc_u32 s65, s65, 0
	s_mov_b32 m0, s33
	v_lshl_add_u64 v[224:225], s[64:65], 0, v[152:153]
	ds_read_b128 v[186:189], v168 offset:32768
	ds_read_b128 v[190:193], v168 offset:33792
	ds_read_b128 v[194:197], v168 offset:34816
	ds_read_b128 v[198:201], v168 offset:35840
	ds_read_b128 v[202:205], v168 offset:36864
	ds_read_b128 v[206:209], v168 offset:37888
	ds_read_b128 v[210:213], v168 offset:38912
	ds_read_b128 v[214:217], v168 offset:39936
	global_load_lds_dwordx4 v[224:225], off
	v_lshl_add_u64 v[224:225], s[64:65], 0, v[148:149]
	s_mov_b32 m0, s34
	s_nop 0
	global_load_lds_dwordx4 v[224:225], off
	s_waitcnt vmcnt(8)
	s_waitcnt lgkmcnt(0)
	s_setprio 1
	s_barrier
	v_mfma_f32_16x16x32_bf16 v[142:145], v[86:89], v[186:189], v[142:145]
	v_mfma_f32_16x16x32_bf16 v[134:137], v[98:101], v[186:189], v[134:137]
	v_mfma_f32_16x16x32_bf16 v[126:129], v[86:89], v[194:197], v[126:129]
	v_mfma_f32_16x16x32_bf16 v[118:121], v[98:101], v[194:197], v[118:121]
	v_mfma_f32_16x16x32_bf16 v[110:113], v[86:89], v[202:205], v[110:113]
	v_mfma_f32_16x16x32_bf16 v[94:97], v[98:101], v[202:205], v[94:97]
	v_mfma_f32_16x16x32_bf16 v[78:81], v[86:89], v[210:213], v[78:81]
	v_mfma_f32_16x16x32_bf16 v[70:73], v[98:101], v[210:213], v[70:73]
	s_setprio 0
	s_setprio 1
	v_mfma_f32_16x16x32_bf16 v[142:145], v[90:93], v[190:193], v[142:145]
	v_mfma_f32_16x16x32_bf16 v[134:137], v[106:109], v[190:193], v[134:137]
	v_mfma_f32_16x16x32_bf16 v[126:129], v[90:93], v[198:201], v[126:129]
	v_mfma_f32_16x16x32_bf16 v[118:121], v[106:109], v[198:201], v[118:121]
	v_mfma_f32_16x16x32_bf16 v[110:113], v[90:93], v[206:209], v[110:113]
	v_mfma_f32_16x16x32_bf16 v[94:97], v[106:109], v[206:209], v[94:97]
	v_mfma_f32_16x16x32_bf16 v[78:81], v[90:93], v[214:217], v[78:81]
	v_mfma_f32_16x16x32_bf16 v[70:73], v[106:109], v[214:217], v[70:73]
	s_setprio 0
	s_setprio 1
	v_mfma_f32_16x16x32_bf16 v[138:141], v[170:173], v[186:189], v[138:141]
	v_mfma_f32_16x16x32_bf16 v[130:133], v[178:181], v[186:189], v[130:133]
	v_mfma_f32_16x16x32_bf16 v[122:125], v[170:173], v[194:197], v[122:125]
	v_mfma_f32_16x16x32_bf16 v[114:117], v[178:181], v[194:197], v[114:117]
	v_mfma_f32_16x16x32_bf16 v[102:105], v[170:173], v[202:205], v[102:105]
	v_mfma_f32_16x16x32_bf16 v[82:85], v[178:181], v[202:205], v[82:85]
	v_mfma_f32_16x16x32_bf16 v[74:77], v[170:173], v[210:213], v[74:77]
	v_mfma_f32_16x16x32_bf16 v[66:69], v[178:181], v[210:213], v[66:69]
	s_setprio 0
	s_setprio 1
	v_mfma_f32_16x16x32_bf16 v[138:141], v[174:177], v[190:193], v[138:141]
	v_mfma_f32_16x16x32_bf16 v[130:133], v[182:185], v[190:193], v[130:133]
	v_mfma_f32_16x16x32_bf16 v[122:125], v[174:177], v[198:201], v[122:125]
	v_mfma_f32_16x16x32_bf16 v[114:117], v[182:185], v[198:201], v[114:117]
	v_mfma_f32_16x16x32_bf16 v[102:105], v[174:177], v[206:209], v[102:105]
	v_mfma_f32_16x16x32_bf16 v[82:85], v[182:185], v[206:209], v[82:85]
	v_mfma_f32_16x16x32_bf16 v[74:77], v[174:177], v[214:217], v[74:77]
	v_mfma_f32_16x16x32_bf16 v[66:69], v[182:185], v[214:217], v[66:69]
	s_barrier
	s_setprio 0
	s_add_i32 s64, s71, s11
	v_lshl_add_u64 v[162:163], v[162:163], 0, s[22:23]
	s_mov_b32 m0, s64
	ds_read_b128 v[186:189], v168 offset:49152
	ds_read_b128 v[190:193], v168 offset:50176
	ds_read_b128 v[194:197], v168 offset:51200
	ds_read_b128 v[198:201], v168 offset:52224
	ds_read_b128 v[202:205], v168 offset:53248
	ds_read_b128 v[206:209], v168 offset:54272
	ds_read_b128 v[210:213], v168 offset:55296
	ds_read_b128 v[214:217], v168 offset:56320
	global_load_lds_dwordx4 v[162:163], off
	s_add_i32 m0, s64, 0x2000
	s_add_u32 s62, s62, 0x80080
	v_lshl_add_u64 v[162:163], v[218:219], 0, s[22:23]
	s_addc_u32 s63, s63, 0
	s_add_i32 s64, s72, s11
	global_load_lds_dwordx4 v[162:163], off
	v_lshl_add_u64 v[162:163], s[62:63], 0, v[150:151]
	s_mov_b32 m0, s64
	s_nop 0
	global_load_lds_dwordx4 v[162:163], off
	v_lshl_add_u64 v[162:163], s[62:63], 0, v[146:147]
	s_add_i32 m0, s64, 0x2000
	s_nop 0
	global_load_lds_dwordx4 v[162:163], off
	v_lshl_add_u64 v[162:163], v[220:221], 0, s[22:23]
	s_mov_b32 m0, s39
	s_nop 0
	global_load_lds_dwordx4 v[162:163], off
	v_lshl_add_u64 v[162:163], v[222:223], 0, s[22:23]
	s_mov_b32 m0, s46
	s_nop 0
	global_load_lds_dwordx4 v[162:163], off
	s_waitcnt vmcnt(8)
	s_waitcnt lgkmcnt(0)
	s_setprio 1
	s_barrier
	v_mfma_f32_16x16x32_bf16 v[62:65], v[86:89], v[186:189], v[62:65]
	v_mfma_f32_16x16x32_bf16 v[54:57], v[98:101], v[186:189], v[54:57]
	v_mfma_f32_16x16x32_bf16 v[46:49], v[86:89], v[194:197], v[46:49]
	v_mfma_f32_16x16x32_bf16 v[38:41], v[98:101], v[194:197], v[38:41]
	v_mfma_f32_16x16x32_bf16 v[30:33], v[86:89], v[202:205], v[30:33]
	v_mfma_f32_16x16x32_bf16 v[22:25], v[98:101], v[202:205], v[22:25]
	v_mfma_f32_16x16x32_bf16 v[14:17], v[86:89], v[210:213], v[14:17]
	v_mfma_f32_16x16x32_bf16 v[6:9], v[98:101], v[210:213], v[6:9]
	s_setprio 0
	s_setprio 1
	v_mfma_f32_16x16x32_bf16 v[62:65], v[90:93], v[190:193], v[62:65]
	v_mfma_f32_16x16x32_bf16 v[54:57], v[106:109], v[190:193], v[54:57]
	v_mfma_f32_16x16x32_bf16 v[46:49], v[90:93], v[198:201], v[46:49]
	v_mfma_f32_16x16x32_bf16 v[38:41], v[106:109], v[198:201], v[38:41]
	v_mfma_f32_16x16x32_bf16 v[30:33], v[90:93], v[206:209], v[30:33]
	v_mfma_f32_16x16x32_bf16 v[22:25], v[106:109], v[206:209], v[22:25]
	v_mfma_f32_16x16x32_bf16 v[14:17], v[90:93], v[214:217], v[14:17]
	v_mfma_f32_16x16x32_bf16 v[6:9], v[106:109], v[214:217], v[6:9]
	s_setprio 0
	s_setprio 1
	v_mfma_f32_16x16x32_bf16 v[58:61], v[170:173], v[186:189], v[58:61]
	v_mfma_f32_16x16x32_bf16 v[50:53], v[178:181], v[186:189], v[50:53]
	v_mfma_f32_16x16x32_bf16 v[42:45], v[170:173], v[194:197], v[42:45]
	v_mfma_f32_16x16x32_bf16 v[34:37], v[178:181], v[194:197], v[34:37]
	v_mfma_f32_16x16x32_bf16 v[26:29], v[170:173], v[202:205], v[26:29]
	v_mfma_f32_16x16x32_bf16 v[18:21], v[178:181], v[202:205], v[18:21]
	v_mfma_f32_16x16x32_bf16 v[10:13], v[170:173], v[210:213], v[10:13]
	v_mfma_f32_16x16x32_bf16 v[2:5], v[178:181], v[210:213], v[2:5]
	s_setprio 0
	s_setprio 1
	v_mfma_f32_16x16x32_bf16 v[58:61], v[174:177], v[190:193], v[58:61]
	v_mfma_f32_16x16x32_bf16 v[50:53], v[182:185], v[190:193], v[50:53]
	v_mfma_f32_16x16x32_bf16 v[42:45], v[174:177], v[198:201], v[42:45]
	v_mfma_f32_16x16x32_bf16 v[34:37], v[182:185], v[198:201], v[34:37]
	v_mfma_f32_16x16x32_bf16 v[26:29], v[174:177], v[206:209], v[26:29]
	v_mfma_f32_16x16x32_bf16 v[18:21], v[182:185], v[206:209], v[18:21]
	v_mfma_f32_16x16x32_bf16 v[10:13], v[174:177], v[214:217], v[10:13]
	v_mfma_f32_16x16x32_bf16 v[2:5], v[182:185], v[214:217], v[2:5]
	s_barrier
	s_setprio 0
	s_add_i32 s70, s70, 2
	s_add_u32 s68, s68, 0x100
	s_addc_u32 s69, s69, 0
	s_add_u32 s60, s60, 0x100
	s_addc_u32 s61, s61, 0
	s_cmp_gt_u32 s70, 29
	s_cbranch_scc0 .LBB0_1130
	s_and_b64 vcc, exec, s[24:25]
	s_cbranch_vccz .LBB0_1133
	s_barrier

.LBB0_1201:
	s_add_u32 s62, s58, s60
	s_addc_u32 s63, s59, s61
	s_add_u32 s62, s62, 0x100
	s_addc_u32 s63, s63, 0
	s_add_u32 s71, s68, s60
	s_addc_u32 s72, s69, s61
	s_cmpk_eq_i32 s60, 0xf00
	s_cselect_b32 s65, s50, s63
	s_cselect_b32 s64, s51, s62
	s_cselect_b32 s63, s66, s72
	s_cselect_b32 s62, s67, s71
	s_add_i32 s71, 0, 0x10000
	v_add_u32_e32 v3, s71, v171
	ds_read_b128 v[134:137], v3
	ds_read_b128 v[138:141], v3 offset:1024
	ds_read_b128 v[142:145], v3 offset:2048
	ds_read_b128 v[146:149], v3 offset:3072
	v_add_u32_e32 v3, s49, v171
	ds_read_b128 v[174:177], v3
	ds_read_b128 v[178:181], v3 offset:1024
	ds_read_b128 v[182:185], v3 offset:2048
	ds_read_b128 v[186:189], v3 offset:3072
	v_lshl_add_u64 v[4:5], v[168:169], 0, s[60:61]
	s_add_i32 m0, s14, 0xc000
	ds_read_b128 v[190:193], v172
	ds_read_b128 v[194:197], v172 offset:1024
	ds_read_b128 v[198:201], v172 offset:2048
	ds_read_b128 v[202:205], v172 offset:3072
	ds_read_b128 v[206:209], v172 offset:4096
	ds_read_b128 v[210:213], v172 offset:5120
	ds_read_b128 v[214:217], v172 offset:6144
	ds_read_b128 v[218:221], v172 offset:7168
	global_load_lds_dwordx4 v[4:5], off
	v_lshl_add_u64 v[4:5], v[166:167], 0, s[60:61]
	s_add_i32 m0, s14, 0xe000
	s_nop 0
	global_load_lds_dwordx4 v[4:5], off
	s_waitcnt vmcnt(8)
	s_waitcnt lgkmcnt(0)
	s_setprio 1
	s_barrier
	v_mfma_f32_16x16x32_bf16 v[130:133], v[134:137], v[190:193], v[130:133]
	v_mfma_f32_16x16x32_bf16 v[126:129], v[142:145], v[190:193], v[126:129]
	v_mfma_f32_16x16x32_bf16 v[122:125], v[134:137], v[198:201], v[122:125]
	v_mfma_f32_16x16x32_bf16 v[114:117], v[142:145], v[198:201], v[114:117]
	v_mfma_f32_16x16x32_bf16 v[98:101], v[134:137], v[206:209], v[98:101]
	v_mfma_f32_16x16x32_bf16 v[94:97], v[142:145], v[206:209], v[94:97]
	v_mfma_f32_16x16x32_bf16 v[82:85], v[134:137], v[214:217], v[82:85]
	v_mfma_f32_16x16x32_bf16 v[78:81], v[142:145], v[214:217], v[78:81]
	s_setprio 0
	s_setprio 1
	v_mfma_f32_16x16x32_bf16 v[130:133], v[138:141], v[194:197], v[130:133]
	v_mfma_f32_16x16x32_bf16 v[126:129], v[146:149], v[194:197], v[126:129]
	v_mfma_f32_16x16x32_bf16 v[122:125], v[138:141], v[202:205], v[122:125]
	v_mfma_f32_16x16x32_bf16 v[114:117], v[146:149], v[202:205], v[114:117]
	v_mfma_f32_16x16x32_bf16 v[98:101], v[138:141], v[210:213], v[98:101]
	v_mfma_f32_16x16x32_bf16 v[94:97], v[146:149], v[210:213], v[94:97]
	v_mfma_f32_16x16x32_bf16 v[82:85], v[138:141], v[218:221], v[82:85]
	v_mfma_f32_16x16x32_bf16 v[78:81], v[146:149], v[218:221], v[78:81]
	s_setprio 0
	s_setprio 1
	v_mfma_f32_16x16x32_bf16 v[118:121], v[174:177], v[190:193], v[118:121]
	v_mfma_f32_16x16x32_bf16 v[110:113], v[182:185], v[190:193], v[110:113]
	v_mfma_f32_16x16x32_bf16 v[106:109], v[174:177], v[198:201], v[106:109]
	v_mfma_f32_16x16x32_bf16 v[102:105], v[182:185], v[198:201], v[102:105]
	v_mfma_f32_16x16x32_bf16 v[90:93], v[174:177], v[206:209], v[90:93]
	v_mfma_f32_16x16x32_bf16 v[86:89], v[182:185], v[206:209], v[86:89]
	v_mfma_f32_16x16x32_bf16 v[74:77], v[174:177], v[214:217], v[74:77]
	v_mfma_f32_16x16x32_bf16 v[70:73], v[182:185], v[214:217], v[70:73]
	s_setprio 0
	s_setprio 1
	v_mfma_f32_16x16x32_bf16 v[118:121], v[178:181], v[194:197], v[118:121]
	v_mfma_f32_16x16x32_bf16 v[110:113], v[186:189], v[194:197], v[110:113]
	v_mfma_f32_16x16x32_bf16 v[106:109], v[178:181], v[202:205], v[106:109]
	v_mfma_f32_16x16x32_bf16 v[102:105], v[186:189], v[202:205], v[102:105]
	v_mfma_f32_16x16x32_bf16 v[90:93], v[178:181], v[210:213], v[90:93]
	v_mfma_f32_16x16x32_bf16 v[86:89], v[186:189], v[210:213], v[86:89]
	v_mfma_f32_16x16x32_bf16 v[74:77], v[178:181], v[218:221], v[74:77]
	v_mfma_f32_16x16x32_bf16 v[70:73], v[186:189], v[218:221], v[70:73]
	s_barrier
	s_setprio 0
	s_add_i32 s71, s71, s11
	v_lshl_add_u64 v[222:223], s[62:63], 0, v[154:155]
	s_mov_b32 m0, s71
	ds_read_b128 v[190:193], v172 offset:16384
	ds_read_b128 v[194:197], v172 offset:17408
	ds_read_b128 v[198:201], v172 offset:18432
	ds_read_b128 v[202:205], v172 offset:19456
	ds_read_b128 v[206:209], v172 offset:20480
	ds_read_b128 v[210:213], v172 offset:21504
	ds_read_b128 v[214:217], v172 offset:22528
	ds_read_b128 v[218:221], v172 offset:23552
	global_load_lds_dwordx4 v[222:223], off
	s_add_i32 m0, s71, 0x2000
	s_add_u32 s72, s62, 0x80000
	v_lshl_add_u64 v[224:225], s[62:63], 0, v[150:151]
	s_addc_u32 s73, s63, 0
	s_add_i32 s71, s49, s11
	global_load_lds_dwordx4 v[224:225], off
	v_lshl_add_u64 v[4:5], s[72:73], 0, v[154:155]
	s_mov_b32 m0, s71
	v_lshl_add_u64 v[226:227], s[64:65], 0, v[156:157]
	global_load_lds_dwordx4 v[4:5], off
	v_lshl_add_u64 v[4:5], s[72:73], 0, v[150:151]
	s_add_i32 m0, s71, 0x2000
	v_lshl_add_u64 v[228:229], s[64:65], 0, v[152:153]
	global_load_lds_dwordx4 v[4:5], off
	s_mov_b32 m0, s14
	s_nop 0
	global_load_lds_dwordx4 v[226:227], off
	s_mov_b32 m0, s15
	s_nop 0
	global_load_lds_dwordx4 v[228:229], off
	s_waitcnt vmcnt(8)
	s_waitcnt lgkmcnt(0)
	s_setprio 1
	s_barrier
	v_mfma_f32_16x16x32_bf16 v[66:69], v[134:137], v[190:193], v[66:69]
	v_mfma_f32_16x16x32_bf16 v[62:65], v[142:145], v[190:193], v[62:65]
	v_mfma_f32_16x16x32_bf16 v[50:53], v[134:137], v[198:201], v[50:53]
	v_mfma_f32_16x16x32_bf16 v[46:49], v[142:145], v[198:201], v[46:49]
	v_mfma_f32_16x16x32_bf16 v[34:37], v[134:137], v[206:209], v[34:37]
	v_mfma_f32_16x16x32_bf16 v[30:33], v[142:145], v[206:209], v[30:33]
	v_mfma_f32_16x16x32_bf16 v[18:21], v[134:137], v[214:217], v[18:21]
	v_mfma_f32_16x16x32_bf16 v[14:17], v[142:145], v[214:217], v[14:17]
	s_setprio 0
	s_setprio 1
	v_mfma_f32_16x16x32_bf16 v[66:69], v[138:141], v[194:197], v[66:69]
	v_mfma_f32_16x16x32_bf16 v[62:65], v[146:149], v[194:197], v[62:65]
	v_mfma_f32_16x16x32_bf16 v[50:53], v[138:141], v[202:205], v[50:53]
	v_mfma_f32_16x16x32_bf16 v[46:49], v[146:149], v[202:205], v[46:49]
	v_mfma_f32_16x16x32_bf16 v[34:37], v[138:141], v[210:213], v[34:37]
	v_mfma_f32_16x16x32_bf16 v[30:33], v[146:149], v[210:213], v[30:33]
	v_mfma_f32_16x16x32_bf16 v[18:21], v[138:141], v[218:221], v[18:21]
	v_mfma_f32_16x16x32_bf16 v[14:17], v[146:149], v[218:221], v[14:17]
	s_setprio 0
	s_setprio 1
	v_mfma_f32_16x16x32_bf16 v[58:61], v[174:177], v[190:193], v[58:61]
	v_mfma_f32_16x16x32_bf16 v[54:57], v[182:185], v[190:193], v[54:57]
	v_mfma_f32_16x16x32_bf16 v[42:45], v[174:177], v[198:201], v[42:45]
	v_mfma_f32_16x16x32_bf16 v[38:41], v[182:185], v[198:201], v[38:41]
	v_mfma_f32_16x16x32_bf16 v[26:29], v[174:177], v[206:209], v[26:29]
	v_mfma_f32_16x16x32_bf16 v[22:25], v[182:185], v[206:209], v[22:25]
	v_mfma_f32_16x16x32_bf16 v[10:13], v[174:177], v[214:217], v[10:13]
	v_mfma_f32_16x16x32_bf16 v[4:7], v[182:185], v[214:217], v[6:9]
	s_setprio 0
	s_setprio 1
	v_mfma_f32_16x16x32_bf16 v[58:61], v[178:181], v[194:197], v[58:61]
	v_mfma_f32_16x16x32_bf16 v[54:57], v[186:189], v[194:197], v[54:57]
	v_mfma_f32_16x16x32_bf16 v[42:45], v[178:181], v[202:205], v[42:45]
	v_mfma_f32_16x16x32_bf16 v[38:41], v[186:189], v[202:205], v[38:41]
	v_mfma_f32_16x16x32_bf16 v[26:29], v[178:181], v[210:213], v[26:29]
	v_mfma_f32_16x16x32_bf16 v[22:25], v[186:189], v[210:213], v[22:25]
	v_mfma_f32_16x16x32_bf16 v[10:13], v[178:181], v[218:221], v[10:13]
	v_mfma_f32_16x16x32_bf16 v[4:7], v[186:189], v[218:221], v[4:7]
	s_barrier
	s_setprio 0
	s_add_i32 s71, 0, 0x18000
	v_add_u32_e32 v3, s71, v171
	s_add_i32 s72, 0, 0x1c000
	ds_read_b128 v[134:137], v3
	ds_read_b128 v[138:141], v3 offset:1024
	ds_read_b128 v[142:145], v3 offset:2048
	ds_read_b128 v[146:149], v3 offset:3072
	v_add_u32_e32 v3, s72, v171
	ds_read_b128 v[174:177], v3
	ds_read_b128 v[178:181], v3 offset:1024
	ds_read_b128 v[182:185], v3 offset:2048
	ds_read_b128 v[186:189], v3 offset:3072
	s_add_u32 s64, s64, 0x80000
	s_addc_u32 s65, s65, 0
	s_mov_b32 m0, s33
	v_lshl_add_u64 v[8:9], s[64:65], 0, v[156:157]
	ds_read_b128 v[190:193], v172 offset:32768
	ds_read_b128 v[194:197], v172 offset:33792
	ds_read_b128 v[198:201], v172 offset:34816
	ds_read_b128 v[202:205], v172 offset:35840
	ds_read_b128 v[206:209], v172 offset:36864
	ds_read_b128 v[210:213], v172 offset:37888
	ds_read_b128 v[214:217], v172 offset:38912
	ds_read_b128 v[218:221], v172 offset:39936
	global_load_lds_dwordx4 v[8:9], off
	v_lshl_add_u64 v[8:9], s[64:65], 0, v[152:153]
	s_mov_b32 m0, s34
	s_nop 0
	global_load_lds_dwordx4 v[8:9], off
	s_waitcnt vmcnt(8)
	s_waitcnt lgkmcnt(0)
	s_setprio 1
	s_barrier
	v_mfma_f32_16x16x32_bf16 v[130:133], v[134:137], v[190:193], v[130:133]
	v_mfma_f32_16x16x32_bf16 v[126:129], v[142:145], v[190:193], v[126:129]
	v_mfma_f32_16x16x32_bf16 v[122:125], v[134:137], v[198:201], v[122:125]
	v_mfma_f32_16x16x32_bf16 v[114:117], v[142:145], v[198:201], v[114:117]
	v_mfma_f32_16x16x32_bf16 v[98:101], v[134:137], v[206:209], v[98:101]
	v_mfma_f32_16x16x32_bf16 v[94:97], v[142:145], v[206:209], v[94:97]
	v_mfma_f32_16x16x32_bf16 v[82:85], v[134:137], v[214:217], v[82:85]
	v_mfma_f32_16x16x32_bf16 v[78:81], v[142:145], v[214:217], v[78:81]
	s_setprio 0
	s_setprio 1
	v_mfma_f32_16x16x32_bf16 v[130:133], v[138:141], v[194:197], v[130:133]
	v_mfma_f32_16x16x32_bf16 v[126:129], v[146:149], v[194:197], v[126:129]
	v_mfma_f32_16x16x32_bf16 v[122:125], v[138:141], v[202:205], v[122:125]
	v_mfma_f32_16x16x32_bf16 v[114:117], v[146:149], v[202:205], v[114:117]
	v_mfma_f32_16x16x32_bf16 v[98:101], v[138:141], v[210:213], v[98:101]
	v_mfma_f32_16x16x32_bf16 v[94:97], v[146:149], v[210:213], v[94:97]
	v_mfma_f32_16x16x32_bf16 v[82:85], v[138:141], v[218:221], v[82:85]
	v_mfma_f32_16x16x32_bf16 v[78:81], v[146:149], v[218:221], v[78:81]
	s_setprio 0
	s_setprio 1
	v_mfma_f32_16x16x32_bf16 v[118:121], v[174:177], v[190:193], v[118:121]
	v_mfma_f32_16x16x32_bf16 v[110:113], v[182:185], v[190:193], v[110:113]
	v_mfma_f32_16x16x32_bf16 v[106:109], v[174:177], v[198:201], v[106:109]
	v_mfma_f32_16x16x32_bf16 v[102:105], v[182:185], v[198:201], v[102:105]
	v_mfma_f32_16x16x32_bf16 v[90:93], v[174:177], v[206:209], v[90:93]
	v_mfma_f32_16x16x32_bf16 v[86:89], v[182:185], v[206:209], v[86:89]
	v_mfma_f32_16x16x32_bf16 v[74:77], v[174:177], v[214:217], v[74:77]
	v_mfma_f32_16x16x32_bf16 v[70:73], v[182:185], v[214:217], v[70:73]
	s_setprio 0
	s_setprio 1
	v_mfma_f32_16x16x32_bf16 v[118:121], v[178:181], v[194:197], v[118:121]
	v_mfma_f32_16x16x32_bf16 v[110:113], v[186:189], v[194:197], v[110:113]
	v_mfma_f32_16x16x32_bf16 v[106:109], v[178:181], v[202:205], v[106:109]
	v_mfma_f32_16x16x32_bf16 v[102:105], v[186:189], v[202:205], v[102:105]
	v_mfma_f32_16x16x32_bf16 v[90:93], v[178:181], v[210:213], v[90:93]
	v_mfma_f32_16x16x32_bf16 v[86:89], v[186:189], v[210:213], v[86:89]
	v_mfma_f32_16x16x32_bf16 v[74:77], v[178:181], v[218:221], v[74:77]
	v_mfma_f32_16x16x32_bf16 v[70:73], v[186:189], v[218:221], v[70:73]
	s_barrier
	s_setprio 0
	s_add_i32 s64, s71, s11
	v_lshl_add_u64 v[8:9], v[222:223], 0, s[22:23]
	s_mov_b32 m0, s64
	ds_read_b128 v[190:193], v172 offset:49152
	ds_read_b128 v[194:197], v172 offset:50176
	ds_read_b128 v[198:201], v172 offset:51200
	ds_read_b128 v[202:205], v172 offset:52224
	ds_read_b128 v[206:209], v172 offset:53248
	ds_read_b128 v[210:213], v172 offset:54272
	ds_read_b128 v[214:217], v172 offset:55296
	ds_read_b128 v[218:221], v172 offset:56320
	global_load_lds_dwordx4 v[8:9], off
	s_add_i32 m0, s64, 0x2000
	s_add_u32 s62, s62, 0x80080
	v_lshl_add_u64 v[8:9], v[224:225], 0, s[22:23]
	s_addc_u32 s63, s63, 0
	s_add_i32 s64, s72, s11
	global_load_lds_dwordx4 v[8:9], off
	v_lshl_add_u64 v[8:9], s[62:63], 0, v[154:155]
	s_mov_b32 m0, s64
	s_nop 0
	global_load_lds_dwordx4 v[8:9], off
	v_lshl_add_u64 v[8:9], s[62:63], 0, v[150:151]
	s_add_i32 m0, s64, 0x2000
	s_nop 0
	global_load_lds_dwordx4 v[8:9], off
	v_lshl_add_u64 v[8:9], v[226:227], 0, s[22:23]
	s_mov_b32 m0, s39
	s_nop 0
	global_load_lds_dwordx4 v[8:9], off
	v_lshl_add_u64 v[8:9], v[228:229], 0, s[22:23]
	s_mov_b32 m0, s46
	s_nop 0
	global_load_lds_dwordx4 v[8:9], off
	s_waitcnt vmcnt(8)
	s_waitcnt lgkmcnt(0)
	s_setprio 1
	s_barrier
	v_mfma_f32_16x16x32_bf16 v[66:69], v[134:137], v[190:193], v[66:69]
	v_mfma_f32_16x16x32_bf16 v[62:65], v[142:145], v[190:193], v[62:65]
	v_mfma_f32_16x16x32_bf16 v[50:53], v[134:137], v[198:201], v[50:53]
	v_mfma_f32_16x16x32_bf16 v[46:49], v[142:145], v[198:201], v[46:49]
	v_mfma_f32_16x16x32_bf16 v[34:37], v[134:137], v[206:209], v[34:37]
	v_mfma_f32_16x16x32_bf16 v[30:33], v[142:145], v[206:209], v[30:33]
	v_mfma_f32_16x16x32_bf16 v[18:21], v[134:137], v[214:217], v[18:21]
	v_mfma_f32_16x16x32_bf16 v[14:17], v[142:145], v[214:217], v[14:17]
	s_setprio 0
	s_setprio 1
	v_mfma_f32_16x16x32_bf16 v[66:69], v[138:141], v[194:197], v[66:69]
	v_mfma_f32_16x16x32_bf16 v[62:65], v[146:149], v[194:197], v[62:65]
	v_mfma_f32_16x16x32_bf16 v[50:53], v[138:141], v[202:205], v[50:53]
	v_mfma_f32_16x16x32_bf16 v[46:49], v[146:149], v[202:205], v[46:49]
	v_mfma_f32_16x16x32_bf16 v[34:37], v[138:141], v[210:213], v[34:37]
	v_mfma_f32_16x16x32_bf16 v[30:33], v[146:149], v[210:213], v[30:33]
	v_mfma_f32_16x16x32_bf16 v[18:21], v[138:141], v[218:221], v[18:21]
	v_mfma_f32_16x16x32_bf16 v[14:17], v[146:149], v[218:221], v[14:17]
	s_setprio 0
	s_setprio 1
	v_mfma_f32_16x16x32_bf16 v[58:61], v[174:177], v[190:193], v[58:61]
	v_mfma_f32_16x16x32_bf16 v[54:57], v[182:185], v[190:193], v[54:57]
	v_mfma_f32_16x16x32_bf16 v[42:45], v[174:177], v[198:201], v[42:45]
	v_mfma_f32_16x16x32_bf16 v[38:41], v[182:185], v[198:201], v[38:41]
	v_mfma_f32_16x16x32_bf16 v[26:29], v[174:177], v[206:209], v[26:29]
	v_mfma_f32_16x16x32_bf16 v[22:25], v[182:185], v[206:209], v[22:25]
	v_mfma_f32_16x16x32_bf16 v[8:11], v[174:177], v[214:217], v[10:13]
	v_mfma_f32_16x16x32_bf16 v[4:7], v[182:185], v[214:217], v[4:7]
	s_setprio 0
	s_setprio 1
	v_mfma_f32_16x16x32_bf16 v[58:61], v[178:181], v[194:197], v[58:61]
	v_mfma_f32_16x16x32_bf16 v[54:57], v[186:189], v[194:197], v[54:57]
	v_mfma_f32_16x16x32_bf16 v[42:45], v[178:181], v[202:205], v[42:45]
	v_mfma_f32_16x16x32_bf16 v[38:41], v[186:189], v[202:205], v[38:41]
	v_mfma_f32_16x16x32_bf16 v[26:29], v[178:181], v[210:213], v[26:29]
	v_mfma_f32_16x16x32_bf16 v[22:25], v[186:189], v[210:213], v[22:25]
	v_mfma_f32_16x16x32_bf16 v[10:13], v[178:181], v[218:221], v[8:11]
	v_mfma_f32_16x16x32_bf16 v[6:9], v[186:189], v[218:221], v[4:7]
	s_barrier
	s_setprio 0
	s_add_i32 s70, s70, 2
	s_add_u32 s60, s60, 0x100
	s_addc_u32 s61, s61, 0
	s_cmp_gt_u32 s70, 29
	s_cbranch_scc1 .LBB0_1204

.LBB0_1364:
	ds_read_b128 v[86:89], v220
	ds_read_b128 v[90:93], v220 offset:1024
	ds_read_b128 v[114:117], v220 offset:2048
	ds_read_b128 v[118:121], v220 offset:3072
	ds_read_b128 v[146:149], v221
	ds_read_b128 v[150:153], v221 offset:1024
	ds_read_b128 v[154:157], v221 offset:2048
	ds_read_b128 v[158:161], v221 offset:3072
	s_add_u32 s10, s8, 0xfff80080
	s_addc_u32 s11, s9, -1
	s_cmp_eq_u32 s63, 28
	s_cselect_b32 s13, s7, s11
	s_cselect_b32 s12, s14, s10
	s_cselect_b32 s11, s15, s41
	s_cselect_b32 s10, s18, s39
	v_lshl_add_u64 v[208:209], s[8:9], 0, v[180:181]
	s_add_i32 m0, s47, 0xc000
	ds_read_b128 v[162:165], v222
	ds_read_b128 v[166:169], v222 offset:1024
	ds_read_b128 v[184:187], v222 offset:2048
	ds_read_b128 v[188:191], v222 offset:3072
	ds_read_b128 v[192:195], v222 offset:4096
	ds_read_b128 v[196:199], v222 offset:5120
	ds_read_b128 v[200:203], v222 offset:6144
	ds_read_b128 v[204:207], v222 offset:7168
	global_load_lds_dwordx4 v[208:209], off
	v_lshl_add_u64 v[208:209], s[8:9], 0, v[178:179]
	s_add_i32 m0, s47, 0xe000
	s_nop 0
	global_load_lds_dwordx4 v[208:209], off
	s_waitcnt vmcnt(8)
	s_waitcnt lgkmcnt(0)
	s_setprio 1
	s_barrier
	v_mfma_f32_16x16x32_bf16 v[142:145], v[86:89], v[162:165], v[142:145]
	v_mfma_f32_16x16x32_bf16 v[138:141], v[114:117], v[162:165], v[138:141]
	v_mfma_f32_16x16x32_bf16 v[126:129], v[86:89], v[184:187], v[126:129]
	v_mfma_f32_16x16x32_bf16 v[122:125], v[114:117], v[184:187], v[122:125]
	v_mfma_f32_16x16x32_bf16 v[102:105], v[86:89], v[192:195], v[102:105]
	v_mfma_f32_16x16x32_bf16 v[98:101], v[114:117], v[192:195], v[98:101]
	v_mfma_f32_16x16x32_bf16 v[78:81], v[86:89], v[200:203], v[78:81]
	v_mfma_f32_16x16x32_bf16 v[74:77], v[114:117], v[200:203], v[74:77]
	s_setprio 0
	s_setprio 1
	v_mfma_f32_16x16x32_bf16 v[142:145], v[90:93], v[166:169], v[142:145]
	v_mfma_f32_16x16x32_bf16 v[138:141], v[118:121], v[166:169], v[138:141]
	v_mfma_f32_16x16x32_bf16 v[126:129], v[90:93], v[188:191], v[126:129]
	v_mfma_f32_16x16x32_bf16 v[122:125], v[118:121], v[188:191], v[122:125]
	v_mfma_f32_16x16x32_bf16 v[102:105], v[90:93], v[196:199], v[102:105]
	v_mfma_f32_16x16x32_bf16 v[98:101], v[118:121], v[196:199], v[98:101]
	v_mfma_f32_16x16x32_bf16 v[78:81], v[90:93], v[204:207], v[78:81]
	v_mfma_f32_16x16x32_bf16 v[74:77], v[118:121], v[204:207], v[74:77]
	s_setprio 0
	s_setprio 1
	v_mfma_f32_16x16x32_bf16 v[134:137], v[146:149], v[162:165], v[134:137]
	v_mfma_f32_16x16x32_bf16 v[130:133], v[154:157], v[162:165], v[130:133]
	v_mfma_f32_16x16x32_bf16 v[110:113], v[146:149], v[184:187], v[110:113]
	v_mfma_f32_16x16x32_bf16 v[106:109], v[154:157], v[184:187], v[106:109]
	v_mfma_f32_16x16x32_bf16 v[94:97], v[146:149], v[192:195], v[94:97]
	v_mfma_f32_16x16x32_bf16 v[82:85], v[154:157], v[192:195], v[82:85]
	v_mfma_f32_16x16x32_bf16 v[70:73], v[146:149], v[200:203], v[70:73]
	v_mfma_f32_16x16x32_bf16 v[66:69], v[154:157], v[200:203], v[66:69]
	s_setprio 0
	s_setprio 1
	v_mfma_f32_16x16x32_bf16 v[134:137], v[150:153], v[166:169], v[134:137]
	v_mfma_f32_16x16x32_bf16 v[130:133], v[158:161], v[166:169], v[130:133]
	v_mfma_f32_16x16x32_bf16 v[110:113], v[150:153], v[188:191], v[110:113]
	v_mfma_f32_16x16x32_bf16 v[106:109], v[158:161], v[188:191], v[106:109]
	v_mfma_f32_16x16x32_bf16 v[94:97], v[150:153], v[196:199], v[94:97]
	v_mfma_f32_16x16x32_bf16 v[82:85], v[158:161], v[196:199], v[82:85]
	v_mfma_f32_16x16x32_bf16 v[70:73], v[150:153], v[204:207], v[70:73]
	v_mfma_f32_16x16x32_bf16 v[66:69], v[158:161], v[204:207], v[66:69]
	s_barrier
	s_setprio 0
	s_add_i32 s64, s60, s49
	v_lshl_add_u64 v[208:209], s[10:11], 0, v[172:173]
	s_mov_b32 m0, s64
	ds_read_b128 v[162:165], v222 offset:16384
	ds_read_b128 v[166:169], v222 offset:17408
	ds_read_b128 v[184:187], v222 offset:18432
	ds_read_b128 v[188:191], v222 offset:19456
	ds_read_b128 v[192:195], v222 offset:20480
	ds_read_b128 v[196:199], v222 offset:21504
	ds_read_b128 v[200:203], v222 offset:22528
	ds_read_b128 v[204:207], v222 offset:23552
	global_load_lds_dwordx4 v[208:209], off
	s_add_i32 m0, s64, 0x2000
	s_add_u32 s64, s10, 0x80000
	v_lshl_add_u64 v[210:211], s[10:11], 0, v[176:177]
	s_addc_u32 s65, s11, 0
	s_add_i32 s66, s61, s49
	global_load_lds_dwordx4 v[210:211], off
	v_lshl_add_u64 v[212:213], s[64:65], 0, v[172:173]
	s_mov_b32 m0, s66
	v_lshl_add_u64 v[214:215], s[12:13], 0, v[174:175]
	global_load_lds_dwordx4 v[212:213], off
	v_lshl_add_u64 v[212:213], s[64:65], 0, v[176:177]
	s_add_i32 m0, s66, 0x2000
	s_nop 0
	global_load_lds_dwordx4 v[212:213], off
	v_lshl_add_u64 v[212:213], s[12:13], 0, v[170:171]
	s_mov_b32 m0, s47
	s_nop 0
	global_load_lds_dwordx4 v[212:213], off
	s_mov_b32 m0, s50
	s_nop 0
	global_load_lds_dwordx4 v[214:215], off
	s_waitcnt vmcnt(8)
	s_waitcnt lgkmcnt(0)
	s_setprio 1
	s_barrier
	v_mfma_f32_16x16x32_bf16 v[62:65], v[86:89], v[162:165], v[62:65]
	v_mfma_f32_16x16x32_bf16 v[58:61], v[114:117], v[162:165], v[58:61]
	v_mfma_f32_16x16x32_bf16 v[46:49], v[86:89], v[184:187], v[46:49]
	v_mfma_f32_16x16x32_bf16 v[42:45], v[114:117], v[184:187], v[42:45]
	v_mfma_f32_16x16x32_bf16 v[30:33], v[86:89], v[192:195], v[30:33]
	v_mfma_f32_16x16x32_bf16 v[26:29], v[114:117], v[192:195], v[26:29]
	v_mfma_f32_16x16x32_bf16 v[14:17], v[86:89], v[200:203], v[14:17]
	v_mfma_f32_16x16x32_bf16 v[10:13], v[114:117], v[200:203], v[10:13]
	s_setprio 0
	s_setprio 1
	v_mfma_f32_16x16x32_bf16 v[62:65], v[90:93], v[166:169], v[62:65]
	v_mfma_f32_16x16x32_bf16 v[58:61], v[118:121], v[166:169], v[58:61]
	v_mfma_f32_16x16x32_bf16 v[46:49], v[90:93], v[188:191], v[46:49]
	v_mfma_f32_16x16x32_bf16 v[42:45], v[118:121], v[188:191], v[42:45]
	v_mfma_f32_16x16x32_bf16 v[30:33], v[90:93], v[196:199], v[30:33]
	v_mfma_f32_16x16x32_bf16 v[26:29], v[118:121], v[196:199], v[26:29]
	v_mfma_f32_16x16x32_bf16 v[14:17], v[90:93], v[204:207], v[14:17]
	v_mfma_f32_16x16x32_bf16 v[10:13], v[118:121], v[204:207], v[10:13]
	s_setprio 0
	s_setprio 1
	v_mfma_f32_16x16x32_bf16 v[54:57], v[146:149], v[162:165], v[54:57]
	v_mfma_f32_16x16x32_bf16 v[50:53], v[154:157], v[162:165], v[50:53]
	v_mfma_f32_16x16x32_bf16 v[38:41], v[146:149], v[184:187], v[38:41]
	v_mfma_f32_16x16x32_bf16 v[34:37], v[154:157], v[184:187], v[34:37]
	v_mfma_f32_16x16x32_bf16 v[22:25], v[146:149], v[192:195], v[22:25]
	v_mfma_f32_16x16x32_bf16 v[18:21], v[154:157], v[192:195], v[18:21]
	v_mfma_f32_16x16x32_bf16 v[6:9], v[146:149], v[200:203], v[6:9]
	v_mfma_f32_16x16x32_bf16 v[2:5], v[154:157], v[200:203], v[2:5]
	s_setprio 0
	s_setprio 1
	v_mfma_f32_16x16x32_bf16 v[54:57], v[150:153], v[166:169], v[54:57]
	v_mfma_f32_16x16x32_bf16 v[50:53], v[158:161], v[166:169], v[50:53]
	v_mfma_f32_16x16x32_bf16 v[38:41], v[150:153], v[188:191], v[38:41]
	v_mfma_f32_16x16x32_bf16 v[34:37], v[158:161], v[188:191], v[34:37]
	v_mfma_f32_16x16x32_bf16 v[22:25], v[150:153], v[196:199], v[22:25]
	v_mfma_f32_16x16x32_bf16 v[18:21], v[158:161], v[196:199], v[18:21]
	v_mfma_f32_16x16x32_bf16 v[6:9], v[150:153], v[204:207], v[6:9]
	v_mfma_f32_16x16x32_bf16 v[2:5], v[158:161], v[204:207], v[2:5]
	s_barrier
	s_setprio 0
	s_add_i32 s64, 0, 0x18000
	s_add_i32 s65, 0, 0x1c000
	v_add_u32_e32 v118, s64, v219
	v_add_u32_e32 v158, s65, v219
	ds_read_b128 v[86:89], v118
	ds_read_b128 v[90:93], v118 offset:1024
	ds_read_b128 v[114:117], v118 offset:2048
	ds_read_b128 v[118:121], v118 offset:3072
	ds_read_b128 v[146:149], v158
	ds_read_b128 v[150:153], v158 offset:1024
	ds_read_b128 v[154:157], v158 offset:2048
	ds_read_b128 v[158:161], v158 offset:3072
	s_add_u32 s12, s12, 0x80000
	s_addc_u32 s13, s13, 0
	s_mov_b32 m0, s51
	v_lshl_add_u64 v[216:217], s[12:13], 0, v[170:171]
	ds_read_b128 v[162:165], v222 offset:32768
	ds_read_b128 v[166:169], v222 offset:33792
	ds_read_b128 v[184:187], v222 offset:34816
	ds_read_b128 v[188:191], v222 offset:35840
	ds_read_b128 v[192:195], v222 offset:36864
	ds_read_b128 v[196:199], v222 offset:37888
	ds_read_b128 v[200:203], v222 offset:38912
	ds_read_b128 v[204:207], v222 offset:39936
	global_load_lds_dwordx4 v[216:217], off
	v_lshl_add_u64 v[216:217], s[12:13], 0, v[174:175]
	s_mov_b32 m0, s52
	s_nop 0
	global_load_lds_dwordx4 v[216:217], off
	s_waitcnt vmcnt(8)
	s_waitcnt lgkmcnt(0)
	s_setprio 1
	s_barrier
	v_mfma_f32_16x16x32_bf16 v[142:145], v[86:89], v[162:165], v[142:145]
	v_mfma_f32_16x16x32_bf16 v[138:141], v[114:117], v[162:165], v[138:141]
	v_mfma_f32_16x16x32_bf16 v[126:129], v[86:89], v[184:187], v[126:129]
	v_mfma_f32_16x16x32_bf16 v[122:125], v[114:117], v[184:187], v[122:125]
	v_mfma_f32_16x16x32_bf16 v[102:105], v[86:89], v[192:195], v[102:105]
	v_mfma_f32_16x16x32_bf16 v[98:101], v[114:117], v[192:195], v[98:101]
	v_mfma_f32_16x16x32_bf16 v[78:81], v[86:89], v[200:203], v[78:81]
	v_mfma_f32_16x16x32_bf16 v[74:77], v[114:117], v[200:203], v[74:77]
	s_setprio 0
	s_setprio 1
	v_mfma_f32_16x16x32_bf16 v[142:145], v[90:93], v[166:169], v[142:145]
	v_mfma_f32_16x16x32_bf16 v[138:141], v[118:121], v[166:169], v[138:141]
	v_mfma_f32_16x16x32_bf16 v[126:129], v[90:93], v[188:191], v[126:129]
	v_mfma_f32_16x16x32_bf16 v[122:125], v[118:121], v[188:191], v[122:125]
	v_mfma_f32_16x16x32_bf16 v[102:105], v[90:93], v[196:199], v[102:105]
	v_mfma_f32_16x16x32_bf16 v[98:101], v[118:121], v[196:199], v[98:101]
	v_mfma_f32_16x16x32_bf16 v[78:81], v[90:93], v[204:207], v[78:81]
	v_mfma_f32_16x16x32_bf16 v[74:77], v[118:121], v[204:207], v[74:77]
	s_setprio 0
	s_setprio 1
	v_mfma_f32_16x16x32_bf16 v[134:137], v[146:149], v[162:165], v[134:137]
	v_mfma_f32_16x16x32_bf16 v[130:133], v[154:157], v[162:165], v[130:133]
	v_mfma_f32_16x16x32_bf16 v[110:113], v[146:149], v[184:187], v[110:113]
	v_mfma_f32_16x16x32_bf16 v[106:109], v[154:157], v[184:187], v[106:109]
	v_mfma_f32_16x16x32_bf16 v[94:97], v[146:149], v[192:195], v[94:97]
	v_mfma_f32_16x16x32_bf16 v[82:85], v[154:157], v[192:195], v[82:85]
	v_mfma_f32_16x16x32_bf16 v[70:73], v[146:149], v[200:203], v[70:73]
	v_mfma_f32_16x16x32_bf16 v[66:69], v[154:157], v[200:203], v[66:69]
	s_setprio 0
	s_setprio 1
	v_mfma_f32_16x16x32_bf16 v[134:137], v[150:153], v[166:169], v[134:137]
	v_mfma_f32_16x16x32_bf16 v[130:133], v[158:161], v[166:169], v[130:133]
	v_mfma_f32_16x16x32_bf16 v[110:113], v[150:153], v[188:191], v[110:113]
	v_mfma_f32_16x16x32_bf16 v[106:109], v[158:161], v[188:191], v[106:109]
	v_mfma_f32_16x16x32_bf16 v[94:97], v[150:153], v[196:199], v[94:97]
	v_mfma_f32_16x16x32_bf16 v[82:85], v[158:161], v[196:199], v[82:85]
	v_mfma_f32_16x16x32_bf16 v[70:73], v[150:153], v[204:207], v[70:73]
	v_mfma_f32_16x16x32_bf16 v[66:69], v[158:161], v[204:207], v[66:69]
	s_barrier
	s_setprio 0
	s_add_i32 s12, s64, s49
	v_lshl_add_u64 v[208:209], v[208:209], 0, s[30:31]
	s_mov_b32 m0, s12
	ds_read_b128 v[162:165], v222 offset:49152
	ds_read_b128 v[166:169], v222 offset:50176
	ds_read_b128 v[184:187], v222 offset:51200
	ds_read_b128 v[188:191], v222 offset:52224
	ds_read_b128 v[192:195], v222 offset:53248
	ds_read_b128 v[196:199], v222 offset:54272
	ds_read_b128 v[200:203], v222 offset:55296
	ds_read_b128 v[204:207], v222 offset:56320
	global_load_lds_dwordx4 v[208:209], off
	s_add_i32 m0, s12, 0x2000
	s_add_u32 s10, s10, 0x80080
	v_lshl_add_u64 v[208:209], v[210:211], 0, s[30:31]
	s_addc_u32 s11, s11, 0
	s_add_i32 s12, s65, s49
	global_load_lds_dwordx4 v[208:209], off
	v_lshl_add_u64 v[208:209], s[10:11], 0, v[172:173]
	s_mov_b32 m0, s12
	s_nop 0
	global_load_lds_dwordx4 v[208:209], off
	v_lshl_add_u64 v[208:209], s[10:11], 0, v[176:177]
	s_add_i32 m0, s12, 0x2000
	s_nop 0
	global_load_lds_dwordx4 v[208:209], off
	v_lshl_add_u64 v[208:209], v[212:213], 0, s[30:31]
	s_mov_b32 m0, s56
	s_nop 0
	global_load_lds_dwordx4 v[208:209], off
	v_lshl_add_u64 v[208:209], v[214:215], 0, s[30:31]
	s_mov_b32 m0, s57
	s_nop 0
	global_load_lds_dwordx4 v[208:209], off
	s_waitcnt vmcnt(8)
	s_waitcnt lgkmcnt(0)
	s_setprio 1
	s_barrier
	v_mfma_f32_16x16x32_bf16 v[62:65], v[86:89], v[162:165], v[62:65]
	v_mfma_f32_16x16x32_bf16 v[58:61], v[114:117], v[162:165], v[58:61]
	v_mfma_f32_16x16x32_bf16 v[46:49], v[86:89], v[184:187], v[46:49]
	v_mfma_f32_16x16x32_bf16 v[42:45], v[114:117], v[184:187], v[42:45]
	v_mfma_f32_16x16x32_bf16 v[30:33], v[86:89], v[192:195], v[30:33]
	v_mfma_f32_16x16x32_bf16 v[26:29], v[114:117], v[192:195], v[26:29]
	v_mfma_f32_16x16x32_bf16 v[14:17], v[86:89], v[200:203], v[14:17]
	v_mfma_f32_16x16x32_bf16 v[10:13], v[114:117], v[200:203], v[10:13]
	s_setprio 0
	s_setprio 1
	v_mfma_f32_16x16x32_bf16 v[62:65], v[90:93], v[166:169], v[62:65]
	v_mfma_f32_16x16x32_bf16 v[58:61], v[118:121], v[166:169], v[58:61]
	v_mfma_f32_16x16x32_bf16 v[46:49], v[90:93], v[188:191], v[46:49]
	v_mfma_f32_16x16x32_bf16 v[42:45], v[118:121], v[188:191], v[42:45]
	v_mfma_f32_16x16x32_bf16 v[30:33], v[90:93], v[196:199], v[30:33]
	v_mfma_f32_16x16x32_bf16 v[26:29], v[118:121], v[196:199], v[26:29]
	v_mfma_f32_16x16x32_bf16 v[14:17], v[90:93], v[204:207], v[14:17]
	v_mfma_f32_16x16x32_bf16 v[10:13], v[118:121], v[204:207], v[10:13]
	s_setprio 0
	s_setprio 1
	v_mfma_f32_16x16x32_bf16 v[54:57], v[146:149], v[162:165], v[54:57]
	v_mfma_f32_16x16x32_bf16 v[50:53], v[154:157], v[162:165], v[50:53]
	v_mfma_f32_16x16x32_bf16 v[38:41], v[146:149], v[184:187], v[38:41]
	v_mfma_f32_16x16x32_bf16 v[34:37], v[154:157], v[184:187], v[34:37]
	v_mfma_f32_16x16x32_bf16 v[22:25], v[146:149], v[192:195], v[22:25]
	v_mfma_f32_16x16x32_bf16 v[18:21], v[154:157], v[192:195], v[18:21]
	v_mfma_f32_16x16x32_bf16 v[6:9], v[146:149], v[200:203], v[6:9]
	v_mfma_f32_16x16x32_bf16 v[2:5], v[154:157], v[200:203], v[2:5]
	s_setprio 0
	s_setprio 1
	v_mfma_f32_16x16x32_bf16 v[54:57], v[150:153], v[166:169], v[54:57]
	v_mfma_f32_16x16x32_bf16 v[50:53], v[158:161], v[166:169], v[50:53]
	v_mfma_f32_16x16x32_bf16 v[38:41], v[150:153], v[188:191], v[38:41]
	v_mfma_f32_16x16x32_bf16 v[34:37], v[158:161], v[188:191], v[34:37]
	v_mfma_f32_16x16x32_bf16 v[22:25], v[150:153], v[196:199], v[22:25]
	v_mfma_f32_16x16x32_bf16 v[18:21], v[158:161], v[196:199], v[18:21]
	v_mfma_f32_16x16x32_bf16 v[6:9], v[150:153], v[204:207], v[6:9]
	v_mfma_f32_16x16x32_bf16 v[2:5], v[158:161], v[204:207], v[2:5]
	s_barrier
	s_setprio 0
	s_add_i32 s63, s63, 2
	s_add_u32 s39, s39, 0x100
	s_addc_u32 s41, s41, 0
	s_add_u32 s8, s8, 0x100
	s_addc_u32 s9, s9, 0
	s_cmp_gt_u32 s63, 29
	s_cbranch_scc0 .LBB0_1364
	s_and_b64 vcc, exec, s[36:37]
	s_cbranch_vccz .LBB0_1367
	s_barrier

.LBB0_1390:
	ds_read_b128 v[148:151], v143
	ds_read_b128 v[152:155], v143 offset:1024
	ds_read_b128 v[156:159], v143 offset:2048
	ds_read_b128 v[160:163], v143 offset:3072
	ds_read_b128 v[164:167], v144
	ds_read_b128 v[168:171], v144 offset:1024
	ds_read_b128 v[172:175], v144 offset:2048
	ds_read_b128 v[176:179], v144 offset:3072
	s_add_u32 s12, s10, 0x100
	s_addc_u32 s13, s11, 0
	s_cmp_lg_u32 s0, 4
	s_cselect_b32 s14, s12, 0
	s_cselect_b32 s15, s13, 0
	s_add_u32 s16, s6, s14
	s_addc_u32 s17, s7, s15
	s_add_u32 s14, s4, s14
	s_addc_u32 s15, s5, s15
	s_mov_b32 m0, s1
	v_lshl_add_u64 v[212:213], v[140:141], 0, s[10:11]
	ds_read_b128 v[180:183], v145
	ds_read_b128 v[184:187], v145 offset:1024
	ds_read_b128 v[188:191], v145 offset:2048
	ds_read_b128 v[192:195], v145 offset:3072
	ds_read_b128 v[196:199], v145 offset:4096
	ds_read_b128 v[200:203], v145 offset:5120
	ds_read_b128 v[204:207], v145 offset:6144
	ds_read_b128 v[208:211], v145 offset:7168
	global_load_lds_dwordx4 v[212:213], off
	v_lshl_add_u64 v[212:213], v[138:139], 0, s[10:11]
	s_mov_b32 m0, s30
	s_nop 0
	global_load_lds_dwordx4 v[212:213], off
	s_waitcnt vmcnt(8)
	s_waitcnt lgkmcnt(0)
	s_setprio 1
	s_barrier
	v_mfma_f32_16x16x32_bf16 v[126:129], v[148:151], v[180:183], v[126:129]
	v_mfma_f32_16x16x32_bf16 v[122:125], v[156:159], v[180:183], v[122:125]
	v_mfma_f32_16x16x32_bf16 v[118:121], v[148:151], v[188:191], v[118:121]
	v_mfma_f32_16x16x32_bf16 v[114:117], v[156:159], v[188:191], v[114:117]
	v_mfma_f32_16x16x32_bf16 v[106:109], v[148:151], v[196:199], v[106:109]
	v_mfma_f32_16x16x32_bf16 v[98:101], v[156:159], v[196:199], v[98:101]
	v_mfma_f32_16x16x32_bf16 v[90:93], v[148:151], v[204:207], v[90:93]
	v_mfma_f32_16x16x32_bf16 v[82:85], v[156:159], v[204:207], v[82:85]
	s_setprio 0
	s_setprio 1
	v_mfma_f32_16x16x32_bf16 v[126:129], v[152:155], v[184:187], v[126:129]
	v_mfma_f32_16x16x32_bf16 v[122:125], v[160:163], v[184:187], v[122:125]
	v_mfma_f32_16x16x32_bf16 v[118:121], v[152:155], v[192:195], v[118:121]
	v_mfma_f32_16x16x32_bf16 v[114:117], v[160:163], v[192:195], v[114:117]
	v_mfma_f32_16x16x32_bf16 v[106:109], v[152:155], v[200:203], v[106:109]
	v_mfma_f32_16x16x32_bf16 v[98:101], v[160:163], v[200:203], v[98:101]
	v_mfma_f32_16x16x32_bf16 v[90:93], v[152:155], v[208:211], v[90:93]
	v_mfma_f32_16x16x32_bf16 v[82:85], v[160:163], v[208:211], v[82:85]
	s_setprio 0
	s_setprio 1
	v_mfma_f32_16x16x32_bf16 v[110:113], v[164:167], v[180:183], v[110:113]
	v_mfma_f32_16x16x32_bf16 v[102:105], v[172:175], v[180:183], v[102:105]
	v_mfma_f32_16x16x32_bf16 v[94:97], v[164:167], v[188:191], v[94:97]
	v_mfma_f32_16x16x32_bf16 v[86:89], v[172:175], v[188:191], v[86:89]
	v_mfma_f32_16x16x32_bf16 v[78:81], v[164:167], v[196:199], v[78:81]
	v_mfma_f32_16x16x32_bf16 v[74:77], v[172:175], v[196:199], v[74:77]
	v_mfma_f32_16x16x32_bf16 v[70:73], v[164:167], v[204:207], v[70:73]
	v_mfma_f32_16x16x32_bf16 v[66:69], v[172:175], v[204:207], v[66:69]
	s_setprio 0
	s_setprio 1
	v_mfma_f32_16x16x32_bf16 v[110:113], v[168:171], v[184:187], v[110:113]
	v_mfma_f32_16x16x32_bf16 v[102:105], v[176:179], v[184:187], v[102:105]
	v_mfma_f32_16x16x32_bf16 v[94:97], v[168:171], v[192:195], v[94:97]
	v_mfma_f32_16x16x32_bf16 v[86:89], v[176:179], v[192:195], v[86:89]
	v_mfma_f32_16x16x32_bf16 v[78:81], v[168:171], v[200:203], v[78:81]
	v_mfma_f32_16x16x32_bf16 v[74:77], v[176:179], v[200:203], v[74:77]
	v_mfma_f32_16x16x32_bf16 v[70:73], v[168:171], v[208:211], v[70:73]
	v_mfma_f32_16x16x32_bf16 v[66:69], v[176:179], v[208:211], v[66:69]
	s_barrier
	s_setprio 0
	s_mov_b32 m0, s31
	v_lshl_add_u64 v[212:213], s[14:15], 0, v[132:133]
	s_add_u32 s10, s14, 0x80000
	ds_read_b128 v[180:183], v145 offset:16384
	ds_read_b128 v[184:187], v145 offset:17408
	ds_read_b128 v[188:191], v145 offset:18432
	ds_read_b128 v[192:195], v145 offset:19456
	ds_read_b128 v[196:199], v145 offset:20480
	ds_read_b128 v[200:203], v145 offset:21504
	ds_read_b128 v[204:207], v145 offset:22528
	ds_read_b128 v[208:211], v145 offset:23552
	global_load_lds_dwordx4 v[212:213], off
	v_lshl_add_u64 v[214:215], s[14:15], 0, v[136:137]
	s_mov_b32 m0, s33
	s_addc_u32 s11, s15, 0
	global_load_lds_dwordx4 v[214:215], off
	v_lshl_add_u64 v[216:217], s[10:11], 0, v[132:133]
	s_mov_b32 m0, s34
	v_lshl_add_u64 v[218:219], s[16:17], 0, v[134:135]
	global_load_lds_dwordx4 v[216:217], off
	v_lshl_add_u64 v[216:217], s[10:11], 0, v[136:137]
	s_mov_b32 m0, s35
	s_nop 0
	global_load_lds_dwordx4 v[216:217], off
	v_lshl_add_u64 v[216:217], s[16:17], 0, v[130:131]
	s_mov_b32 m0, s20
	s_nop 0
	global_load_lds_dwordx4 v[216:217], off
	s_mov_b32 m0, s23
	s_nop 0
	global_load_lds_dwordx4 v[218:219], off
	s_waitcnt vmcnt(8)
	s_waitcnt lgkmcnt(0)
	s_setprio 1
	s_barrier
	v_mfma_f32_16x16x32_bf16 v[62:65], v[148:151], v[180:183], v[62:65]
	v_mfma_f32_16x16x32_bf16 v[58:61], v[156:159], v[180:183], v[58:61]
	v_mfma_f32_16x16x32_bf16 v[54:57], v[148:151], v[188:191], v[54:57]
	v_mfma_f32_16x16x32_bf16 v[50:53], v[156:159], v[188:191], v[50:53]
	v_mfma_f32_16x16x32_bf16 v[42:45], v[148:151], v[196:199], v[42:45]
	v_mfma_f32_16x16x32_bf16 v[34:37], v[156:159], v[196:199], v[34:37]
	v_mfma_f32_16x16x32_bf16 v[26:29], v[148:151], v[204:207], v[26:29]
	v_mfma_f32_16x16x32_bf16 v[18:21], v[156:159], v[204:207], v[18:21]
	s_setprio 0
	s_setprio 1
	v_mfma_f32_16x16x32_bf16 v[62:65], v[152:155], v[184:187], v[62:65]
	v_mfma_f32_16x16x32_bf16 v[58:61], v[160:163], v[184:187], v[58:61]
	v_mfma_f32_16x16x32_bf16 v[54:57], v[152:155], v[192:195], v[54:57]
	v_mfma_f32_16x16x32_bf16 v[50:53], v[160:163], v[192:195], v[50:53]
	v_mfma_f32_16x16x32_bf16 v[42:45], v[152:155], v[200:203], v[42:45]
	v_mfma_f32_16x16x32_bf16 v[34:37], v[160:163], v[200:203], v[34:37]
	v_mfma_f32_16x16x32_bf16 v[26:29], v[152:155], v[208:211], v[26:29]
	v_mfma_f32_16x16x32_bf16 v[18:21], v[160:163], v[208:211], v[18:21]
	s_setprio 0
	s_setprio 1
	v_mfma_f32_16x16x32_bf16 v[46:49], v[164:167], v[180:183], v[46:49]
	v_mfma_f32_16x16x32_bf16 v[38:41], v[172:175], v[180:183], v[38:41]
	v_mfma_f32_16x16x32_bf16 v[30:33], v[164:167], v[188:191], v[30:33]
	v_mfma_f32_16x16x32_bf16 v[22:25], v[172:175], v[188:191], v[22:25]
	v_mfma_f32_16x16x32_bf16 v[14:17], v[164:167], v[196:199], v[14:17]
	v_mfma_f32_16x16x32_bf16 v[10:13], v[172:175], v[196:199], v[10:13]
	v_mfma_f32_16x16x32_bf16 v[6:9], v[164:167], v[204:207], v[6:9]
	v_mfma_f32_16x16x32_bf16 v[2:5], v[172:175], v[204:207], v[2:5]
	s_setprio 0
	s_setprio 1
	v_mfma_f32_16x16x32_bf16 v[46:49], v[168:171], v[184:187], v[46:49]
	v_mfma_f32_16x16x32_bf16 v[38:41], v[176:179], v[184:187], v[38:41]
	v_mfma_f32_16x16x32_bf16 v[30:33], v[168:171], v[192:195], v[30:33]
	v_mfma_f32_16x16x32_bf16 v[22:25], v[176:179], v[192:195], v[22:25]
	v_mfma_f32_16x16x32_bf16 v[14:17], v[168:171], v[200:203], v[14:17]
	v_mfma_f32_16x16x32_bf16 v[10:13], v[176:179], v[200:203], v[10:13]
	v_mfma_f32_16x16x32_bf16 v[6:9], v[168:171], v[208:211], v[6:9]
	v_mfma_f32_16x16x32_bf16 v[2:5], v[176:179], v[208:211], v[2:5]
	s_barrier
	s_setprio 0
	ds_read_b128 v[148:151], v146
	ds_read_b128 v[152:155], v146 offset:1024
	ds_read_b128 v[156:159], v146 offset:2048
	ds_read_b128 v[160:163], v146 offset:3072
	ds_read_b128 v[164:167], v147
	ds_read_b128 v[168:171], v147 offset:1024
	ds_read_b128 v[172:175], v147 offset:2048
	ds_read_b128 v[176:179], v147 offset:3072
	s_add_u32 s10, s16, 0x80000
	s_addc_u32 s11, s17, 0
	s_mov_b32 m0, s24
	v_lshl_add_u64 v[220:221], s[10:11], 0, v[130:131]
	ds_read_b128 v[180:183], v145 offset:32768
	ds_read_b128 v[184:187], v145 offset:33792
	ds_read_b128 v[188:191], v145 offset:34816
	ds_read_b128 v[192:195], v145 offset:35840
	ds_read_b128 v[196:199], v145 offset:36864
	ds_read_b128 v[200:203], v145 offset:37888
	ds_read_b128 v[204:207], v145 offset:38912
	ds_read_b128 v[208:211], v145 offset:39936
	global_load_lds_dwordx4 v[220:221], off
	v_lshl_add_u64 v[220:221], s[10:11], 0, v[134:135]
	s_mov_b32 m0, s26
	s_nop 0
	global_load_lds_dwordx4 v[220:221], off
	s_waitcnt vmcnt(8)
	s_waitcnt lgkmcnt(0)
	s_setprio 1
	s_barrier
	v_mfma_f32_16x16x32_bf16 v[126:129], v[148:151], v[180:183], v[126:129]
	v_mfma_f32_16x16x32_bf16 v[122:125], v[156:159], v[180:183], v[122:125]
	v_mfma_f32_16x16x32_bf16 v[118:121], v[148:151], v[188:191], v[118:121]
	v_mfma_f32_16x16x32_bf16 v[114:117], v[156:159], v[188:191], v[114:117]
	v_mfma_f32_16x16x32_bf16 v[106:109], v[148:151], v[196:199], v[106:109]
	v_mfma_f32_16x16x32_bf16 v[98:101], v[156:159], v[196:199], v[98:101]
	v_mfma_f32_16x16x32_bf16 v[90:93], v[148:151], v[204:207], v[90:93]
	v_mfma_f32_16x16x32_bf16 v[82:85], v[156:159], v[204:207], v[82:85]
	s_setprio 0
	s_setprio 1
	v_mfma_f32_16x16x32_bf16 v[126:129], v[152:155], v[184:187], v[126:129]
	v_mfma_f32_16x16x32_bf16 v[122:125], v[160:163], v[184:187], v[122:125]
	v_mfma_f32_16x16x32_bf16 v[118:121], v[152:155], v[192:195], v[118:121]
	v_mfma_f32_16x16x32_bf16 v[114:117], v[160:163], v[192:195], v[114:117]
	v_mfma_f32_16x16x32_bf16 v[106:109], v[152:155], v[200:203], v[106:109]
	v_mfma_f32_16x16x32_bf16 v[98:101], v[160:163], v[200:203], v[98:101]
	v_mfma_f32_16x16x32_bf16 v[90:93], v[152:155], v[208:211], v[90:93]
	v_mfma_f32_16x16x32_bf16 v[82:85], v[160:163], v[208:211], v[82:85]
	s_setprio 0
	s_setprio 1
	v_mfma_f32_16x16x32_bf16 v[110:113], v[164:167], v[180:183], v[110:113]
	v_mfma_f32_16x16x32_bf16 v[102:105], v[172:175], v[180:183], v[102:105]
	v_mfma_f32_16x16x32_bf16 v[94:97], v[164:167], v[188:191], v[94:97]
	v_mfma_f32_16x16x32_bf16 v[86:89], v[172:175], v[188:191], v[86:89]
	v_mfma_f32_16x16x32_bf16 v[78:81], v[164:167], v[196:199], v[78:81]
	v_mfma_f32_16x16x32_bf16 v[74:77], v[172:175], v[196:199], v[74:77]
	v_mfma_f32_16x16x32_bf16 v[70:73], v[164:167], v[204:207], v[70:73]
	v_mfma_f32_16x16x32_bf16 v[66:69], v[172:175], v[204:207], v[66:69]
	s_setprio 0
	s_setprio 1
	v_mfma_f32_16x16x32_bf16 v[110:113], v[168:171], v[184:187], v[110:113]
	v_mfma_f32_16x16x32_bf16 v[102:105], v[176:179], v[184:187], v[102:105]
	v_mfma_f32_16x16x32_bf16 v[94:97], v[168:171], v[192:195], v[94:97]
	v_mfma_f32_16x16x32_bf16 v[86:89], v[176:179], v[192:195], v[86:89]
	v_mfma_f32_16x16x32_bf16 v[78:81], v[168:171], v[200:203], v[78:81]
	v_mfma_f32_16x16x32_bf16 v[74:77], v[176:179], v[200:203], v[74:77]
	v_mfma_f32_16x16x32_bf16 v[70:73], v[168:171], v[208:211], v[70:73]
	v_mfma_f32_16x16x32_bf16 v[66:69], v[176:179], v[208:211], v[66:69]
	s_barrier
	s_setprio 0
	s_mov_b32 m0, s36
	v_lshl_add_u64 v[212:213], v[212:213], 0, s[8:9]
	s_add_u32 s10, s14, 0x80080
	ds_read_b128 v[180:183], v145 offset:49152
	ds_read_b128 v[184:187], v145 offset:50176
	ds_read_b128 v[188:191], v145 offset:51200
	ds_read_b128 v[192:195], v145 offset:52224
	ds_read_b128 v[196:199], v145 offset:53248
	ds_read_b128 v[200:203], v145 offset:54272
	ds_read_b128 v[204:207], v145 offset:55296
	ds_read_b128 v[208:211], v145 offset:56320
	global_load_lds_dwordx4 v[212:213], off
	v_lshl_add_u64 v[212:213], v[214:215], 0, s[8:9]
	s_mov_b32 m0, s37
	s_addc_u32 s11, s15, 0
	global_load_lds_dwordx4 v[212:213], off
	v_lshl_add_u64 v[212:213], s[10:11], 0, v[132:133]
	s_mov_b32 m0, s38
	s_nop 0
	global_load_lds_dwordx4 v[212:213], off
	v_lshl_add_u64 v[212:213], s[10:11], 0, v[136:137]
	s_mov_b32 m0, s39
	s_nop 0
	global_load_lds_dwordx4 v[212:213], off
	v_lshl_add_u64 v[212:213], v[216:217], 0, s[8:9]
	s_mov_b32 m0, s28
	s_nop 0
	global_load_lds_dwordx4 v[212:213], off
	v_lshl_add_u64 v[212:213], v[218:219], 0, s[8:9]
	s_mov_b32 m0, s29
	s_nop 0
	global_load_lds_dwordx4 v[212:213], off
	s_waitcnt vmcnt(8)
	s_waitcnt lgkmcnt(0)
	s_setprio 1
	s_barrier
	v_mfma_f32_16x16x32_bf16 v[62:65], v[148:151], v[180:183], v[62:65]
	v_mfma_f32_16x16x32_bf16 v[58:61], v[156:159], v[180:183], v[58:61]
	v_mfma_f32_16x16x32_bf16 v[54:57], v[148:151], v[188:191], v[54:57]
	v_mfma_f32_16x16x32_bf16 v[50:53], v[156:159], v[188:191], v[50:53]
	v_mfma_f32_16x16x32_bf16 v[42:45], v[148:151], v[196:199], v[42:45]
	v_mfma_f32_16x16x32_bf16 v[34:37], v[156:159], v[196:199], v[34:37]
	v_mfma_f32_16x16x32_bf16 v[26:29], v[148:151], v[204:207], v[26:29]
	v_mfma_f32_16x16x32_bf16 v[18:21], v[156:159], v[204:207], v[18:21]
	s_setprio 0
	s_setprio 1
	v_mfma_f32_16x16x32_bf16 v[62:65], v[152:155], v[184:187], v[62:65]
	v_mfma_f32_16x16x32_bf16 v[58:61], v[160:163], v[184:187], v[58:61]
	v_mfma_f32_16x16x32_bf16 v[54:57], v[152:155], v[192:195], v[54:57]
	v_mfma_f32_16x16x32_bf16 v[50:53], v[160:163], v[192:195], v[50:53]
	v_mfma_f32_16x16x32_bf16 v[42:45], v[152:155], v[200:203], v[42:45]
	v_mfma_f32_16x16x32_bf16 v[34:37], v[160:163], v[200:203], v[34:37]
	v_mfma_f32_16x16x32_bf16 v[26:29], v[152:155], v[208:211], v[26:29]
	v_mfma_f32_16x16x32_bf16 v[18:21], v[160:163], v[208:211], v[18:21]
	s_setprio 0
	s_setprio 1
	v_mfma_f32_16x16x32_bf16 v[46:49], v[164:167], v[180:183], v[46:49]
	v_mfma_f32_16x16x32_bf16 v[38:41], v[172:175], v[180:183], v[38:41]
	v_mfma_f32_16x16x32_bf16 v[30:33], v[164:167], v[188:191], v[30:33]
	v_mfma_f32_16x16x32_bf16 v[22:25], v[172:175], v[188:191], v[22:25]
	v_mfma_f32_16x16x32_bf16 v[14:17], v[164:167], v[196:199], v[14:17]
	v_mfma_f32_16x16x32_bf16 v[10:13], v[172:175], v[196:199], v[10:13]
	v_mfma_f32_16x16x32_bf16 v[6:9], v[164:167], v[204:207], v[6:9]
	v_mfma_f32_16x16x32_bf16 v[2:5], v[172:175], v[204:207], v[2:5]
	s_setprio 0
	s_setprio 1
	v_mfma_f32_16x16x32_bf16 v[46:49], v[168:171], v[184:187], v[46:49]
	v_mfma_f32_16x16x32_bf16 v[38:41], v[176:179], v[184:187], v[38:41]
	v_mfma_f32_16x16x32_bf16 v[30:33], v[168:171], v[192:195], v[30:33]
	v_mfma_f32_16x16x32_bf16 v[22:25], v[176:179], v[192:195], v[22:25]
	v_mfma_f32_16x16x32_bf16 v[14:17], v[168:171], v[200:203], v[14:17]
	v_mfma_f32_16x16x32_bf16 v[10:13], v[176:179], v[200:203], v[10:13]
	v_mfma_f32_16x16x32_bf16 v[6:9], v[168:171], v[208:211], v[6:9]
	v_mfma_f32_16x16x32_bf16 v[2:5], v[176:179], v[208:211], v[2:5]
	s_barrier
	s_setprio 0
	s_add_i32 s0, s0, 2
	s_cmp_gt_u32 s0, 5
	s_mov_b64 s[10:11], s[12:13]
	s_cbranch_scc0 .LBB0_1390
	s_cmpk_lt_u32 s19, 0x100
	s_cbranch_scc0 .LBB0_1393
	s_barrier

.LBB0_1525:
	ds_read_b128 v[146:149], v152
	ds_read_b128 v[156:159], v152 offset:1024
	ds_read_b128 v[160:163], v152 offset:2048
	ds_read_b128 v[164:167], v152 offset:3072
	ds_read_b128 v[168:171], v153
	ds_read_b128 v[172:175], v153 offset:1024
	ds_read_b128 v[176:179], v153 offset:2048
	ds_read_b128 v[180:183], v153 offset:3072
	s_add_u32 s46, s44, 0xfff80080
	s_addc_u32 s47, s45, -1
	s_cmp_eq_u32 s73, 28
	s_cselect_b32 s49, s37, s47
	s_cselect_b32 s48, s69, s46
	s_cselect_b32 s47, s31, s72
	s_cselect_b32 s46, s70, s71
	v_lshl_add_u64 v[216:217], s[44:45], 0, v[140:141]
	s_add_i32 m0, s43, 0xc000
	ds_read_b128 v[184:187], v154
	ds_read_b128 v[188:191], v154 offset:1024
	ds_read_b128 v[192:195], v154 offset:2048
	ds_read_b128 v[196:199], v154 offset:3072
	ds_read_b128 v[200:203], v154 offset:4096
	ds_read_b128 v[204:207], v154 offset:5120
	ds_read_b128 v[208:211], v154 offset:6144
	ds_read_b128 v[212:215], v154 offset:7168
	global_load_lds_dwordx4 v[216:217], off
	v_lshl_add_u64 v[216:217], s[44:45], 0, v[138:139]
	s_add_i32 m0, s43, 0xe000
	s_nop 0
	global_load_lds_dwordx4 v[216:217], off
	s_waitcnt vmcnt(8)
	s_waitcnt lgkmcnt(0)
	s_setprio 1
	s_barrier
	v_mfma_f32_16x16x32_bf16 v[126:129], v[146:149], v[184:187], v[126:129]
	v_mfma_f32_16x16x32_bf16 v[122:125], v[160:163], v[184:187], v[122:125]
	v_mfma_f32_16x16x32_bf16 v[110:113], v[146:149], v[192:195], v[110:113]
	v_mfma_f32_16x16x32_bf16 v[106:109], v[160:163], v[192:195], v[106:109]
	v_mfma_f32_16x16x32_bf16 v[94:97], v[146:149], v[200:203], v[94:97]
	v_mfma_f32_16x16x32_bf16 v[90:93], v[160:163], v[200:203], v[90:93]
	v_mfma_f32_16x16x32_bf16 v[78:81], v[146:149], v[208:211], v[78:81]
	v_mfma_f32_16x16x32_bf16 v[74:77], v[160:163], v[208:211], v[74:77]
	s_setprio 0
	s_setprio 1
	v_mfma_f32_16x16x32_bf16 v[126:129], v[156:159], v[188:191], v[126:129]
	v_mfma_f32_16x16x32_bf16 v[122:125], v[164:167], v[188:191], v[122:125]
	v_mfma_f32_16x16x32_bf16 v[110:113], v[156:159], v[196:199], v[110:113]
	v_mfma_f32_16x16x32_bf16 v[106:109], v[164:167], v[196:199], v[106:109]
	v_mfma_f32_16x16x32_bf16 v[94:97], v[156:159], v[204:207], v[94:97]
	v_mfma_f32_16x16x32_bf16 v[90:93], v[164:167], v[204:207], v[90:93]
	v_mfma_f32_16x16x32_bf16 v[78:81], v[156:159], v[212:215], v[78:81]
	v_mfma_f32_16x16x32_bf16 v[74:77], v[164:167], v[212:215], v[74:77]
	s_setprio 0
	s_setprio 1
	v_mfma_f32_16x16x32_bf16 v[118:121], v[168:171], v[184:187], v[118:121]
	v_mfma_f32_16x16x32_bf16 v[114:117], v[176:179], v[184:187], v[114:117]
	v_mfma_f32_16x16x32_bf16 v[102:105], v[168:171], v[192:195], v[102:105]
	v_mfma_f32_16x16x32_bf16 v[98:101], v[176:179], v[192:195], v[98:101]
	v_mfma_f32_16x16x32_bf16 v[86:89], v[168:171], v[200:203], v[86:89]
	v_mfma_f32_16x16x32_bf16 v[82:85], v[176:179], v[200:203], v[82:85]
	v_mfma_f32_16x16x32_bf16 v[70:73], v[168:171], v[208:211], v[70:73]
	v_mfma_f32_16x16x32_bf16 v[66:69], v[176:179], v[208:211], v[66:69]
	s_setprio 0
	s_setprio 1
	v_mfma_f32_16x16x32_bf16 v[118:121], v[172:175], v[188:191], v[118:121]
	v_mfma_f32_16x16x32_bf16 v[114:117], v[180:183], v[188:191], v[114:117]
	v_mfma_f32_16x16x32_bf16 v[102:105], v[172:175], v[196:199], v[102:105]
	v_mfma_f32_16x16x32_bf16 v[98:101], v[180:183], v[196:199], v[98:101]
	v_mfma_f32_16x16x32_bf16 v[86:89], v[172:175], v[204:207], v[86:89]
	v_mfma_f32_16x16x32_bf16 v[82:85], v[180:183], v[204:207], v[82:85]
	v_mfma_f32_16x16x32_bf16 v[70:73], v[172:175], v[212:215], v[70:73]
	v_mfma_f32_16x16x32_bf16 v[66:69], v[180:183], v[212:215], v[66:69]
	s_barrier
	s_setprio 0
	s_add_i32 s74, s61, s34
	v_lshl_add_u64 v[216:217], s[46:47], 0, v[134:135]
	s_mov_b32 m0, s74
	ds_read_b128 v[184:187], v154 offset:16384
	ds_read_b128 v[188:191], v154 offset:17408
	ds_read_b128 v[192:195], v154 offset:18432
	ds_read_b128 v[196:199], v154 offset:19456
	ds_read_b128 v[200:203], v154 offset:20480
	ds_read_b128 v[204:207], v154 offset:21504
	ds_read_b128 v[208:211], v154 offset:22528
	ds_read_b128 v[212:215], v154 offset:23552
	global_load_lds_dwordx4 v[216:217], off
	s_add_i32 m0, s74, 0x2000
	s_add_u32 s74, s46, 0x80000
	v_lshl_add_u64 v[218:219], s[46:47], 0, v[130:131]
	s_addc_u32 s75, s47, 0
	s_add_i32 s76, s62, s34
	global_load_lds_dwordx4 v[218:219], off
	v_lshl_add_u64 v[220:221], s[74:75], 0, v[134:135]
	s_mov_b32 m0, s76
	v_lshl_add_u64 v[222:223], s[48:49], 0, v[132:133]
	global_load_lds_dwordx4 v[220:221], off
	v_lshl_add_u64 v[220:221], s[74:75], 0, v[130:131]
	s_add_i32 m0, s76, 0x2000
	s_nop 0
	global_load_lds_dwordx4 v[220:221], off
	v_lshl_add_u64 v[220:221], s[48:49], 0, v[136:137]
	s_mov_b32 m0, s43
	s_nop 0
	global_load_lds_dwordx4 v[220:221], off
	s_mov_b32 m0, s50
	s_nop 0
	global_load_lds_dwordx4 v[222:223], off
	s_waitcnt vmcnt(8)
	s_waitcnt lgkmcnt(0)
	s_setprio 1
	s_barrier
	v_mfma_f32_16x16x32_bf16 v[62:65], v[146:149], v[184:187], v[62:65]
	v_mfma_f32_16x16x32_bf16 v[58:61], v[160:163], v[184:187], v[58:61]
	v_mfma_f32_16x16x32_bf16 v[46:49], v[146:149], v[192:195], v[46:49]
	v_mfma_f32_16x16x32_bf16 v[42:45], v[160:163], v[192:195], v[42:45]
	v_mfma_f32_16x16x32_bf16 v[30:33], v[146:149], v[200:203], v[30:33]
	v_mfma_f32_16x16x32_bf16 v[26:29], v[160:163], v[200:203], v[26:29]
	v_mfma_f32_16x16x32_bf16 v[14:17], v[146:149], v[208:211], v[14:17]
	v_mfma_f32_16x16x32_bf16 v[10:13], v[160:163], v[208:211], v[10:13]
	s_setprio 0
	s_setprio 1
	v_mfma_f32_16x16x32_bf16 v[62:65], v[156:159], v[188:191], v[62:65]
	v_mfma_f32_16x16x32_bf16 v[58:61], v[164:167], v[188:191], v[58:61]
	v_mfma_f32_16x16x32_bf16 v[46:49], v[156:159], v[196:199], v[46:49]
	v_mfma_f32_16x16x32_bf16 v[42:45], v[164:167], v[196:199], v[42:45]
	v_mfma_f32_16x16x32_bf16 v[30:33], v[156:159], v[204:207], v[30:33]
	v_mfma_f32_16x16x32_bf16 v[26:29], v[164:167], v[204:207], v[26:29]
	v_mfma_f32_16x16x32_bf16 v[14:17], v[156:159], v[212:215], v[14:17]
	v_mfma_f32_16x16x32_bf16 v[10:13], v[164:167], v[212:215], v[10:13]
	s_setprio 0
	s_setprio 1
	v_mfma_f32_16x16x32_bf16 v[54:57], v[168:171], v[184:187], v[54:57]
	v_mfma_f32_16x16x32_bf16 v[50:53], v[176:179], v[184:187], v[50:53]
	v_mfma_f32_16x16x32_bf16 v[38:41], v[168:171], v[192:195], v[38:41]
	v_mfma_f32_16x16x32_bf16 v[34:37], v[176:179], v[192:195], v[34:37]
	v_mfma_f32_16x16x32_bf16 v[22:25], v[168:171], v[200:203], v[22:25]
	v_mfma_f32_16x16x32_bf16 v[18:21], v[176:179], v[200:203], v[18:21]
	v_mfma_f32_16x16x32_bf16 v[6:9], v[168:171], v[208:211], v[6:9]
	v_mfma_f32_16x16x32_bf16 v[2:5], v[176:179], v[208:211], v[2:5]
	s_setprio 0
	s_setprio 1
	v_mfma_f32_16x16x32_bf16 v[54:57], v[172:175], v[188:191], v[54:57]
	v_mfma_f32_16x16x32_bf16 v[50:53], v[180:183], v[188:191], v[50:53]
	v_mfma_f32_16x16x32_bf16 v[38:41], v[172:175], v[196:199], v[38:41]
	v_mfma_f32_16x16x32_bf16 v[34:37], v[180:183], v[196:199], v[34:37]
	v_mfma_f32_16x16x32_bf16 v[22:25], v[172:175], v[204:207], v[22:25]
	v_mfma_f32_16x16x32_bf16 v[18:21], v[180:183], v[204:207], v[18:21]
	v_mfma_f32_16x16x32_bf16 v[6:9], v[172:175], v[212:215], v[6:9]
	v_mfma_f32_16x16x32_bf16 v[2:5], v[180:183], v[212:215], v[2:5]
	s_barrier
	s_setprio 0
	s_add_i32 s74, 0, 0x18000
	v_add_u32_e32 v155, s74, v151
	s_add_i32 s75, 0, 0x1c000
	ds_read_b128 v[146:149], v155
	ds_read_b128 v[156:159], v155 offset:1024
	ds_read_b128 v[160:163], v155 offset:2048
	ds_read_b128 v[164:167], v155 offset:3072
	v_add_u32_e32 v155, s75, v151
	ds_read_b128 v[168:171], v155
	ds_read_b128 v[172:175], v155 offset:1024
	ds_read_b128 v[176:179], v155 offset:2048
	ds_read_b128 v[180:183], v155 offset:3072
	s_add_u32 s48, s48, 0x80000
	s_addc_u32 s49, s49, 0
	s_mov_b32 m0, s51
	v_lshl_add_u64 v[224:225], s[48:49], 0, v[136:137]
	ds_read_b128 v[184:187], v154 offset:32768
	ds_read_b128 v[188:191], v154 offset:33792
	ds_read_b128 v[192:195], v154 offset:34816
	ds_read_b128 v[196:199], v154 offset:35840
	ds_read_b128 v[200:203], v154 offset:36864
	ds_read_b128 v[204:207], v154 offset:37888
	ds_read_b128 v[208:211], v154 offset:38912
	ds_read_b128 v[212:215], v154 offset:39936
	global_load_lds_dwordx4 v[224:225], off
	v_lshl_add_u64 v[224:225], s[48:49], 0, v[132:133]
	s_mov_b32 m0, s52
	s_nop 0
	global_load_lds_dwordx4 v[224:225], off
	s_waitcnt vmcnt(8)
	s_waitcnt lgkmcnt(0)
	s_setprio 1
	s_barrier
	v_mfma_f32_16x16x32_bf16 v[126:129], v[146:149], v[184:187], v[126:129]
	v_mfma_f32_16x16x32_bf16 v[122:125], v[160:163], v[184:187], v[122:125]
	v_mfma_f32_16x16x32_bf16 v[110:113], v[146:149], v[192:195], v[110:113]
	v_mfma_f32_16x16x32_bf16 v[106:109], v[160:163], v[192:195], v[106:109]
	v_mfma_f32_16x16x32_bf16 v[94:97], v[146:149], v[200:203], v[94:97]
	v_mfma_f32_16x16x32_bf16 v[90:93], v[160:163], v[200:203], v[90:93]
	v_mfma_f32_16x16x32_bf16 v[78:81], v[146:149], v[208:211], v[78:81]
	v_mfma_f32_16x16x32_bf16 v[74:77], v[160:163], v[208:211], v[74:77]
	s_setprio 0
	s_setprio 1
	v_mfma_f32_16x16x32_bf16 v[126:129], v[156:159], v[188:191], v[126:129]
	v_mfma_f32_16x16x32_bf16 v[122:125], v[164:167], v[188:191], v[122:125]
	v_mfma_f32_16x16x32_bf16 v[110:113], v[156:159], v[196:199], v[110:113]
	v_mfma_f32_16x16x32_bf16 v[106:109], v[164:167], v[196:199], v[106:109]
	v_mfma_f32_16x16x32_bf16 v[94:97], v[156:159], v[204:207], v[94:97]
	v_mfma_f32_16x16x32_bf16 v[90:93], v[164:167], v[204:207], v[90:93]
	v_mfma_f32_16x16x32_bf16 v[78:81], v[156:159], v[212:215], v[78:81]
	v_mfma_f32_16x16x32_bf16 v[74:77], v[164:167], v[212:215], v[74:77]
	s_setprio 0
	s_setprio 1
	v_mfma_f32_16x16x32_bf16 v[118:121], v[168:171], v[184:187], v[118:121]
	v_mfma_f32_16x16x32_bf16 v[114:117], v[176:179], v[184:187], v[114:117]
	v_mfma_f32_16x16x32_bf16 v[102:105], v[168:171], v[192:195], v[102:105]
	v_mfma_f32_16x16x32_bf16 v[98:101], v[176:179], v[192:195], v[98:101]
	v_mfma_f32_16x16x32_bf16 v[86:89], v[168:171], v[200:203], v[86:89]
	v_mfma_f32_16x16x32_bf16 v[82:85], v[176:179], v[200:203], v[82:85]
	v_mfma_f32_16x16x32_bf16 v[70:73], v[168:171], v[208:211], v[70:73]
	v_mfma_f32_16x16x32_bf16 v[66:69], v[176:179], v[208:211], v[66:69]
	s_setprio 0
	s_setprio 1
	v_mfma_f32_16x16x32_bf16 v[118:121], v[172:175], v[188:191], v[118:121]
	v_mfma_f32_16x16x32_bf16 v[114:117], v[180:183], v[188:191], v[114:117]
	v_mfma_f32_16x16x32_bf16 v[102:105], v[172:175], v[196:199], v[102:105]
	v_mfma_f32_16x16x32_bf16 v[98:101], v[180:183], v[196:199], v[98:101]
	v_mfma_f32_16x16x32_bf16 v[86:89], v[172:175], v[204:207], v[86:89]
	v_mfma_f32_16x16x32_bf16 v[82:85], v[180:183], v[204:207], v[82:85]
	v_mfma_f32_16x16x32_bf16 v[70:73], v[172:175], v[212:215], v[70:73]
	v_mfma_f32_16x16x32_bf16 v[66:69], v[180:183], v[212:215], v[66:69]
	s_barrier
	s_setprio 0
	s_add_i32 s48, s74, s34
	v_lshl_add_u64 v[216:217], v[216:217], 0, s[12:13]
	s_mov_b32 m0, s48
	ds_read_b128 v[184:187], v154 offset:49152
	ds_read_b128 v[188:191], v154 offset:50176
	ds_read_b128 v[192:195], v154 offset:51200
	ds_read_b128 v[196:199], v154 offset:52224
	ds_read_b128 v[200:203], v154 offset:53248
	ds_read_b128 v[204:207], v154 offset:54272
	ds_read_b128 v[208:211], v154 offset:55296
	ds_read_b128 v[212:215], v154 offset:56320
	global_load_lds_dwordx4 v[216:217], off
	s_add_i32 m0, s48, 0x2000
	s_add_u32 s46, s46, 0x80080
	v_lshl_add_u64 v[216:217], v[218:219], 0, s[12:13]
	s_addc_u32 s47, s47, 0
	s_add_i32 s48, s75, s34
	global_load_lds_dwordx4 v[216:217], off
	v_lshl_add_u64 v[216:217], s[46:47], 0, v[134:135]
	s_mov_b32 m0, s48
	s_nop 0
	global_load_lds_dwordx4 v[216:217], off
	v_lshl_add_u64 v[216:217], s[46:47], 0, v[130:131]
	s_add_i32 m0, s48, 0x2000
	s_nop 0
	global_load_lds_dwordx4 v[216:217], off
	v_lshl_add_u64 v[216:217], v[220:221], 0, s[12:13]
	s_mov_b32 m0, s56
	s_nop 0
	global_load_lds_dwordx4 v[216:217], off
	v_lshl_add_u64 v[216:217], v[222:223], 0, s[12:13]
	s_mov_b32 m0, s57
	s_nop 0
	global_load_lds_dwordx4 v[216:217], off
	s_waitcnt vmcnt(8)
	s_waitcnt lgkmcnt(0)
	s_setprio 1
	s_barrier
	v_mfma_f32_16x16x32_bf16 v[62:65], v[146:149], v[184:187], v[62:65]
	v_mfma_f32_16x16x32_bf16 v[58:61], v[160:163], v[184:187], v[58:61]
	v_mfma_f32_16x16x32_bf16 v[46:49], v[146:149], v[192:195], v[46:49]
	v_mfma_f32_16x16x32_bf16 v[42:45], v[160:163], v[192:195], v[42:45]
	v_mfma_f32_16x16x32_bf16 v[30:33], v[146:149], v[200:203], v[30:33]
	v_mfma_f32_16x16x32_bf16 v[26:29], v[160:163], v[200:203], v[26:29]
	v_mfma_f32_16x16x32_bf16 v[14:17], v[146:149], v[208:211], v[14:17]
	v_mfma_f32_16x16x32_bf16 v[10:13], v[160:163], v[208:211], v[10:13]
	s_setprio 0
	s_setprio 1
	v_mfma_f32_16x16x32_bf16 v[62:65], v[156:159], v[188:191], v[62:65]
	v_mfma_f32_16x16x32_bf16 v[58:61], v[164:167], v[188:191], v[58:61]
	v_mfma_f32_16x16x32_bf16 v[46:49], v[156:159], v[196:199], v[46:49]
	v_mfma_f32_16x16x32_bf16 v[42:45], v[164:167], v[196:199], v[42:45]
	v_mfma_f32_16x16x32_bf16 v[30:33], v[156:159], v[204:207], v[30:33]
	v_mfma_f32_16x16x32_bf16 v[26:29], v[164:167], v[204:207], v[26:29]
	v_mfma_f32_16x16x32_bf16 v[14:17], v[156:159], v[212:215], v[14:17]
	v_mfma_f32_16x16x32_bf16 v[10:13], v[164:167], v[212:215], v[10:13]
	s_setprio 0
	s_setprio 1
	v_mfma_f32_16x16x32_bf16 v[54:57], v[168:171], v[184:187], v[54:57]
	v_mfma_f32_16x16x32_bf16 v[50:53], v[176:179], v[184:187], v[50:53]
	v_mfma_f32_16x16x32_bf16 v[38:41], v[168:171], v[192:195], v[38:41]
	v_mfma_f32_16x16x32_bf16 v[34:37], v[176:179], v[192:195], v[34:37]
	v_mfma_f32_16x16x32_bf16 v[22:25], v[168:171], v[200:203], v[22:25]
	v_mfma_f32_16x16x32_bf16 v[18:21], v[176:179], v[200:203], v[18:21]
	v_mfma_f32_16x16x32_bf16 v[6:9], v[168:171], v[208:211], v[6:9]
	v_mfma_f32_16x16x32_bf16 v[2:5], v[176:179], v[208:211], v[2:5]
	s_setprio 0
	s_setprio 1
	v_mfma_f32_16x16x32_bf16 v[54:57], v[172:175], v[188:191], v[54:57]
	v_mfma_f32_16x16x32_bf16 v[50:53], v[180:183], v[188:191], v[50:53]
	v_mfma_f32_16x16x32_bf16 v[38:41], v[172:175], v[196:199], v[38:41]
	v_mfma_f32_16x16x32_bf16 v[34:37], v[180:183], v[196:199], v[34:37]
	v_mfma_f32_16x16x32_bf16 v[22:25], v[172:175], v[204:207], v[22:25]
	v_mfma_f32_16x16x32_bf16 v[18:21], v[180:183], v[204:207], v[18:21]
	v_mfma_f32_16x16x32_bf16 v[6:9], v[172:175], v[212:215], v[6:9]
	v_mfma_f32_16x16x32_bf16 v[2:5], v[180:183], v[212:215], v[2:5]
	s_barrier
	s_setprio 0
	s_add_i32 s73, s73, 2
	s_add_u32 s71, s71, 0x100
	s_addc_u32 s72, s72, 0
	s_add_u32 s44, s44, 0x100
	s_addc_u32 s45, s45, 0
	s_cmp_gt_u32 s73, 29
	s_cbranch_scc0 .LBB0_1525
	s_and_b64 vcc, exec, s[14:15]
	s_cbranch_vccz .LBB0_1528
	s_barrier

.LBB0_1681:
	ds_read_b128 v[86:89], v220
	ds_read_b128 v[90:93], v220 offset:1024
	ds_read_b128 v[114:117], v220 offset:2048
	ds_read_b128 v[118:121], v220 offset:3072
	ds_read_b128 v[146:149], v221
	ds_read_b128 v[150:153], v221 offset:1024
	ds_read_b128 v[154:157], v221 offset:2048
	ds_read_b128 v[158:161], v221 offset:3072
	s_add_u32 s10, s8, 0xfffe0080
	s_addc_u32 s11, s9, -1
	s_cmp_eq_u32 s63, 4
	s_cselect_b32 s13, s7, s11
	s_cselect_b32 s12, s14, s10
	s_cselect_b32 s11, s15, s41
	s_cselect_b32 s10, s18, s39
	v_lshl_add_u64 v[208:209], s[8:9], 0, v[180:181]
	s_add_i32 m0, s47, 0xc000
	ds_read_b128 v[162:165], v222
	ds_read_b128 v[166:169], v222 offset:1024
	ds_read_b128 v[184:187], v222 offset:2048
	ds_read_b128 v[188:191], v222 offset:3072
	ds_read_b128 v[192:195], v222 offset:4096
	ds_read_b128 v[196:199], v222 offset:5120
	ds_read_b128 v[200:203], v222 offset:6144
	ds_read_b128 v[204:207], v222 offset:7168
	global_load_lds_dwordx4 v[208:209], off
	v_lshl_add_u64 v[208:209], s[8:9], 0, v[178:179]
	s_add_i32 m0, s47, 0xe000
	s_nop 0
	global_load_lds_dwordx4 v[208:209], off
	s_waitcnt vmcnt(8)
	s_waitcnt lgkmcnt(0)
	s_setprio 1
	s_barrier
	v_mfma_f32_16x16x32_bf16 v[142:145], v[86:89], v[162:165], v[142:145]
	v_mfma_f32_16x16x32_bf16 v[138:141], v[114:117], v[162:165], v[138:141]
	v_mfma_f32_16x16x32_bf16 v[126:129], v[86:89], v[184:187], v[126:129]
	v_mfma_f32_16x16x32_bf16 v[122:125], v[114:117], v[184:187], v[122:125]
	v_mfma_f32_16x16x32_bf16 v[102:105], v[86:89], v[192:195], v[102:105]
	v_mfma_f32_16x16x32_bf16 v[98:101], v[114:117], v[192:195], v[98:101]
	v_mfma_f32_16x16x32_bf16 v[78:81], v[86:89], v[200:203], v[78:81]
	v_mfma_f32_16x16x32_bf16 v[74:77], v[114:117], v[200:203], v[74:77]
	s_setprio 0
	s_setprio 1
	v_mfma_f32_16x16x32_bf16 v[142:145], v[90:93], v[166:169], v[142:145]
	v_mfma_f32_16x16x32_bf16 v[138:141], v[118:121], v[166:169], v[138:141]
	v_mfma_f32_16x16x32_bf16 v[126:129], v[90:93], v[188:191], v[126:129]
	v_mfma_f32_16x16x32_bf16 v[122:125], v[118:121], v[188:191], v[122:125]
	v_mfma_f32_16x16x32_bf16 v[102:105], v[90:93], v[196:199], v[102:105]
	v_mfma_f32_16x16x32_bf16 v[98:101], v[118:121], v[196:199], v[98:101]
	v_mfma_f32_16x16x32_bf16 v[78:81], v[90:93], v[204:207], v[78:81]
	v_mfma_f32_16x16x32_bf16 v[74:77], v[118:121], v[204:207], v[74:77]
	s_setprio 0
	s_setprio 1
	v_mfma_f32_16x16x32_bf16 v[134:137], v[146:149], v[162:165], v[134:137]
	v_mfma_f32_16x16x32_bf16 v[130:133], v[154:157], v[162:165], v[130:133]
	v_mfma_f32_16x16x32_bf16 v[110:113], v[146:149], v[184:187], v[110:113]
	v_mfma_f32_16x16x32_bf16 v[106:109], v[154:157], v[184:187], v[106:109]
	v_mfma_f32_16x16x32_bf16 v[94:97], v[146:149], v[192:195], v[94:97]
	v_mfma_f32_16x16x32_bf16 v[82:85], v[154:157], v[192:195], v[82:85]
	v_mfma_f32_16x16x32_bf16 v[70:73], v[146:149], v[200:203], v[70:73]
	v_mfma_f32_16x16x32_bf16 v[66:69], v[154:157], v[200:203], v[66:69]
	s_setprio 0
	s_setprio 1
	v_mfma_f32_16x16x32_bf16 v[134:137], v[150:153], v[166:169], v[134:137]
	v_mfma_f32_16x16x32_bf16 v[130:133], v[158:161], v[166:169], v[130:133]
	v_mfma_f32_16x16x32_bf16 v[110:113], v[150:153], v[188:191], v[110:113]
	v_mfma_f32_16x16x32_bf16 v[106:109], v[158:161], v[188:191], v[106:109]
	v_mfma_f32_16x16x32_bf16 v[94:97], v[150:153], v[196:199], v[94:97]
	v_mfma_f32_16x16x32_bf16 v[82:85], v[158:161], v[196:199], v[82:85]
	v_mfma_f32_16x16x32_bf16 v[70:73], v[150:153], v[204:207], v[70:73]
	v_mfma_f32_16x16x32_bf16 v[66:69], v[158:161], v[204:207], v[66:69]
	s_barrier
	s_setprio 0
	s_add_i32 s64, s60, s49
	v_lshl_add_u64 v[208:209], s[10:11], 0, v[172:173]
	s_mov_b32 m0, s64
	ds_read_b128 v[162:165], v222 offset:16384
	ds_read_b128 v[166:169], v222 offset:17408
	ds_read_b128 v[184:187], v222 offset:18432
	ds_read_b128 v[188:191], v222 offset:19456
	ds_read_b128 v[192:195], v222 offset:20480
	ds_read_b128 v[196:199], v222 offset:21504
	ds_read_b128 v[200:203], v222 offset:22528
	ds_read_b128 v[204:207], v222 offset:23552
	global_load_lds_dwordx4 v[208:209], off
	s_add_i32 m0, s64, 0x2000
	s_add_u32 s64, s10, 0x20000
	v_lshl_add_u64 v[210:211], s[10:11], 0, v[176:177]
	s_addc_u32 s65, s11, 0
	s_add_i32 s66, s61, s49
	global_load_lds_dwordx4 v[210:211], off
	v_lshl_add_u64 v[212:213], s[64:65], 0, v[172:173]
	s_mov_b32 m0, s66
	v_lshl_add_u64 v[214:215], s[12:13], 0, v[174:175]
	global_load_lds_dwordx4 v[212:213], off
	v_lshl_add_u64 v[212:213], s[64:65], 0, v[176:177]
	s_add_i32 m0, s66, 0x2000
	s_nop 0
	global_load_lds_dwordx4 v[212:213], off
	v_lshl_add_u64 v[212:213], s[12:13], 0, v[170:171]
	s_mov_b32 m0, s47
	s_nop 0
	global_load_lds_dwordx4 v[212:213], off
	s_mov_b32 m0, s50
	s_nop 0
	global_load_lds_dwordx4 v[214:215], off
	s_waitcnt vmcnt(8)
	s_waitcnt lgkmcnt(0)
	s_setprio 1
	s_barrier
	v_mfma_f32_16x16x32_bf16 v[62:65], v[86:89], v[162:165], v[62:65]
	v_mfma_f32_16x16x32_bf16 v[58:61], v[114:117], v[162:165], v[58:61]
	v_mfma_f32_16x16x32_bf16 v[46:49], v[86:89], v[184:187], v[46:49]
	v_mfma_f32_16x16x32_bf16 v[42:45], v[114:117], v[184:187], v[42:45]
	v_mfma_f32_16x16x32_bf16 v[30:33], v[86:89], v[192:195], v[30:33]
	v_mfma_f32_16x16x32_bf16 v[26:29], v[114:117], v[192:195], v[26:29]
	v_mfma_f32_16x16x32_bf16 v[14:17], v[86:89], v[200:203], v[14:17]
	v_mfma_f32_16x16x32_bf16 v[10:13], v[114:117], v[200:203], v[10:13]
	s_setprio 0
	s_setprio 1
	v_mfma_f32_16x16x32_bf16 v[62:65], v[90:93], v[166:169], v[62:65]
	v_mfma_f32_16x16x32_bf16 v[58:61], v[118:121], v[166:169], v[58:61]
	v_mfma_f32_16x16x32_bf16 v[46:49], v[90:93], v[188:191], v[46:49]
	v_mfma_f32_16x16x32_bf16 v[42:45], v[118:121], v[188:191], v[42:45]
	v_mfma_f32_16x16x32_bf16 v[30:33], v[90:93], v[196:199], v[30:33]
	v_mfma_f32_16x16x32_bf16 v[26:29], v[118:121], v[196:199], v[26:29]
	v_mfma_f32_16x16x32_bf16 v[14:17], v[90:93], v[204:207], v[14:17]
	v_mfma_f32_16x16x32_bf16 v[10:13], v[118:121], v[204:207], v[10:13]
	s_setprio 0
	s_setprio 1
	v_mfma_f32_16x16x32_bf16 v[54:57], v[146:149], v[162:165], v[54:57]
	v_mfma_f32_16x16x32_bf16 v[50:53], v[154:157], v[162:165], v[50:53]
	v_mfma_f32_16x16x32_bf16 v[38:41], v[146:149], v[184:187], v[38:41]
	v_mfma_f32_16x16x32_bf16 v[34:37], v[154:157], v[184:187], v[34:37]
	v_mfma_f32_16x16x32_bf16 v[22:25], v[146:149], v[192:195], v[22:25]
	v_mfma_f32_16x16x32_bf16 v[18:21], v[154:157], v[192:195], v[18:21]
	v_mfma_f32_16x16x32_bf16 v[6:9], v[146:149], v[200:203], v[6:9]
	v_mfma_f32_16x16x32_bf16 v[2:5], v[154:157], v[200:203], v[2:5]
	s_setprio 0
	s_setprio 1
	v_mfma_f32_16x16x32_bf16 v[54:57], v[150:153], v[166:169], v[54:57]
	v_mfma_f32_16x16x32_bf16 v[50:53], v[158:161], v[166:169], v[50:53]
	v_mfma_f32_16x16x32_bf16 v[38:41], v[150:153], v[188:191], v[38:41]
	v_mfma_f32_16x16x32_bf16 v[34:37], v[158:161], v[188:191], v[34:37]
	v_mfma_f32_16x16x32_bf16 v[22:25], v[150:153], v[196:199], v[22:25]
	v_mfma_f32_16x16x32_bf16 v[18:21], v[158:161], v[196:199], v[18:21]
	v_mfma_f32_16x16x32_bf16 v[6:9], v[150:153], v[204:207], v[6:9]
	v_mfma_f32_16x16x32_bf16 v[2:5], v[158:161], v[204:207], v[2:5]
	s_barrier
	s_setprio 0
	s_add_i32 s64, 0, 0x18000
	s_add_i32 s65, 0, 0x1c000
	v_add_u32_e32 v118, s64, v219
	v_add_u32_e32 v158, s65, v219
	ds_read_b128 v[86:89], v118
	ds_read_b128 v[90:93], v118 offset:1024
	ds_read_b128 v[114:117], v118 offset:2048
	ds_read_b128 v[118:121], v118 offset:3072
	ds_read_b128 v[146:149], v158
	ds_read_b128 v[150:153], v158 offset:1024
	ds_read_b128 v[154:157], v158 offset:2048
	ds_read_b128 v[158:161], v158 offset:3072
	s_add_u32 s12, s12, 0x20000
	s_addc_u32 s13, s13, 0
	s_mov_b32 m0, s51
	v_lshl_add_u64 v[216:217], s[12:13], 0, v[170:171]
	ds_read_b128 v[162:165], v222 offset:32768
	ds_read_b128 v[166:169], v222 offset:33792
	ds_read_b128 v[184:187], v222 offset:34816
	ds_read_b128 v[188:191], v222 offset:35840
	ds_read_b128 v[192:195], v222 offset:36864
	ds_read_b128 v[196:199], v222 offset:37888
	ds_read_b128 v[200:203], v222 offset:38912
	ds_read_b128 v[204:207], v222 offset:39936
	global_load_lds_dwordx4 v[216:217], off
	v_lshl_add_u64 v[216:217], s[12:13], 0, v[174:175]
	s_mov_b32 m0, s52
	s_nop 0
	global_load_lds_dwordx4 v[216:217], off
	s_waitcnt vmcnt(8)
	s_waitcnt lgkmcnt(0)
	s_setprio 1
	s_barrier
	v_mfma_f32_16x16x32_bf16 v[142:145], v[86:89], v[162:165], v[142:145]
	v_mfma_f32_16x16x32_bf16 v[138:141], v[114:117], v[162:165], v[138:141]
	v_mfma_f32_16x16x32_bf16 v[126:129], v[86:89], v[184:187], v[126:129]
	v_mfma_f32_16x16x32_bf16 v[122:125], v[114:117], v[184:187], v[122:125]
	v_mfma_f32_16x16x32_bf16 v[102:105], v[86:89], v[192:195], v[102:105]
	v_mfma_f32_16x16x32_bf16 v[98:101], v[114:117], v[192:195], v[98:101]
	v_mfma_f32_16x16x32_bf16 v[78:81], v[86:89], v[200:203], v[78:81]
	v_mfma_f32_16x16x32_bf16 v[74:77], v[114:117], v[200:203], v[74:77]
	s_setprio 0
	s_setprio 1
	v_mfma_f32_16x16x32_bf16 v[142:145], v[90:93], v[166:169], v[142:145]
	v_mfma_f32_16x16x32_bf16 v[138:141], v[118:121], v[166:169], v[138:141]
	v_mfma_f32_16x16x32_bf16 v[126:129], v[90:93], v[188:191], v[126:129]
	v_mfma_f32_16x16x32_bf16 v[122:125], v[118:121], v[188:191], v[122:125]
	v_mfma_f32_16x16x32_bf16 v[102:105], v[90:93], v[196:199], v[102:105]
	v_mfma_f32_16x16x32_bf16 v[98:101], v[118:121], v[196:199], v[98:101]
	v_mfma_f32_16x16x32_bf16 v[78:81], v[90:93], v[204:207], v[78:81]
	v_mfma_f32_16x16x32_bf16 v[74:77], v[118:121], v[204:207], v[74:77]
	s_setprio 0
	s_setprio 1
	v_mfma_f32_16x16x32_bf16 v[134:137], v[146:149], v[162:165], v[134:137]
	v_mfma_f32_16x16x32_bf16 v[130:133], v[154:157], v[162:165], v[130:133]
	v_mfma_f32_16x16x32_bf16 v[110:113], v[146:149], v[184:187], v[110:113]
	v_mfma_f32_16x16x32_bf16 v[106:109], v[154:157], v[184:187], v[106:109]
	v_mfma_f32_16x16x32_bf16 v[94:97], v[146:149], v[192:195], v[94:97]
	v_mfma_f32_16x16x32_bf16 v[82:85], v[154:157], v[192:195], v[82:85]
	v_mfma_f32_16x16x32_bf16 v[70:73], v[146:149], v[200:203], v[70:73]
	v_mfma_f32_16x16x32_bf16 v[66:69], v[154:157], v[200:203], v[66:69]
	s_setprio 0
	s_setprio 1
	v_mfma_f32_16x16x32_bf16 v[134:137], v[150:153], v[166:169], v[134:137]
	v_mfma_f32_16x16x32_bf16 v[130:133], v[158:161], v[166:169], v[130:133]
	v_mfma_f32_16x16x32_bf16 v[110:113], v[150:153], v[188:191], v[110:113]
	v_mfma_f32_16x16x32_bf16 v[106:109], v[158:161], v[188:191], v[106:109]
	v_mfma_f32_16x16x32_bf16 v[94:97], v[150:153], v[196:199], v[94:97]
	v_mfma_f32_16x16x32_bf16 v[82:85], v[158:161], v[196:199], v[82:85]
	v_mfma_f32_16x16x32_bf16 v[70:73], v[150:153], v[204:207], v[70:73]
	v_mfma_f32_16x16x32_bf16 v[66:69], v[158:161], v[204:207], v[66:69]
	s_barrier
	s_setprio 0
	s_add_i32 s12, s64, s49
	v_lshl_add_u64 v[208:209], v[208:209], 0, s[30:31]
	s_mov_b32 m0, s12
	ds_read_b128 v[162:165], v222 offset:49152
	ds_read_b128 v[166:169], v222 offset:50176
	ds_read_b128 v[184:187], v222 offset:51200
	ds_read_b128 v[188:191], v222 offset:52224
	ds_read_b128 v[192:195], v222 offset:53248
	ds_read_b128 v[196:199], v222 offset:54272
	ds_read_b128 v[200:203], v222 offset:55296
	ds_read_b128 v[204:207], v222 offset:56320
	global_load_lds_dwordx4 v[208:209], off
	s_add_i32 m0, s12, 0x2000
	s_add_u32 s10, s10, 0x20080
	v_lshl_add_u64 v[208:209], v[210:211], 0, s[30:31]
	s_addc_u32 s11, s11, 0
	s_add_i32 s12, s65, s49
	global_load_lds_dwordx4 v[208:209], off
	v_lshl_add_u64 v[208:209], s[10:11], 0, v[172:173]
	s_mov_b32 m0, s12
	s_nop 0
	global_load_lds_dwordx4 v[208:209], off
	v_lshl_add_u64 v[208:209], s[10:11], 0, v[176:177]
	s_add_i32 m0, s12, 0x2000
	s_nop 0
	global_load_lds_dwordx4 v[208:209], off
	v_lshl_add_u64 v[208:209], v[212:213], 0, s[30:31]
	s_mov_b32 m0, s56
	s_nop 0
	global_load_lds_dwordx4 v[208:209], off
	v_lshl_add_u64 v[208:209], v[214:215], 0, s[30:31]
	s_mov_b32 m0, s57
	s_nop 0
	global_load_lds_dwordx4 v[208:209], off
	s_waitcnt vmcnt(8)
	s_waitcnt lgkmcnt(0)
	s_setprio 1
	s_barrier
	v_mfma_f32_16x16x32_bf16 v[62:65], v[86:89], v[162:165], v[62:65]
	v_mfma_f32_16x16x32_bf16 v[58:61], v[114:117], v[162:165], v[58:61]
	v_mfma_f32_16x16x32_bf16 v[46:49], v[86:89], v[184:187], v[46:49]
	v_mfma_f32_16x16x32_bf16 v[42:45], v[114:117], v[184:187], v[42:45]
	v_mfma_f32_16x16x32_bf16 v[30:33], v[86:89], v[192:195], v[30:33]
	v_mfma_f32_16x16x32_bf16 v[26:29], v[114:117], v[192:195], v[26:29]
	v_mfma_f32_16x16x32_bf16 v[14:17], v[86:89], v[200:203], v[14:17]
	v_mfma_f32_16x16x32_bf16 v[10:13], v[114:117], v[200:203], v[10:13]
	s_setprio 0
	s_setprio 1
	v_mfma_f32_16x16x32_bf16 v[62:65], v[90:93], v[166:169], v[62:65]
	v_mfma_f32_16x16x32_bf16 v[58:61], v[118:121], v[166:169], v[58:61]
	v_mfma_f32_16x16x32_bf16 v[46:49], v[90:93], v[188:191], v[46:49]
	v_mfma_f32_16x16x32_bf16 v[42:45], v[118:121], v[188:191], v[42:45]
	v_mfma_f32_16x16x32_bf16 v[30:33], v[90:93], v[196:199], v[30:33]
	v_mfma_f32_16x16x32_bf16 v[26:29], v[118:121], v[196:199], v[26:29]
	v_mfma_f32_16x16x32_bf16 v[14:17], v[90:93], v[204:207], v[14:17]
	v_mfma_f32_16x16x32_bf16 v[10:13], v[118:121], v[204:207], v[10:13]
	s_setprio 0
	s_setprio 1
	v_mfma_f32_16x16x32_bf16 v[54:57], v[146:149], v[162:165], v[54:57]
	v_mfma_f32_16x16x32_bf16 v[50:53], v[154:157], v[162:165], v[50:53]
	v_mfma_f32_16x16x32_bf16 v[38:41], v[146:149], v[184:187], v[38:41]
	v_mfma_f32_16x16x32_bf16 v[34:37], v[154:157], v[184:187], v[34:37]
	v_mfma_f32_16x16x32_bf16 v[22:25], v[146:149], v[192:195], v[22:25]
	v_mfma_f32_16x16x32_bf16 v[18:21], v[154:157], v[192:195], v[18:21]
	v_mfma_f32_16x16x32_bf16 v[6:9], v[146:149], v[200:203], v[6:9]
	v_mfma_f32_16x16x32_bf16 v[2:5], v[154:157], v[200:203], v[2:5]
	s_setprio 0
	s_setprio 1
	v_mfma_f32_16x16x32_bf16 v[54:57], v[150:153], v[166:169], v[54:57]
	v_mfma_f32_16x16x32_bf16 v[50:53], v[158:161], v[166:169], v[50:53]
	v_mfma_f32_16x16x32_bf16 v[38:41], v[150:153], v[188:191], v[38:41]
	v_mfma_f32_16x16x32_bf16 v[34:37], v[158:161], v[188:191], v[34:37]
	v_mfma_f32_16x16x32_bf16 v[22:25], v[150:153], v[196:199], v[22:25]
	v_mfma_f32_16x16x32_bf16 v[18:21], v[158:161], v[196:199], v[18:21]
	v_mfma_f32_16x16x32_bf16 v[6:9], v[150:153], v[204:207], v[6:9]
	v_mfma_f32_16x16x32_bf16 v[2:5], v[158:161], v[204:207], v[2:5]
	s_barrier
	s_setprio 0
	s_add_i32 s63, s63, 2
	s_add_u32 s39, s39, 0x100
	s_addc_u32 s41, s41, 0
	s_add_u32 s8, s8, 0x100
	s_addc_u32 s9, s9, 0
	s_cmp_gt_u32 s63, 5
	s_cbranch_scc0 .LBB0_1681
	s_and_b64 vcc, exec, s[36:37]
	s_cbranch_vccz .LBB0_1684
	s_barrier

.LBB0_1706:
	s_lshl_b32 s10, s10, 5
	s_add_i32 s25, 0, 0x18000
	s_lshl_b32 s9, s11, 6
	s_and_b32 s10, s10, 0x60
	s_lshl_b32 s24, s11, 13
	s_add_i32 s11, s25, s22
	s_mov_b64 s[18:19], 0x80
	s_lshl_b32 s23, s10, 7
	v_lshl_add_u64 v[32:33], v[18:19], 0, s[18:19]
	s_mov_b32 m0, s11
	s_add_i32 s13, s11, 0x2000
	s_add_i32 s12, s20, 0x8000
	s_add_i32 s14, s20, 0xa000
	s_waitcnt vmcnt(2)
	s_barrier
	global_load_lds_dwordx4 v[32:33], off
	v_lshl_add_u64 v[38:39], v[20:21], 0, s[18:19]
	s_mov_b32 m0, s13
	s_add_u32 s4, s4, 0x20080
	global_load_lds_dwordx4 v[38:39], off
	v_lshl_add_u64 v[30:31], v[12:13], 0, s[18:19]
	s_mov_b32 m0, s12
	s_addc_u32 s5, s5, 0
	s_add_i32 s26, 0, 0x1c000
	global_load_lds_dwordx4 v[30:31], off
	v_lshl_add_u64 v[40:41], v[14:15], 0, s[18:19]
	s_mov_b32 m0, s14
	s_add_i32 s18, s26, s22
	global_load_lds_dwordx4 v[40:41], off
	v_lshl_add_u64 v[240:241], s[4:5], 0, v[22:23]
	s_mov_b32 m0, s18
	s_add_i32 s19, s18, 0x2000
	global_load_lds_dwordx4 v[240:241], off
	v_lshl_add_u64 v[242:243], s[4:5], 0, v[24:25]
	s_mov_b32 m0, s19
	v_bfe_u32 v1, v26, 4, 2
	global_load_lds_dwordx4 v[242:243], off
	v_and_b32_e32 v130, 15, v26
	v_lshlrev_b32_e32 v22, 4, v1
	v_lshlrev_b32_e32 v23, 2, v26
	v_lshl_or_b32 v22, v130, 6, v22
	v_and_b32_e32 v23, 32, v23
	v_bitop3_b32 v24, v22, s23, v23 bitop3:0xde
	v_bitop3_b32 v22, v22, s24, v23 bitop3:0xde
	s_add_i32 s23, 0, 0x10000
	s_add_i32 s24, 0, 0x14000
	v_add_u32_e32 v42, s23, v24
	v_add_u32_e32 v58, s24, v24
	s_waitcnt vmcnt(6)
	s_barrier
	v_add_u32_e32 v131, 0, v22
	v_add_u32_e32 v204, s25, v24
	v_add_u32_e32 v220, s26, v24
	ds_read_b128 v[22:25], v42
	ds_read_b128 v[26:29], v42 offset:1024
	ds_read_b128 v[34:37], v42 offset:2048
	ds_read_b128 v[42:45], v42 offset:3072
	ds_read_b128 v[46:49], v58
	ds_read_b128 v[50:53], v58 offset:1024
	ds_read_b128 v[54:57], v58 offset:2048
	ds_read_b128 v[58:61], v58 offset:3072
	s_add_u32 s6, s6, 0x20080
	s_addc_u32 s7, s7, 0
	s_add_i32 s23, s23, s22
	s_add_i32 s22, s24, s22
	s_mov_b32 s4, 0x8000
	s_mov_b32 s5, 0xc000
	s_add_i32 m0, s20, 0xc000
	s_add_i32 s25, s20, 0xe000
	s_add_i32 s26, s23, 0x2000
	s_add_i32 s24, s22, 0x2000
	s_cmpk_gt_u32 s17, 0xff
	v_lshl_add_u64 v[6:7], s[6:7], 0, v[6:7]
	ds_read_b128 v[62:65], v131
	ds_read_b128 v[66:69], v131 offset:1024
	ds_read_b128 v[70:73], v131 offset:2048
	ds_read_b128 v[74:77], v131 offset:3072
	ds_read_b128 v[78:81], v131 offset:4096
	ds_read_b128 v[82:85], v131 offset:5120
	ds_read_b128 v[86:89], v131 offset:6144
	ds_read_b128 v[90:93], v131 offset:7168
	global_load_lds_dwordx4 v[6:7], off
	v_lshl_add_u64 v[6:7], s[6:7], 0, v[8:9]
	s_mov_b32 m0, s25
	s_nop 0
	global_load_lds_dwordx4 v[6:7], off
	s_waitcnt vmcnt(8)
	s_waitcnt lgkmcnt(0)
	s_setprio 1
	s_barrier
	v_mfma_f32_16x16x32_bf16 v[6:9], v[22:25], v[62:65], 0
	v_mfma_f32_16x16x32_bf16 v[94:97], v[34:37], v[62:65], 0
	v_mfma_f32_16x16x32_bf16 v[98:101], v[22:25], v[70:73], 0
	v_mfma_f32_16x16x32_bf16 v[102:105], v[34:37], v[70:73], 0
	v_mfma_f32_16x16x32_bf16 v[106:109], v[22:25], v[78:81], 0
	v_mfma_f32_16x16x32_bf16 v[110:113], v[34:37], v[78:81], 0
	v_mfma_f32_16x16x32_bf16 v[114:117], v[22:25], v[86:89], 0
	v_mfma_f32_16x16x32_bf16 v[118:121], v[34:37], v[86:89], 0
	s_setprio 0
	s_setprio 1
	v_mfma_f32_16x16x32_bf16 v[6:9], v[26:29], v[66:69], v[6:9]
	v_mfma_f32_16x16x32_bf16 v[94:97], v[42:45], v[66:69], v[94:97]
	v_mfma_f32_16x16x32_bf16 v[98:101], v[26:29], v[74:77], v[98:101]
	v_mfma_f32_16x16x32_bf16 v[102:105], v[42:45], v[74:77], v[102:105]
	v_mfma_f32_16x16x32_bf16 v[106:109], v[26:29], v[82:85], v[106:109]
	v_mfma_f32_16x16x32_bf16 v[110:113], v[42:45], v[82:85], v[110:113]
	v_mfma_f32_16x16x32_bf16 v[114:117], v[26:29], v[90:93], v[114:117]
	v_mfma_f32_16x16x32_bf16 v[118:121], v[42:45], v[90:93], v[118:121]
	s_setprio 0
	s_setprio 1
	v_mfma_f32_16x16x32_bf16 v[122:125], v[46:49], v[62:65], 0
	v_mfma_f32_16x16x32_bf16 v[62:65], v[54:57], v[62:65], 0
	v_mfma_f32_16x16x32_bf16 v[122:125], v[50:53], v[66:69], v[122:125]
	v_mfma_f32_16x16x32_bf16 v[62:65], v[58:61], v[66:69], v[62:65]
	v_mfma_f32_16x16x32_bf16 v[66:69], v[46:49], v[70:73], 0
	v_mfma_f32_16x16x32_bf16 v[70:73], v[54:57], v[70:73], 0
	v_mfma_f32_16x16x32_bf16 v[66:69], v[50:53], v[74:77], v[66:69]
	v_mfma_f32_16x16x32_bf16 v[70:73], v[58:61], v[74:77], v[70:73]
	s_setprio 0
	s_setprio 1
	v_mfma_f32_16x16x32_bf16 v[74:77], v[46:49], v[78:81], 0
	v_mfma_f32_16x16x32_bf16 v[78:81], v[54:57], v[78:81], 0
	v_mfma_f32_16x16x32_bf16 v[74:77], v[50:53], v[82:85], v[74:77]
	v_mfma_f32_16x16x32_bf16 v[78:81], v[58:61], v[82:85], v[78:81]
	v_mfma_f32_16x16x32_bf16 v[82:85], v[46:49], v[86:89], 0
	v_mfma_f32_16x16x32_bf16 v[86:89], v[54:57], v[86:89], 0
	v_mfma_f32_16x16x32_bf16 v[82:85], v[50:53], v[90:93], v[82:85]
	v_mfma_f32_16x16x32_bf16 v[86:89], v[58:61], v[90:93], v[86:89]
	s_barrier
	s_setprio 0
	s_mov_b32 m0, s23
	ds_read_b128 v[90:93], v131 offset:16384
	ds_read_b128 v[126:129], v131 offset:17408
	ds_read_b128 v[132:135], v131 offset:18432
	ds_read_b128 v[136:139], v131 offset:19456
	ds_read_b128 v[140:143], v131 offset:20480
	ds_read_b128 v[144:147], v131 offset:21504
	ds_read_b128 v[148:151], v131 offset:22528
	ds_read_b128 v[152:155], v131 offset:23552
	global_load_lds_dwordx4 v[18:19], off
	s_mov_b32 m0, s26
	s_nop 0
	global_load_lds_dwordx4 v[20:21], off
	s_mov_b32 m0, s22
	s_nop 0
	global_load_lds_dwordx4 v[16:17], off
	s_mov_b32 m0, s24
	s_nop 0
	global_load_lds_dwordx4 v[10:11], off
	s_mov_b32 m0, s20
	s_nop 0
	global_load_lds_dwordx4 v[12:13], off
	s_mov_b32 m0, s21
	s_nop 0
	global_load_lds_dwordx4 v[14:15], off
	s_waitcnt vmcnt(8)
	s_waitcnt lgkmcnt(0)
	s_setprio 1
	s_barrier
	v_mfma_f32_16x16x32_bf16 v[10:13], v[22:25], v[90:93], 0
	v_mfma_f32_16x16x32_bf16 v[156:159], v[26:29], v[126:129], v[10:13]
	v_mfma_f32_16x16x32_bf16 v[10:13], v[34:37], v[90:93], 0
	v_mfma_f32_16x16x32_bf16 v[160:163], v[42:45], v[126:129], v[10:13]
	v_mfma_f32_16x16x32_bf16 v[10:13], v[22:25], v[132:135], 0
	v_mfma_f32_16x16x32_bf16 v[164:167], v[26:29], v[136:139], v[10:13]
	v_mfma_f32_16x16x32_bf16 v[10:13], v[34:37], v[132:135], 0
	v_mfma_f32_16x16x32_bf16 v[168:171], v[42:45], v[136:139], v[10:13]
	s_setprio 0
	s_setprio 1
	v_mfma_f32_16x16x32_bf16 v[10:13], v[22:25], v[140:143], 0
	v_mfma_f32_16x16x32_bf16 v[172:175], v[26:29], v[144:147], v[10:13]
	v_mfma_f32_16x16x32_bf16 v[10:13], v[34:37], v[140:143], 0
	v_mfma_f32_16x16x32_bf16 v[176:179], v[42:45], v[144:147], v[10:13]
	v_mfma_f32_16x16x32_bf16 v[10:13], v[22:25], v[148:151], 0
	v_mfma_f32_16x16x32_bf16 v[180:183], v[26:29], v[152:155], v[10:13]
	v_mfma_f32_16x16x32_bf16 v[10:13], v[34:37], v[148:151], 0
	v_mfma_f32_16x16x32_bf16 v[184:187], v[42:45], v[152:155], v[10:13]
	s_setprio 0
	s_setprio 1
	v_mfma_f32_16x16x32_bf16 v[10:13], v[46:49], v[90:93], 0
	v_mfma_f32_16x16x32_bf16 v[188:191], v[50:53], v[126:129], v[10:13]
	v_mfma_f32_16x16x32_bf16 v[10:13], v[54:57], v[90:93], 0
	v_mfma_f32_16x16x32_bf16 v[126:129], v[58:61], v[126:129], v[10:13]
	v_mfma_f32_16x16x32_bf16 v[10:13], v[46:49], v[132:135], 0
	v_mfma_f32_16x16x32_bf16 v[192:195], v[50:53], v[136:139], v[10:13]
	v_mfma_f32_16x16x32_bf16 v[10:13], v[54:57], v[132:135], 0
	v_mfma_f32_16x16x32_bf16 v[132:135], v[58:61], v[136:139], v[10:13]
	s_setprio 0
	s_setprio 1
	v_mfma_f32_16x16x32_bf16 v[10:13], v[46:49], v[140:143], 0
	v_mfma_f32_16x16x32_bf16 v[136:139], v[50:53], v[144:147], v[10:13]
	v_mfma_f32_16x16x32_bf16 v[10:13], v[54:57], v[140:143], 0
	v_mfma_f32_16x16x32_bf16 v[140:143], v[58:61], v[144:147], v[10:13]
	v_mfma_f32_16x16x32_bf16 v[10:13], v[46:49], v[148:151], 0
	v_mfma_f32_16x16x32_bf16 v[144:147], v[50:53], v[152:155], v[10:13]
	v_mfma_f32_16x16x32_bf16 v[10:13], v[54:57], v[148:151], 0
	v_mfma_f32_16x16x32_bf16 v[148:151], v[58:61], v[152:155], v[10:13]
	s_barrier
	s_setprio 0
	ds_read_b128 v[152:155], v204
	ds_read_b128 v[196:199], v204 offset:1024
	ds_read_b128 v[200:203], v204 offset:2048
	ds_read_b128 v[204:207], v204 offset:3072
	ds_read_b128 v[208:211], v220
	ds_read_b128 v[212:215], v220 offset:1024
	ds_read_b128 v[216:219], v220 offset:2048
	ds_read_b128 v[220:223], v220 offset:3072
	s_mov_b32 m0, s15
	ds_read_b128 v[26:29], v131 offset:32768
	ds_read_b128 v[34:37], v131 offset:33792
	ds_read_b128 v[50:53], v131 offset:34816
	ds_read_b128 v[54:57], v131 offset:35840
	ds_read_b128 v[58:61], v131 offset:36864
	ds_read_b128 v[224:227], v131 offset:37888
	ds_read_b128 v[228:231], v131 offset:38912
	ds_read_b128 v[232:235], v131 offset:39936
	global_load_lds_dwordx4 v[2:3], off
	s_mov_b32 m0, s16
	s_nop 0
	global_load_lds_dwordx4 v[4:5], off
	s_waitcnt vmcnt(8)
	s_waitcnt lgkmcnt(0)
	s_setprio 1
	s_barrier
	v_mfma_f32_16x16x32_bf16 v[2:5], v[152:155], v[26:29], v[6:9]
	v_mfma_f32_16x16x32_bf16 v[42:45], v[196:199], v[34:37], v[2:5]
	v_mfma_f32_16x16x32_bf16 v[2:5], v[200:203], v[26:29], v[94:97]
	v_mfma_f32_16x16x32_bf16 v[46:49], v[204:207], v[34:37], v[2:5]
	v_mfma_f32_16x16x32_bf16 v[2:5], v[152:155], v[50:53], v[98:101]
	v_mfma_f32_16x16x32_bf16 v[18:21], v[196:199], v[54:57], v[2:5]
	v_mfma_f32_16x16x32_bf16 v[2:5], v[200:203], v[50:53], v[102:105]
	v_mfma_f32_16x16x32_bf16 v[22:25], v[204:207], v[54:57], v[2:5]
	s_setprio 0
	s_setprio 1
	v_mfma_f32_16x16x32_bf16 v[2:5], v[152:155], v[58:61], v[106:109]
	v_mfma_f32_16x16x32_bf16 v[10:13], v[196:199], v[224:227], v[2:5]
	v_mfma_f32_16x16x32_bf16 v[2:5], v[200:203], v[58:61], v[110:113]
	v_mfma_f32_16x16x32_bf16 v[14:17], v[204:207], v[224:227], v[2:5]
	v_mfma_f32_16x16x32_bf16 v[2:5], v[152:155], v[228:231], v[114:117]
	v_mfma_f32_16x16x32_bf16 v[6:9], v[200:203], v[228:231], v[118:121]
	v_mfma_f32_16x16x32_bf16 v[2:5], v[196:199], v[232:235], v[2:5]
	v_mfma_f32_16x16x32_bf16 v[6:9], v[204:207], v[232:235], v[6:9]
	s_setprio 0
	s_setprio 1
	v_mfma_f32_16x16x32_bf16 v[90:93], v[208:211], v[26:29], v[122:125]
	v_mfma_f32_16x16x32_bf16 v[26:29], v[216:219], v[26:29], v[62:65]
	v_mfma_f32_16x16x32_bf16 v[94:97], v[220:223], v[34:37], v[26:29]
	v_mfma_f32_16x16x32_bf16 v[26:29], v[208:211], v[50:53], v[66:69]
	v_mfma_f32_16x16x32_bf16 v[66:69], v[212:215], v[54:57], v[26:29]
	v_mfma_f32_16x16x32_bf16 v[26:29], v[216:219], v[50:53], v[70:73]
	v_mfma_f32_16x16x32_bf16 v[70:73], v[220:223], v[54:57], v[26:29]
	v_mfma_f32_16x16x32_bf16 v[26:29], v[208:211], v[58:61], v[74:77]
	s_setprio 0
	s_setprio 1
	v_mfma_f32_16x16x32_bf16 v[50:53], v[212:215], v[224:227], v[26:29]
	v_mfma_f32_16x16x32_bf16 v[26:29], v[216:219], v[58:61], v[78:81]
	v_mfma_f32_16x16x32_bf16 v[90:93], v[212:215], v[34:37], v[90:93]
	v_mfma_f32_16x16x32_bf16 v[54:57], v[220:223], v[224:227], v[26:29]
	v_mfma_f32_16x16x32_bf16 v[26:29], v[208:211], v[228:231], v[82:85]
	v_mfma_f32_16x16x32_bf16 v[34:37], v[216:219], v[228:231], v[86:89]
	v_mfma_f32_16x16x32_bf16 v[26:29], v[212:215], v[232:235], v[26:29]
	v_mfma_f32_16x16x32_bf16 v[34:37], v[220:223], v[232:235], v[34:37]
	s_barrier
	s_setprio 0
	s_mov_b32 m0, s11
	ds_read_b128 v[82:85], v131 offset:49152
	ds_read_b128 v[86:89], v131 offset:50176
	ds_read_b128 v[106:109], v131 offset:51200
	ds_read_b128 v[110:113], v131 offset:52224
	ds_read_b128 v[224:227], v131 offset:53248
	ds_read_b128 v[228:231], v131 offset:54272
	ds_read_b128 v[232:235], v131 offset:55296
	ds_read_b128 v[236:239], v131 offset:56320
	global_load_lds_dwordx4 v[32:33], off
	s_mov_b32 m0, s13
	s_nop 0
	global_load_lds_dwordx4 v[38:39], off
	s_mov_b32 m0, s18
	s_nop 0
	global_load_lds_dwordx4 v[240:241], off
	s_mov_b32 m0, s19
	s_nop 0
	global_load_lds_dwordx4 v[242:243], off
	s_mov_b32 m0, s12
	s_nop 0
	global_load_lds_dwordx4 v[30:31], off
	s_mov_b32 m0, s14
	s_nop 0
	global_load_lds_dwordx4 v[40:41], off
	s_waitcnt vmcnt(8)
	s_waitcnt lgkmcnt(0)
	s_setprio 1
	s_barrier
	v_mfma_f32_16x16x32_bf16 v[30:33], v[152:155], v[82:85], v[156:159]
	v_mfma_f32_16x16x32_bf16 v[98:101], v[196:199], v[86:89], v[30:33]
	v_mfma_f32_16x16x32_bf16 v[30:33], v[200:203], v[82:85], v[160:163]
	v_mfma_f32_16x16x32_bf16 v[102:105], v[204:207], v[86:89], v[30:33]
	v_mfma_f32_16x16x32_bf16 v[30:33], v[152:155], v[106:109], v[164:167]
	v_mfma_f32_16x16x32_bf16 v[74:77], v[196:199], v[110:113], v[30:33]
	v_mfma_f32_16x16x32_bf16 v[30:33], v[200:203], v[106:109], v[168:171]
	v_mfma_f32_16x16x32_bf16 v[78:81], v[204:207], v[110:113], v[30:33]
	s_setprio 0
	s_setprio 1
	v_mfma_f32_16x16x32_bf16 v[30:33], v[152:155], v[224:227], v[172:175]
	v_mfma_f32_16x16x32_bf16 v[58:61], v[196:199], v[228:231], v[30:33]
	v_mfma_f32_16x16x32_bf16 v[30:33], v[200:203], v[224:227], v[176:179]
	v_mfma_f32_16x16x32_bf16 v[62:65], v[204:207], v[228:231], v[30:33]
	v_mfma_f32_16x16x32_bf16 v[30:33], v[152:155], v[232:235], v[180:183]
	v_mfma_f32_16x16x32_bf16 v[38:41], v[200:203], v[232:235], v[184:187]
	v_mfma_f32_16x16x32_bf16 v[30:33], v[196:199], v[236:239], v[30:33]
	v_mfma_f32_16x16x32_bf16 v[38:41], v[204:207], v[236:239], v[38:41]
	s_setprio 0
	s_setprio 1
	v_mfma_f32_16x16x32_bf16 v[114:117], v[208:211], v[82:85], v[188:191]
	v_mfma_f32_16x16x32_bf16 v[82:85], v[216:219], v[82:85], v[126:129]
	v_mfma_f32_16x16x32_bf16 v[126:129], v[220:223], v[86:89], v[82:85]
	v_mfma_f32_16x16x32_bf16 v[82:85], v[208:211], v[106:109], v[192:195]
	v_mfma_f32_16x16x32_bf16 v[122:125], v[212:215], v[86:89], v[114:117]
	v_mfma_f32_16x16x32_bf16 v[114:117], v[212:215], v[110:113], v[82:85]
	v_mfma_f32_16x16x32_bf16 v[82:85], v[216:219], v[106:109], v[132:135]
	v_mfma_f32_16x16x32_bf16 v[118:121], v[220:223], v[110:113], v[82:85]
	s_setprio 0
	s_setprio 1
	v_mfma_f32_16x16x32_bf16 v[82:85], v[208:211], v[224:227], v[136:139]
	v_mfma_f32_16x16x32_bf16 v[106:109], v[212:215], v[228:231], v[82:85]
	v_mfma_f32_16x16x32_bf16 v[82:85], v[216:219], v[224:227], v[140:143]
	v_mfma_f32_16x16x32_bf16 v[110:113], v[220:223], v[228:231], v[82:85]
	v_mfma_f32_16x16x32_bf16 v[82:85], v[208:211], v[232:235], v[144:147]
	v_mfma_f32_16x16x32_bf16 v[86:89], v[216:219], v[232:235], v[148:151]
	v_mfma_f32_16x16x32_bf16 v[82:85], v[212:215], v[236:239], v[82:85]
	v_mfma_f32_16x16x32_bf16 v[86:89], v[220:223], v[236:239], v[86:89]
	s_barrier
	s_setprio 0
	s_cbranch_scc1 .LBB0_1708
	s_barrier

.LBB0_1840:
	ds_read_b128 v[146:149], v152
	ds_read_b128 v[156:159], v152 offset:1024
	ds_read_b128 v[160:163], v152 offset:2048
	ds_read_b128 v[164:167], v152 offset:3072
	ds_read_b128 v[168:171], v153
	ds_read_b128 v[172:175], v153 offset:1024
	ds_read_b128 v[176:179], v153 offset:2048
	ds_read_b128 v[180:183], v153 offset:3072
	s_add_u32 s28, s26, 0xfff80080
	s_addc_u32 s29, s27, -1
	s_cmp_eq_u32 s54, 28
	s_cselect_b32 s31, s19, s29
	s_cselect_b32 s30, s50, s28
	s_cselect_b32 s29, s17, s53
	s_cselect_b32 s28, s51, s52
	v_lshl_add_u64 v[216:217], s[26:27], 0, v[140:141]
	s_add_i32 m0, s25, 0xc000
	ds_read_b128 v[184:187], v154
	ds_read_b128 v[188:191], v154 offset:1024
	ds_read_b128 v[192:195], v154 offset:2048
	ds_read_b128 v[196:199], v154 offset:3072
	ds_read_b128 v[200:203], v154 offset:4096
	ds_read_b128 v[204:207], v154 offset:5120
	ds_read_b128 v[208:211], v154 offset:6144
	ds_read_b128 v[212:215], v154 offset:7168
	global_load_lds_dwordx4 v[216:217], off
	v_lshl_add_u64 v[216:217], s[26:27], 0, v[138:139]
	s_add_i32 m0, s25, 0xe000
	s_nop 0
	global_load_lds_dwordx4 v[216:217], off
	s_waitcnt vmcnt(8)
	s_waitcnt lgkmcnt(0)
	s_setprio 1
	s_barrier
	v_mfma_f32_16x16x32_bf16 v[122:125], v[146:149], v[184:187], v[122:125]
	v_mfma_f32_16x16x32_bf16 v[118:121], v[160:163], v[184:187], v[118:121]
	v_mfma_f32_16x16x32_bf16 v[106:109], v[146:149], v[192:195], v[106:109]
	v_mfma_f32_16x16x32_bf16 v[102:105], v[160:163], v[192:195], v[102:105]
	v_mfma_f32_16x16x32_bf16 v[90:93], v[146:149], v[200:203], v[90:93]
	v_mfma_f32_16x16x32_bf16 v[86:89], v[160:163], v[200:203], v[86:89]
	v_mfma_f32_16x16x32_bf16 v[74:77], v[146:149], v[208:211], v[74:77]
	v_mfma_f32_16x16x32_bf16 v[70:73], v[160:163], v[208:211], v[70:73]
	s_setprio 0
	s_setprio 1
	v_mfma_f32_16x16x32_bf16 v[122:125], v[156:159], v[188:191], v[122:125]
	v_mfma_f32_16x16x32_bf16 v[118:121], v[164:167], v[188:191], v[118:121]
	v_mfma_f32_16x16x32_bf16 v[106:109], v[156:159], v[196:199], v[106:109]
	v_mfma_f32_16x16x32_bf16 v[102:105], v[164:167], v[196:199], v[102:105]
	v_mfma_f32_16x16x32_bf16 v[90:93], v[156:159], v[204:207], v[90:93]
	v_mfma_f32_16x16x32_bf16 v[86:89], v[164:167], v[204:207], v[86:89]
	v_mfma_f32_16x16x32_bf16 v[74:77], v[156:159], v[212:215], v[74:77]
	v_mfma_f32_16x16x32_bf16 v[70:73], v[164:167], v[212:215], v[70:73]
	s_setprio 0
	s_setprio 1
	v_mfma_f32_16x16x32_bf16 v[126:129], v[168:171], v[184:187], v[126:129]
	v_mfma_f32_16x16x32_bf16 v[114:117], v[176:179], v[184:187], v[114:117]
	v_mfma_f32_16x16x32_bf16 v[110:113], v[168:171], v[192:195], v[110:113]
	v_mfma_f32_16x16x32_bf16 v[98:101], v[176:179], v[192:195], v[98:101]
	v_mfma_f32_16x16x32_bf16 v[94:97], v[168:171], v[200:203], v[94:97]
	v_mfma_f32_16x16x32_bf16 v[82:85], v[176:179], v[200:203], v[82:85]
	v_mfma_f32_16x16x32_bf16 v[78:81], v[168:171], v[208:211], v[78:81]
	v_mfma_f32_16x16x32_bf16 v[66:69], v[176:179], v[208:211], v[66:69]
	s_setprio 0
	s_setprio 1
	v_mfma_f32_16x16x32_bf16 v[126:129], v[172:175], v[188:191], v[126:129]
	v_mfma_f32_16x16x32_bf16 v[114:117], v[180:183], v[188:191], v[114:117]
	v_mfma_f32_16x16x32_bf16 v[110:113], v[172:175], v[196:199], v[110:113]
	v_mfma_f32_16x16x32_bf16 v[98:101], v[180:183], v[196:199], v[98:101]
	v_mfma_f32_16x16x32_bf16 v[94:97], v[172:175], v[204:207], v[94:97]
	v_mfma_f32_16x16x32_bf16 v[82:85], v[180:183], v[204:207], v[82:85]
	v_mfma_f32_16x16x32_bf16 v[78:81], v[172:175], v[212:215], v[78:81]
	v_mfma_f32_16x16x32_bf16 v[66:69], v[180:183], v[212:215], v[66:69]
	s_barrier
	s_setprio 0
	s_add_i32 s55, s46, s34
	v_lshl_add_u64 v[216:217], s[28:29], 0, v[134:135]
	s_mov_b32 m0, s55
	ds_read_b128 v[184:187], v154 offset:16384
	ds_read_b128 v[188:191], v154 offset:17408
	ds_read_b128 v[192:195], v154 offset:18432
	ds_read_b128 v[196:199], v154 offset:19456
	ds_read_b128 v[200:203], v154 offset:20480
	ds_read_b128 v[204:207], v154 offset:21504
	ds_read_b128 v[208:211], v154 offset:22528
	ds_read_b128 v[212:215], v154 offset:23552
	global_load_lds_dwordx4 v[216:217], off
	s_add_i32 m0, s55, 0x2000
	s_add_u32 s56, s28, 0x80000
	v_lshl_add_u64 v[218:219], s[28:29], 0, v[130:131]
	s_addc_u32 s57, s29, 0
	s_add_i32 s55, s47, s34
	global_load_lds_dwordx4 v[218:219], off
	v_lshl_add_u64 v[220:221], s[56:57], 0, v[134:135]
	s_mov_b32 m0, s55
	v_lshl_add_u64 v[222:223], s[30:31], 0, v[132:133]
	global_load_lds_dwordx4 v[220:221], off
	v_lshl_add_u64 v[220:221], s[56:57], 0, v[130:131]
	s_add_i32 m0, s55, 0x2000
	s_nop 0
	global_load_lds_dwordx4 v[220:221], off
	v_lshl_add_u64 v[220:221], s[30:31], 0, v[136:137]
	s_mov_b32 m0, s25
	s_nop 0
	global_load_lds_dwordx4 v[220:221], off
	s_mov_b32 m0, s37
	s_nop 0
	global_load_lds_dwordx4 v[222:223], off
	s_waitcnt vmcnt(8)
	s_waitcnt lgkmcnt(0)
	s_setprio 1
	s_barrier
	v_mfma_f32_16x16x32_bf16 v[58:61], v[146:149], v[184:187], v[58:61]
	v_mfma_f32_16x16x32_bf16 v[54:57], v[160:163], v[184:187], v[54:57]
	v_mfma_f32_16x16x32_bf16 v[42:45], v[146:149], v[192:195], v[42:45]
	v_mfma_f32_16x16x32_bf16 v[38:41], v[160:163], v[192:195], v[38:41]
	v_mfma_f32_16x16x32_bf16 v[26:29], v[146:149], v[200:203], v[26:29]
	v_mfma_f32_16x16x32_bf16 v[22:25], v[160:163], v[200:203], v[22:25]
	v_mfma_f32_16x16x32_bf16 v[10:13], v[146:149], v[208:211], v[10:13]
	v_mfma_f32_16x16x32_bf16 v[6:9], v[160:163], v[208:211], v[6:9]
	s_setprio 0
	s_setprio 1
	v_mfma_f32_16x16x32_bf16 v[58:61], v[156:159], v[188:191], v[58:61]
	v_mfma_f32_16x16x32_bf16 v[54:57], v[164:167], v[188:191], v[54:57]
	v_mfma_f32_16x16x32_bf16 v[42:45], v[156:159], v[196:199], v[42:45]
	v_mfma_f32_16x16x32_bf16 v[38:41], v[164:167], v[196:199], v[38:41]
	v_mfma_f32_16x16x32_bf16 v[26:29], v[156:159], v[204:207], v[26:29]
	v_mfma_f32_16x16x32_bf16 v[22:25], v[164:167], v[204:207], v[22:25]
	v_mfma_f32_16x16x32_bf16 v[10:13], v[156:159], v[212:215], v[10:13]
	v_mfma_f32_16x16x32_bf16 v[6:9], v[164:167], v[212:215], v[6:9]
	s_setprio 0
	s_setprio 1
	v_mfma_f32_16x16x32_bf16 v[62:65], v[168:171], v[184:187], v[62:65]
	v_mfma_f32_16x16x32_bf16 v[50:53], v[176:179], v[184:187], v[50:53]
	v_mfma_f32_16x16x32_bf16 v[46:49], v[168:171], v[192:195], v[46:49]
	v_mfma_f32_16x16x32_bf16 v[34:37], v[176:179], v[192:195], v[34:37]
	v_mfma_f32_16x16x32_bf16 v[30:33], v[168:171], v[200:203], v[30:33]
	v_mfma_f32_16x16x32_bf16 v[18:21], v[176:179], v[200:203], v[18:21]
	v_mfma_f32_16x16x32_bf16 v[14:17], v[168:171], v[208:211], v[14:17]
	v_mfma_f32_16x16x32_bf16 v[2:5], v[176:179], v[208:211], v[2:5]
	s_setprio 0
	s_setprio 1
	v_mfma_f32_16x16x32_bf16 v[62:65], v[172:175], v[188:191], v[62:65]
	v_mfma_f32_16x16x32_bf16 v[50:53], v[180:183], v[188:191], v[50:53]
	v_mfma_f32_16x16x32_bf16 v[46:49], v[172:175], v[196:199], v[46:49]
	v_mfma_f32_16x16x32_bf16 v[34:37], v[180:183], v[196:199], v[34:37]
	v_mfma_f32_16x16x32_bf16 v[30:33], v[172:175], v[204:207], v[30:33]
	v_mfma_f32_16x16x32_bf16 v[18:21], v[180:183], v[204:207], v[18:21]
	v_mfma_f32_16x16x32_bf16 v[14:17], v[172:175], v[212:215], v[14:17]
	v_mfma_f32_16x16x32_bf16 v[2:5], v[180:183], v[212:215], v[2:5]
	s_barrier
	s_setprio 0
	s_add_i32 s55, 0, 0x18000
	v_add_u32_e32 v155, s55, v151
	s_add_i32 s56, 0, 0x1c000
	ds_read_b128 v[146:149], v155
	ds_read_b128 v[156:159], v155 offset:1024
	ds_read_b128 v[160:163], v155 offset:2048
	ds_read_b128 v[164:167], v155 offset:3072
	v_add_u32_e32 v155, s56, v151
	ds_read_b128 v[168:171], v155
	ds_read_b128 v[172:175], v155 offset:1024
	ds_read_b128 v[176:179], v155 offset:2048
	ds_read_b128 v[180:183], v155 offset:3072
	s_add_u32 s30, s30, 0x80000
	s_addc_u32 s31, s31, 0
	s_mov_b32 m0, s38
	v_lshl_add_u64 v[224:225], s[30:31], 0, v[136:137]
	ds_read_b128 v[184:187], v154 offset:32768
	ds_read_b128 v[188:191], v154 offset:33792
	ds_read_b128 v[192:195], v154 offset:34816
	ds_read_b128 v[196:199], v154 offset:35840
	ds_read_b128 v[200:203], v154 offset:36864
	ds_read_b128 v[204:207], v154 offset:37888
	ds_read_b128 v[208:211], v154 offset:38912
	ds_read_b128 v[212:215], v154 offset:39936
	global_load_lds_dwordx4 v[224:225], off
	v_lshl_add_u64 v[224:225], s[30:31], 0, v[132:133]
	s_mov_b32 m0, s39
	s_nop 0
	global_load_lds_dwordx4 v[224:225], off
	s_waitcnt vmcnt(8)
	s_waitcnt lgkmcnt(0)
	s_setprio 1
	s_barrier
	v_mfma_f32_16x16x32_bf16 v[122:125], v[146:149], v[184:187], v[122:125]
	v_mfma_f32_16x16x32_bf16 v[118:121], v[160:163], v[184:187], v[118:121]
	v_mfma_f32_16x16x32_bf16 v[106:109], v[146:149], v[192:195], v[106:109]
	v_mfma_f32_16x16x32_bf16 v[102:105], v[160:163], v[192:195], v[102:105]
	v_mfma_f32_16x16x32_bf16 v[90:93], v[146:149], v[200:203], v[90:93]
	v_mfma_f32_16x16x32_bf16 v[86:89], v[160:163], v[200:203], v[86:89]
	v_mfma_f32_16x16x32_bf16 v[74:77], v[146:149], v[208:211], v[74:77]
	v_mfma_f32_16x16x32_bf16 v[70:73], v[160:163], v[208:211], v[70:73]
	s_setprio 0
	s_setprio 1
	v_mfma_f32_16x16x32_bf16 v[122:125], v[156:159], v[188:191], v[122:125]
	v_mfma_f32_16x16x32_bf16 v[118:121], v[164:167], v[188:191], v[118:121]
	v_mfma_f32_16x16x32_bf16 v[106:109], v[156:159], v[196:199], v[106:109]
	v_mfma_f32_16x16x32_bf16 v[102:105], v[164:167], v[196:199], v[102:105]
	v_mfma_f32_16x16x32_bf16 v[90:93], v[156:159], v[204:207], v[90:93]
	v_mfma_f32_16x16x32_bf16 v[86:89], v[164:167], v[204:207], v[86:89]
	v_mfma_f32_16x16x32_bf16 v[74:77], v[156:159], v[212:215], v[74:77]
	v_mfma_f32_16x16x32_bf16 v[70:73], v[164:167], v[212:215], v[70:73]
	s_setprio 0
	s_setprio 1
	v_mfma_f32_16x16x32_bf16 v[126:129], v[168:171], v[184:187], v[126:129]
	v_mfma_f32_16x16x32_bf16 v[114:117], v[176:179], v[184:187], v[114:117]
	v_mfma_f32_16x16x32_bf16 v[110:113], v[168:171], v[192:195], v[110:113]
	v_mfma_f32_16x16x32_bf16 v[98:101], v[176:179], v[192:195], v[98:101]
	v_mfma_f32_16x16x32_bf16 v[94:97], v[168:171], v[200:203], v[94:97]
	v_mfma_f32_16x16x32_bf16 v[82:85], v[176:179], v[200:203], v[82:85]
	v_mfma_f32_16x16x32_bf16 v[78:81], v[168:171], v[208:211], v[78:81]
	v_mfma_f32_16x16x32_bf16 v[66:69], v[176:179], v[208:211], v[66:69]
	s_setprio 0
	s_setprio 1
	v_mfma_f32_16x16x32_bf16 v[126:129], v[172:175], v[188:191], v[126:129]
	v_mfma_f32_16x16x32_bf16 v[114:117], v[180:183], v[188:191], v[114:117]
	v_mfma_f32_16x16x32_bf16 v[110:113], v[172:175], v[196:199], v[110:113]
	v_mfma_f32_16x16x32_bf16 v[98:101], v[180:183], v[196:199], v[98:101]
	v_mfma_f32_16x16x32_bf16 v[94:97], v[172:175], v[204:207], v[94:97]
	v_mfma_f32_16x16x32_bf16 v[82:85], v[180:183], v[204:207], v[82:85]
	v_mfma_f32_16x16x32_bf16 v[78:81], v[172:175], v[212:215], v[78:81]
	v_mfma_f32_16x16x32_bf16 v[66:69], v[180:183], v[212:215], v[66:69]
	s_barrier
	s_setprio 0
	s_add_i32 s30, s55, s34
	v_lshl_add_u64 v[216:217], v[216:217], 0, s[12:13]
	s_mov_b32 m0, s30
	ds_read_b128 v[184:187], v154 offset:49152
	ds_read_b128 v[188:191], v154 offset:50176
	ds_read_b128 v[192:195], v154 offset:51200
	ds_read_b128 v[196:199], v154 offset:52224
	ds_read_b128 v[200:203], v154 offset:53248
	ds_read_b128 v[204:207], v154 offset:54272
	ds_read_b128 v[208:211], v154 offset:55296
	ds_read_b128 v[212:215], v154 offset:56320
	global_load_lds_dwordx4 v[216:217], off
	s_add_i32 m0, s30, 0x2000
	s_add_u32 s28, s28, 0x80080
	v_lshl_add_u64 v[216:217], v[218:219], 0, s[12:13]
	s_addc_u32 s29, s29, 0
	s_add_i32 s30, s56, s34
	global_load_lds_dwordx4 v[216:217], off
	v_lshl_add_u64 v[216:217], s[28:29], 0, v[134:135]
	s_mov_b32 m0, s30
	s_nop 0
	global_load_lds_dwordx4 v[216:217], off
	v_lshl_add_u64 v[216:217], s[28:29], 0, v[130:131]
	s_add_i32 m0, s30, 0x2000
	s_nop 0
	global_load_lds_dwordx4 v[216:217], off
	v_lshl_add_u64 v[216:217], v[220:221], 0, s[12:13]
	s_mov_b32 m0, s42
	s_nop 0
	global_load_lds_dwordx4 v[216:217], off
	v_lshl_add_u64 v[216:217], v[222:223], 0, s[12:13]
	s_mov_b32 m0, s43
	s_nop 0
	global_load_lds_dwordx4 v[216:217], off
	s_waitcnt vmcnt(8)
	s_waitcnt lgkmcnt(0)
	s_setprio 1
	s_barrier
	v_mfma_f32_16x16x32_bf16 v[58:61], v[146:149], v[184:187], v[58:61]
	v_mfma_f32_16x16x32_bf16 v[54:57], v[160:163], v[184:187], v[54:57]
	v_mfma_f32_16x16x32_bf16 v[42:45], v[146:149], v[192:195], v[42:45]
	v_mfma_f32_16x16x32_bf16 v[38:41], v[160:163], v[192:195], v[38:41]
	v_mfma_f32_16x16x32_bf16 v[26:29], v[146:149], v[200:203], v[26:29]
	v_mfma_f32_16x16x32_bf16 v[22:25], v[160:163], v[200:203], v[22:25]
	v_mfma_f32_16x16x32_bf16 v[10:13], v[146:149], v[208:211], v[10:13]
	v_mfma_f32_16x16x32_bf16 v[6:9], v[160:163], v[208:211], v[6:9]
	s_setprio 0
	s_setprio 1
	v_mfma_f32_16x16x32_bf16 v[58:61], v[156:159], v[188:191], v[58:61]
	v_mfma_f32_16x16x32_bf16 v[54:57], v[164:167], v[188:191], v[54:57]
	v_mfma_f32_16x16x32_bf16 v[42:45], v[156:159], v[196:199], v[42:45]
	v_mfma_f32_16x16x32_bf16 v[38:41], v[164:167], v[196:199], v[38:41]
	v_mfma_f32_16x16x32_bf16 v[26:29], v[156:159], v[204:207], v[26:29]
	v_mfma_f32_16x16x32_bf16 v[22:25], v[164:167], v[204:207], v[22:25]
	v_mfma_f32_16x16x32_bf16 v[10:13], v[156:159], v[212:215], v[10:13]
	v_mfma_f32_16x16x32_bf16 v[6:9], v[164:167], v[212:215], v[6:9]
	s_setprio 0
	s_setprio 1
	v_mfma_f32_16x16x32_bf16 v[62:65], v[168:171], v[184:187], v[62:65]
	v_mfma_f32_16x16x32_bf16 v[50:53], v[176:179], v[184:187], v[50:53]
	v_mfma_f32_16x16x32_bf16 v[46:49], v[168:171], v[192:195], v[46:49]
	v_mfma_f32_16x16x32_bf16 v[34:37], v[176:179], v[192:195], v[34:37]
	v_mfma_f32_16x16x32_bf16 v[30:33], v[168:171], v[200:203], v[30:33]
	v_mfma_f32_16x16x32_bf16 v[18:21], v[176:179], v[200:203], v[18:21]
	v_mfma_f32_16x16x32_bf16 v[14:17], v[168:171], v[208:211], v[14:17]
	v_mfma_f32_16x16x32_bf16 v[2:5], v[176:179], v[208:211], v[2:5]
	s_setprio 0
	s_setprio 1
	v_mfma_f32_16x16x32_bf16 v[62:65], v[172:175], v[188:191], v[62:65]
	v_mfma_f32_16x16x32_bf16 v[50:53], v[180:183], v[188:191], v[50:53]
	v_mfma_f32_16x16x32_bf16 v[46:49], v[172:175], v[196:199], v[46:49]
	v_mfma_f32_16x16x32_bf16 v[34:37], v[180:183], v[196:199], v[34:37]
	v_mfma_f32_16x16x32_bf16 v[30:33], v[172:175], v[204:207], v[30:33]
	v_mfma_f32_16x16x32_bf16 v[18:21], v[180:183], v[204:207], v[18:21]
	v_mfma_f32_16x16x32_bf16 v[14:17], v[172:175], v[212:215], v[14:17]
	v_mfma_f32_16x16x32_bf16 v[2:5], v[180:183], v[212:215], v[2:5]
	s_barrier
	s_setprio 0
	s_add_i32 s54, s54, 2
	s_add_u32 s52, s52, 0x100
	s_addc_u32 s53, s53, 0
	s_add_u32 s26, s26, 0x100
	s_addc_u32 s27, s27, 0
	s_cmp_gt_u32 s54, 29
	s_cbranch_scc0 .LBB0_1840
	s_and_b64 vcc, exec, s[14:15]
	s_cbranch_vccz .LBB0_1843
	s_barrier

.LBB0_1919:
	ds_read_b128 v[82:85], v220
	ds_read_b128 v[86:89], v220 offset:1024
	ds_read_b128 v[106:109], v220 offset:2048
	ds_read_b128 v[110:113], v220 offset:3072
	ds_read_b128 v[146:149], v221
	ds_read_b128 v[150:153], v221 offset:1024
	ds_read_b128 v[154:157], v221 offset:2048
	ds_read_b128 v[158:161], v221 offset:3072
	s_add_u32 s6, s8, 0x100
	s_addc_u32 s7, s9, 0
	s_cmpk_eq_i32 s61, 0x54
	s_cselect_b32 s13, s39, s7
	s_cselect_b32 s12, s38, s6
	s_cselect_b32 s11, s41, s18
	s_cselect_b32 s10, s40, s15
	v_lshl_add_u64 v[208:209], s[8:9], 0, v[180:181]
	s_add_i32 m0, s44, 0xc000
	ds_read_b128 v[162:165], v222
	ds_read_b128 v[166:169], v222 offset:1024
	ds_read_b128 v[184:187], v222 offset:2048
	ds_read_b128 v[188:191], v222 offset:3072
	ds_read_b128 v[192:195], v222 offset:4096
	ds_read_b128 v[196:199], v222 offset:5120
	ds_read_b128 v[200:203], v222 offset:6144
	ds_read_b128 v[204:207], v222 offset:7168
	global_load_lds_dwordx4 v[208:209], off
	v_lshl_add_u64 v[208:209], s[8:9], 0, v[178:179]
	s_add_i32 m0, s44, 0xe000
	s_nop 0
	global_load_lds_dwordx4 v[208:209], off
	s_waitcnt vmcnt(8)
	s_waitcnt lgkmcnt(0)
	s_setprio 1
	s_barrier
	v_mfma_f32_16x16x32_bf16 v[142:145], v[82:85], v[162:165], v[142:145]
	v_mfma_f32_16x16x32_bf16 v[138:141], v[106:109], v[162:165], v[138:141]
	v_mfma_f32_16x16x32_bf16 v[126:129], v[82:85], v[184:187], v[126:129]
	v_mfma_f32_16x16x32_bf16 v[122:125], v[106:109], v[184:187], v[122:125]
	v_mfma_f32_16x16x32_bf16 v[102:105], v[82:85], v[192:195], v[102:105]
	v_mfma_f32_16x16x32_bf16 v[98:101], v[106:109], v[192:195], v[98:101]
	v_mfma_f32_16x16x32_bf16 v[78:81], v[82:85], v[200:203], v[78:81]
	v_mfma_f32_16x16x32_bf16 v[74:77], v[106:109], v[200:203], v[74:77]
	s_setprio 0
	s_setprio 1
	v_mfma_f32_16x16x32_bf16 v[142:145], v[86:89], v[166:169], v[142:145]
	v_mfma_f32_16x16x32_bf16 v[138:141], v[110:113], v[166:169], v[138:141]
	v_mfma_f32_16x16x32_bf16 v[126:129], v[86:89], v[188:191], v[126:129]
	v_mfma_f32_16x16x32_bf16 v[122:125], v[110:113], v[188:191], v[122:125]
	v_mfma_f32_16x16x32_bf16 v[102:105], v[86:89], v[196:199], v[102:105]
	v_mfma_f32_16x16x32_bf16 v[98:101], v[110:113], v[196:199], v[98:101]
	v_mfma_f32_16x16x32_bf16 v[78:81], v[86:89], v[204:207], v[78:81]
	v_mfma_f32_16x16x32_bf16 v[74:77], v[110:113], v[204:207], v[74:77]
	s_setprio 0
	s_setprio 1
	v_mfma_f32_16x16x32_bf16 v[134:137], v[146:149], v[162:165], v[134:137]
	v_mfma_f32_16x16x32_bf16 v[130:133], v[154:157], v[162:165], v[130:133]
	v_mfma_f32_16x16x32_bf16 v[118:121], v[146:149], v[184:187], v[118:121]
	v_mfma_f32_16x16x32_bf16 v[114:117], v[154:157], v[184:187], v[114:117]
	v_mfma_f32_16x16x32_bf16 v[94:97], v[146:149], v[192:195], v[94:97]
	v_mfma_f32_16x16x32_bf16 v[90:93], v[154:157], v[192:195], v[90:93]
	v_mfma_f32_16x16x32_bf16 v[70:73], v[146:149], v[200:203], v[70:73]
	v_mfma_f32_16x16x32_bf16 v[66:69], v[154:157], v[200:203], v[66:69]
	s_setprio 0
	s_setprio 1
	v_mfma_f32_16x16x32_bf16 v[134:137], v[150:153], v[166:169], v[134:137]
	v_mfma_f32_16x16x32_bf16 v[130:133], v[158:161], v[166:169], v[130:133]
	v_mfma_f32_16x16x32_bf16 v[118:121], v[150:153], v[188:191], v[118:121]
	v_mfma_f32_16x16x32_bf16 v[114:117], v[158:161], v[188:191], v[114:117]
	v_mfma_f32_16x16x32_bf16 v[94:97], v[150:153], v[196:199], v[94:97]
	v_mfma_f32_16x16x32_bf16 v[90:93], v[158:161], v[196:199], v[90:93]
	v_mfma_f32_16x16x32_bf16 v[70:73], v[150:153], v[204:207], v[70:73]
	v_mfma_f32_16x16x32_bf16 v[66:69], v[158:161], v[204:207], v[66:69]
	s_barrier
	s_setprio 0
	s_add_i32 s8, s55, s43
	v_lshl_add_u64 v[208:209], s[10:11], 0, v[172:173]
	s_mov_b32 m0, s8
	ds_read_b128 v[162:165], v222 offset:16384
	ds_read_b128 v[166:169], v222 offset:17408
	ds_read_b128 v[184:187], v222 offset:18432
	ds_read_b128 v[188:191], v222 offset:19456
	ds_read_b128 v[192:195], v222 offset:20480
	ds_read_b128 v[196:199], v222 offset:21504
	ds_read_b128 v[200:203], v222 offset:22528
	ds_read_b128 v[204:207], v222 offset:23552
	global_load_lds_dwordx4 v[208:209], off
	s_add_i32 m0, s8, 0x2000
	s_add_u32 s8, s10, 0x160000
	v_lshl_add_u64 v[210:211], s[10:11], 0, v[176:177]
	s_addc_u32 s9, s11, 0
	s_add_i32 s62, s56, s43
	global_load_lds_dwordx4 v[210:211], off
	v_lshl_add_u64 v[212:213], s[8:9], 0, v[172:173]
	s_mov_b32 m0, s62
	v_lshl_add_u64 v[214:215], s[12:13], 0, v[174:175]
	global_load_lds_dwordx4 v[212:213], off
	v_lshl_add_u64 v[212:213], s[8:9], 0, v[176:177]
	s_add_i32 m0, s62, 0x2000
	s_nop 0
	global_load_lds_dwordx4 v[212:213], off
	v_lshl_add_u64 v[212:213], s[12:13], 0, v[170:171]
	s_mov_b32 m0, s44
	s_nop 0
	global_load_lds_dwordx4 v[212:213], off
	s_mov_b32 m0, s45
	s_nop 0
	global_load_lds_dwordx4 v[214:215], off
	s_waitcnt vmcnt(8)
	s_waitcnt lgkmcnt(0)
	s_setprio 1
	s_barrier
	v_mfma_f32_16x16x32_bf16 v[62:65], v[82:85], v[162:165], v[62:65]
	v_mfma_f32_16x16x32_bf16 v[58:61], v[106:109], v[162:165], v[58:61]
	v_mfma_f32_16x16x32_bf16 v[46:49], v[82:85], v[184:187], v[46:49]
	v_mfma_f32_16x16x32_bf16 v[42:45], v[106:109], v[184:187], v[42:45]
	v_mfma_f32_16x16x32_bf16 v[30:33], v[82:85], v[192:195], v[30:33]
	v_mfma_f32_16x16x32_bf16 v[26:29], v[106:109], v[192:195], v[26:29]
	v_mfma_f32_16x16x32_bf16 v[14:17], v[82:85], v[200:203], v[14:17]
	v_mfma_f32_16x16x32_bf16 v[10:13], v[106:109], v[200:203], v[10:13]
	s_setprio 0
	s_setprio 1
	v_mfma_f32_16x16x32_bf16 v[62:65], v[86:89], v[166:169], v[62:65]
	v_mfma_f32_16x16x32_bf16 v[58:61], v[110:113], v[166:169], v[58:61]
	v_mfma_f32_16x16x32_bf16 v[46:49], v[86:89], v[188:191], v[46:49]
	v_mfma_f32_16x16x32_bf16 v[42:45], v[110:113], v[188:191], v[42:45]
	v_mfma_f32_16x16x32_bf16 v[30:33], v[86:89], v[196:199], v[30:33]
	v_mfma_f32_16x16x32_bf16 v[26:29], v[110:113], v[196:199], v[26:29]
	v_mfma_f32_16x16x32_bf16 v[14:17], v[86:89], v[204:207], v[14:17]
	v_mfma_f32_16x16x32_bf16 v[10:13], v[110:113], v[204:207], v[10:13]
	s_setprio 0
	s_setprio 1
	v_mfma_f32_16x16x32_bf16 v[54:57], v[146:149], v[162:165], v[54:57]
	v_mfma_f32_16x16x32_bf16 v[50:53], v[154:157], v[162:165], v[50:53]
	v_mfma_f32_16x16x32_bf16 v[38:41], v[146:149], v[184:187], v[38:41]
	v_mfma_f32_16x16x32_bf16 v[34:37], v[154:157], v[184:187], v[34:37]
	v_mfma_f32_16x16x32_bf16 v[22:25], v[146:149], v[192:195], v[22:25]
	v_mfma_f32_16x16x32_bf16 v[18:21], v[154:157], v[192:195], v[18:21]
	v_mfma_f32_16x16x32_bf16 v[6:9], v[146:149], v[200:203], v[6:9]
	v_mfma_f32_16x16x32_bf16 v[2:5], v[154:157], v[200:203], v[2:5]
	s_setprio 0
	s_setprio 1
	v_mfma_f32_16x16x32_bf16 v[54:57], v[150:153], v[166:169], v[54:57]
	v_mfma_f32_16x16x32_bf16 v[50:53], v[158:161], v[166:169], v[50:53]
	v_mfma_f32_16x16x32_bf16 v[38:41], v[150:153], v[188:191], v[38:41]
	v_mfma_f32_16x16x32_bf16 v[34:37], v[158:161], v[188:191], v[34:37]
	v_mfma_f32_16x16x32_bf16 v[22:25], v[150:153], v[196:199], v[22:25]
	v_mfma_f32_16x16x32_bf16 v[18:21], v[158:161], v[196:199], v[18:21]
	v_mfma_f32_16x16x32_bf16 v[6:9], v[150:153], v[204:207], v[6:9]
	v_mfma_f32_16x16x32_bf16 v[2:5], v[158:161], v[204:207], v[2:5]
	s_barrier
	s_setprio 0
	s_add_i32 s62, 0, 0x18000
	s_add_i32 s63, 0, 0x1c000
	v_add_u32_e32 v110, s62, v219
	v_add_u32_e32 v158, s63, v219
	ds_read_b128 v[82:85], v110
	ds_read_b128 v[86:89], v110 offset:1024
	ds_read_b128 v[106:109], v110 offset:2048
	ds_read_b128 v[110:113], v110 offset:3072
	ds_read_b128 v[146:149], v158
	ds_read_b128 v[150:153], v158 offset:1024
	ds_read_b128 v[154:157], v158 offset:2048
	ds_read_b128 v[158:161], v158 offset:3072
	s_add_u32 s8, s12, 0x160000
	s_addc_u32 s9, s13, 0
	s_mov_b32 m0, s46
	v_lshl_add_u64 v[216:217], s[8:9], 0, v[170:171]
	ds_read_b128 v[162:165], v222 offset:32768
	ds_read_b128 v[166:169], v222 offset:33792
	ds_read_b128 v[184:187], v222 offset:34816
	ds_read_b128 v[188:191], v222 offset:35840
	ds_read_b128 v[192:195], v222 offset:36864
	ds_read_b128 v[196:199], v222 offset:37888
	ds_read_b128 v[200:203], v222 offset:38912
	ds_read_b128 v[204:207], v222 offset:39936
	global_load_lds_dwordx4 v[216:217], off
	v_lshl_add_u64 v[216:217], s[8:9], 0, v[174:175]
	s_mov_b32 m0, s47
	s_nop 0
	global_load_lds_dwordx4 v[216:217], off
	s_waitcnt vmcnt(8)
	s_waitcnt lgkmcnt(0)
	s_setprio 1
	s_barrier
	v_mfma_f32_16x16x32_bf16 v[142:145], v[82:85], v[162:165], v[142:145]
	v_mfma_f32_16x16x32_bf16 v[138:141], v[106:109], v[162:165], v[138:141]
	v_mfma_f32_16x16x32_bf16 v[126:129], v[82:85], v[184:187], v[126:129]
	v_mfma_f32_16x16x32_bf16 v[122:125], v[106:109], v[184:187], v[122:125]
	v_mfma_f32_16x16x32_bf16 v[102:105], v[82:85], v[192:195], v[102:105]
	v_mfma_f32_16x16x32_bf16 v[98:101], v[106:109], v[192:195], v[98:101]
	v_mfma_f32_16x16x32_bf16 v[78:81], v[82:85], v[200:203], v[78:81]
	v_mfma_f32_16x16x32_bf16 v[74:77], v[106:109], v[200:203], v[74:77]
	s_setprio 0
	s_setprio 1
	v_mfma_f32_16x16x32_bf16 v[142:145], v[86:89], v[166:169], v[142:145]
	v_mfma_f32_16x16x32_bf16 v[138:141], v[110:113], v[166:169], v[138:141]
	v_mfma_f32_16x16x32_bf16 v[126:129], v[86:89], v[188:191], v[126:129]
	v_mfma_f32_16x16x32_bf16 v[122:125], v[110:113], v[188:191], v[122:125]
	v_mfma_f32_16x16x32_bf16 v[102:105], v[86:89], v[196:199], v[102:105]
	v_mfma_f32_16x16x32_bf16 v[98:101], v[110:113], v[196:199], v[98:101]
	v_mfma_f32_16x16x32_bf16 v[78:81], v[86:89], v[204:207], v[78:81]
	v_mfma_f32_16x16x32_bf16 v[74:77], v[110:113], v[204:207], v[74:77]
	s_setprio 0
	s_setprio 1
	v_mfma_f32_16x16x32_bf16 v[134:137], v[146:149], v[162:165], v[134:137]
	v_mfma_f32_16x16x32_bf16 v[130:133], v[154:157], v[162:165], v[130:133]
	v_mfma_f32_16x16x32_bf16 v[118:121], v[146:149], v[184:187], v[118:121]
	v_mfma_f32_16x16x32_bf16 v[114:117], v[154:157], v[184:187], v[114:117]
	v_mfma_f32_16x16x32_bf16 v[94:97], v[146:149], v[192:195], v[94:97]
	v_mfma_f32_16x16x32_bf16 v[90:93], v[154:157], v[192:195], v[90:93]
	v_mfma_f32_16x16x32_bf16 v[70:73], v[146:149], v[200:203], v[70:73]
	v_mfma_f32_16x16x32_bf16 v[66:69], v[154:157], v[200:203], v[66:69]
	s_setprio 0
	s_setprio 1
	v_mfma_f32_16x16x32_bf16 v[134:137], v[150:153], v[166:169], v[134:137]
	v_mfma_f32_16x16x32_bf16 v[130:133], v[158:161], v[166:169], v[130:133]
	v_mfma_f32_16x16x32_bf16 v[118:121], v[150:153], v[188:191], v[118:121]
	v_mfma_f32_16x16x32_bf16 v[114:117], v[158:161], v[188:191], v[114:117]
	v_mfma_f32_16x16x32_bf16 v[94:97], v[150:153], v[196:199], v[94:97]
	v_mfma_f32_16x16x32_bf16 v[90:93], v[158:161], v[196:199], v[90:93]
	v_mfma_f32_16x16x32_bf16 v[70:73], v[150:153], v[204:207], v[70:73]
	v_mfma_f32_16x16x32_bf16 v[66:69], v[158:161], v[204:207], v[66:69]
	s_barrier
	s_setprio 0
	s_add_i32 s8, s62, s43
	v_lshl_add_u64 v[208:209], v[208:209], 0, s[30:31]
	s_mov_b32 m0, s8
	ds_read_b128 v[162:165], v222 offset:49152
	ds_read_b128 v[166:169], v222 offset:50176
	ds_read_b128 v[184:187], v222 offset:51200
	ds_read_b128 v[188:191], v222 offset:52224
	ds_read_b128 v[192:195], v222 offset:53248
	ds_read_b128 v[196:199], v222 offset:54272
	ds_read_b128 v[200:203], v222 offset:55296
	ds_read_b128 v[204:207], v222 offset:56320
	global_load_lds_dwordx4 v[208:209], off
	s_add_i32 m0, s8, 0x2000
	s_add_u32 s8, s10, 0x160080
	v_lshl_add_u64 v[208:209], v[210:211], 0, s[30:31]
	s_addc_u32 s9, s11, 0
	s_add_i32 s10, s63, s43
	global_load_lds_dwordx4 v[208:209], off
	v_lshl_add_u64 v[208:209], s[8:9], 0, v[172:173]
	s_mov_b32 m0, s10
	s_nop 0
	global_load_lds_dwordx4 v[208:209], off
	v_lshl_add_u64 v[208:209], s[8:9], 0, v[176:177]
	s_add_i32 m0, s10, 0x2000
	s_nop 0
	global_load_lds_dwordx4 v[208:209], off
	v_lshl_add_u64 v[208:209], v[212:213], 0, s[30:31]
	s_mov_b32 m0, s51
	s_nop 0
	global_load_lds_dwordx4 v[208:209], off
	v_lshl_add_u64 v[208:209], v[214:215], 0, s[30:31]
	s_mov_b32 m0, s52
	s_nop 0
	global_load_lds_dwordx4 v[208:209], off
	s_waitcnt vmcnt(8)
	s_waitcnt lgkmcnt(0)
	s_setprio 1
	s_barrier
	v_mfma_f32_16x16x32_bf16 v[62:65], v[82:85], v[162:165], v[62:65]
	v_mfma_f32_16x16x32_bf16 v[58:61], v[106:109], v[162:165], v[58:61]
	v_mfma_f32_16x16x32_bf16 v[46:49], v[82:85], v[184:187], v[46:49]
	v_mfma_f32_16x16x32_bf16 v[42:45], v[106:109], v[184:187], v[42:45]
	v_mfma_f32_16x16x32_bf16 v[30:33], v[82:85], v[192:195], v[30:33]
	v_mfma_f32_16x16x32_bf16 v[26:29], v[106:109], v[192:195], v[26:29]
	v_mfma_f32_16x16x32_bf16 v[14:17], v[82:85], v[200:203], v[14:17]
	v_mfma_f32_16x16x32_bf16 v[10:13], v[106:109], v[200:203], v[10:13]
	s_setprio 0
	s_setprio 1
	v_mfma_f32_16x16x32_bf16 v[62:65], v[86:89], v[166:169], v[62:65]
	v_mfma_f32_16x16x32_bf16 v[58:61], v[110:113], v[166:169], v[58:61]
	v_mfma_f32_16x16x32_bf16 v[46:49], v[86:89], v[188:191], v[46:49]
	v_mfma_f32_16x16x32_bf16 v[42:45], v[110:113], v[188:191], v[42:45]
	v_mfma_f32_16x16x32_bf16 v[30:33], v[86:89], v[196:199], v[30:33]
	v_mfma_f32_16x16x32_bf16 v[26:29], v[110:113], v[196:199], v[26:29]
	v_mfma_f32_16x16x32_bf16 v[14:17], v[86:89], v[204:207], v[14:17]
	v_mfma_f32_16x16x32_bf16 v[10:13], v[110:113], v[204:207], v[10:13]
	s_setprio 0
	s_setprio 1
	v_mfma_f32_16x16x32_bf16 v[54:57], v[146:149], v[162:165], v[54:57]
	v_mfma_f32_16x16x32_bf16 v[50:53], v[154:157], v[162:165], v[50:53]
	v_mfma_f32_16x16x32_bf16 v[38:41], v[146:149], v[184:187], v[38:41]
	v_mfma_f32_16x16x32_bf16 v[34:37], v[154:157], v[184:187], v[34:37]
	v_mfma_f32_16x16x32_bf16 v[22:25], v[146:149], v[192:195], v[22:25]
	v_mfma_f32_16x16x32_bf16 v[18:21], v[154:157], v[192:195], v[18:21]
	v_mfma_f32_16x16x32_bf16 v[6:9], v[146:149], v[200:203], v[6:9]
	v_mfma_f32_16x16x32_bf16 v[2:5], v[154:157], v[200:203], v[2:5]
	s_setprio 0
	s_setprio 1
	v_mfma_f32_16x16x32_bf16 v[54:57], v[150:153], v[166:169], v[54:57]
	v_mfma_f32_16x16x32_bf16 v[50:53], v[158:161], v[166:169], v[50:53]
	v_mfma_f32_16x16x32_bf16 v[38:41], v[150:153], v[188:191], v[38:41]
	v_mfma_f32_16x16x32_bf16 v[34:37], v[158:161], v[188:191], v[34:37]
	v_mfma_f32_16x16x32_bf16 v[22:25], v[150:153], v[196:199], v[22:25]
	v_mfma_f32_16x16x32_bf16 v[18:21], v[158:161], v[196:199], v[18:21]
	v_mfma_f32_16x16x32_bf16 v[6:9], v[150:153], v[204:207], v[6:9]
	v_mfma_f32_16x16x32_bf16 v[2:5], v[158:161], v[204:207], v[2:5]
	s_barrier
	s_setprio 0
	s_add_i32 s61, s61, 2
	s_add_u32 s15, s15, 0x100
	s_addc_u32 s18, s18, 0
	s_cmpk_gt_u32 s61, 0x55
	s_mov_b64 s[8:9], s[6:7]
	s_cbranch_scc0 .LBB0_1919
	s_and_b64 vcc, exec, s[36:37]
	s_cbranch_vccz .LBB0_1922
	s_barrier

.LBB0_1945:
	ds_read_b128 v[148:151], v143
	ds_read_b128 v[152:155], v143 offset:1024
	ds_read_b128 v[156:159], v143 offset:2048
	ds_read_b128 v[160:163], v143 offset:3072
	ds_read_b128 v[164:167], v144
	ds_read_b128 v[168:171], v144 offset:1024
	ds_read_b128 v[172:175], v144 offset:2048
	ds_read_b128 v[176:179], v144 offset:3072
	s_add_u32 s10, s8, 0x100
	s_addc_u32 s11, s9, 0
	s_cmp_lg_u32 s27, 18
	s_cselect_b32 s12, s10, 0
	s_cselect_b32 s13, s11, 0
	s_add_u32 s14, s4, s12
	s_addc_u32 s15, s5, s13
	s_add_u32 s12, s2, s12
	s_addc_u32 s13, s3, s13
	s_mov_b32 m0, s28
	v_lshl_add_u64 v[212:213], v[140:141], 0, s[8:9]
	ds_read_b128 v[180:183], v145
	ds_read_b128 v[184:187], v145 offset:1024
	ds_read_b128 v[188:191], v145 offset:2048
	ds_read_b128 v[192:195], v145 offset:3072
	ds_read_b128 v[196:199], v145 offset:4096
	ds_read_b128 v[200:203], v145 offset:5120
	ds_read_b128 v[204:207], v145 offset:6144
	ds_read_b128 v[208:211], v145 offset:7168
	global_load_lds_dwordx4 v[212:213], off
	v_lshl_add_u64 v[212:213], v[138:139], 0, s[8:9]
	s_mov_b32 m0, s29
	s_nop 0
	global_load_lds_dwordx4 v[212:213], off
	s_waitcnt vmcnt(8)
	s_waitcnt lgkmcnt(0)
	s_setprio 1
	s_barrier
	v_mfma_f32_16x16x32_bf16 v[126:129], v[148:151], v[180:183], v[126:129]
	v_mfma_f32_16x16x32_bf16 v[122:125], v[156:159], v[180:183], v[122:125]
	v_mfma_f32_16x16x32_bf16 v[118:121], v[148:151], v[188:191], v[118:121]
	v_mfma_f32_16x16x32_bf16 v[114:117], v[156:159], v[188:191], v[114:117]
	v_mfma_f32_16x16x32_bf16 v[106:109], v[148:151], v[196:199], v[106:109]
	v_mfma_f32_16x16x32_bf16 v[98:101], v[156:159], v[196:199], v[98:101]
	v_mfma_f32_16x16x32_bf16 v[90:93], v[148:151], v[204:207], v[90:93]
	v_mfma_f32_16x16x32_bf16 v[82:85], v[156:159], v[204:207], v[82:85]
	s_setprio 0
	s_setprio 1
	v_mfma_f32_16x16x32_bf16 v[126:129], v[152:155], v[184:187], v[126:129]
	v_mfma_f32_16x16x32_bf16 v[122:125], v[160:163], v[184:187], v[122:125]
	v_mfma_f32_16x16x32_bf16 v[118:121], v[152:155], v[192:195], v[118:121]
	v_mfma_f32_16x16x32_bf16 v[114:117], v[160:163], v[192:195], v[114:117]
	v_mfma_f32_16x16x32_bf16 v[106:109], v[152:155], v[200:203], v[106:109]
	v_mfma_f32_16x16x32_bf16 v[98:101], v[160:163], v[200:203], v[98:101]
	v_mfma_f32_16x16x32_bf16 v[90:93], v[152:155], v[208:211], v[90:93]
	v_mfma_f32_16x16x32_bf16 v[82:85], v[160:163], v[208:211], v[82:85]
	s_setprio 0
	s_setprio 1
	v_mfma_f32_16x16x32_bf16 v[110:113], v[164:167], v[180:183], v[110:113]
	v_mfma_f32_16x16x32_bf16 v[102:105], v[172:175], v[180:183], v[102:105]
	v_mfma_f32_16x16x32_bf16 v[94:97], v[164:167], v[188:191], v[94:97]
	v_mfma_f32_16x16x32_bf16 v[86:89], v[172:175], v[188:191], v[86:89]
	v_mfma_f32_16x16x32_bf16 v[78:81], v[164:167], v[196:199], v[78:81]
	v_mfma_f32_16x16x32_bf16 v[74:77], v[172:175], v[196:199], v[74:77]
	v_mfma_f32_16x16x32_bf16 v[70:73], v[164:167], v[204:207], v[70:73]
	v_mfma_f32_16x16x32_bf16 v[66:69], v[172:175], v[204:207], v[66:69]
	s_setprio 0
	s_setprio 1
	v_mfma_f32_16x16x32_bf16 v[110:113], v[168:171], v[184:187], v[110:113]
	v_mfma_f32_16x16x32_bf16 v[102:105], v[176:179], v[184:187], v[102:105]
	v_mfma_f32_16x16x32_bf16 v[94:97], v[168:171], v[192:195], v[94:97]
	v_mfma_f32_16x16x32_bf16 v[86:89], v[176:179], v[192:195], v[86:89]
	v_mfma_f32_16x16x32_bf16 v[78:81], v[168:171], v[200:203], v[78:81]
	v_mfma_f32_16x16x32_bf16 v[74:77], v[176:179], v[200:203], v[74:77]
	v_mfma_f32_16x16x32_bf16 v[70:73], v[168:171], v[208:211], v[70:73]
	v_mfma_f32_16x16x32_bf16 v[66:69], v[176:179], v[208:211], v[66:69]
	s_barrier
	s_setprio 0
	s_mov_b32 m0, s30
	v_lshl_add_u64 v[212:213], s[12:13], 0, v[132:133]
	s_add_u32 s8, s12, 0x160000
	ds_read_b128 v[180:183], v145 offset:16384
	ds_read_b128 v[184:187], v145 offset:17408
	ds_read_b128 v[188:191], v145 offset:18432
	ds_read_b128 v[192:195], v145 offset:19456
	ds_read_b128 v[196:199], v145 offset:20480
	ds_read_b128 v[200:203], v145 offset:21504
	ds_read_b128 v[204:207], v145 offset:22528
	ds_read_b128 v[208:211], v145 offset:23552
	global_load_lds_dwordx4 v[212:213], off
	v_lshl_add_u64 v[214:215], s[12:13], 0, v[136:137]
	s_mov_b32 m0, s31
	s_addc_u32 s9, s13, 0
	global_load_lds_dwordx4 v[214:215], off
	v_lshl_add_u64 v[216:217], s[8:9], 0, v[132:133]
	s_mov_b32 m0, s33
	v_lshl_add_u64 v[218:219], s[14:15], 0, v[134:135]
	global_load_lds_dwordx4 v[216:217], off
	v_lshl_add_u64 v[216:217], s[8:9], 0, v[136:137]
	s_mov_b32 m0, s34
	s_nop 0
	global_load_lds_dwordx4 v[216:217], off
	v_lshl_add_u64 v[216:217], s[14:15], 0, v[130:131]
	s_mov_b32 m0, s19
	s_nop 0
	global_load_lds_dwordx4 v[216:217], off
	s_mov_b32 m0, s20
	s_nop 0
	global_load_lds_dwordx4 v[218:219], off
	s_waitcnt vmcnt(8)
	s_waitcnt lgkmcnt(0)
	s_setprio 1
	s_barrier
	v_mfma_f32_16x16x32_bf16 v[62:65], v[148:151], v[180:183], v[62:65]
	v_mfma_f32_16x16x32_bf16 v[58:61], v[156:159], v[180:183], v[58:61]
	v_mfma_f32_16x16x32_bf16 v[54:57], v[148:151], v[188:191], v[54:57]
	v_mfma_f32_16x16x32_bf16 v[50:53], v[156:159], v[188:191], v[50:53]
	v_mfma_f32_16x16x32_bf16 v[42:45], v[148:151], v[196:199], v[42:45]
	v_mfma_f32_16x16x32_bf16 v[34:37], v[156:159], v[196:199], v[34:37]
	v_mfma_f32_16x16x32_bf16 v[26:29], v[148:151], v[204:207], v[26:29]
	v_mfma_f32_16x16x32_bf16 v[18:21], v[156:159], v[204:207], v[18:21]
	s_setprio 0
	s_setprio 1
	v_mfma_f32_16x16x32_bf16 v[62:65], v[152:155], v[184:187], v[62:65]
	v_mfma_f32_16x16x32_bf16 v[58:61], v[160:163], v[184:187], v[58:61]
	v_mfma_f32_16x16x32_bf16 v[54:57], v[152:155], v[192:195], v[54:57]
	v_mfma_f32_16x16x32_bf16 v[50:53], v[160:163], v[192:195], v[50:53]
	v_mfma_f32_16x16x32_bf16 v[42:45], v[152:155], v[200:203], v[42:45]
	v_mfma_f32_16x16x32_bf16 v[34:37], v[160:163], v[200:203], v[34:37]
	v_mfma_f32_16x16x32_bf16 v[26:29], v[152:155], v[208:211], v[26:29]
	v_mfma_f32_16x16x32_bf16 v[18:21], v[160:163], v[208:211], v[18:21]
	s_setprio 0
	s_setprio 1
	v_mfma_f32_16x16x32_bf16 v[46:49], v[164:167], v[180:183], v[46:49]
	v_mfma_f32_16x16x32_bf16 v[38:41], v[172:175], v[180:183], v[38:41]
	v_mfma_f32_16x16x32_bf16 v[30:33], v[164:167], v[188:191], v[30:33]
	v_mfma_f32_16x16x32_bf16 v[22:25], v[172:175], v[188:191], v[22:25]
	v_mfma_f32_16x16x32_bf16 v[14:17], v[164:167], v[196:199], v[14:17]
	v_mfma_f32_16x16x32_bf16 v[10:13], v[172:175], v[196:199], v[10:13]
	v_mfma_f32_16x16x32_bf16 v[6:9], v[164:167], v[204:207], v[6:9]
	v_mfma_f32_16x16x32_bf16 v[2:5], v[172:175], v[204:207], v[2:5]
	s_setprio 0
	s_setprio 1
	v_mfma_f32_16x16x32_bf16 v[46:49], v[168:171], v[184:187], v[46:49]
	v_mfma_f32_16x16x32_bf16 v[38:41], v[176:179], v[184:187], v[38:41]
	v_mfma_f32_16x16x32_bf16 v[30:33], v[168:171], v[192:195], v[30:33]
	v_mfma_f32_16x16x32_bf16 v[22:25], v[176:179], v[192:195], v[22:25]
	v_mfma_f32_16x16x32_bf16 v[14:17], v[168:171], v[200:203], v[14:17]
	v_mfma_f32_16x16x32_bf16 v[10:13], v[176:179], v[200:203], v[10:13]
	v_mfma_f32_16x16x32_bf16 v[6:9], v[168:171], v[208:211], v[6:9]
	v_mfma_f32_16x16x32_bf16 v[2:5], v[176:179], v[208:211], v[2:5]
	s_barrier
	s_setprio 0
	ds_read_b128 v[148:151], v146
	ds_read_b128 v[152:155], v146 offset:1024
	ds_read_b128 v[156:159], v146 offset:2048
	ds_read_b128 v[160:163], v146 offset:3072
	ds_read_b128 v[164:167], v147
	ds_read_b128 v[168:171], v147 offset:1024
	ds_read_b128 v[172:175], v147 offset:2048
	ds_read_b128 v[176:179], v147 offset:3072
	s_add_u32 s8, s14, 0x160000
	s_addc_u32 s9, s15, 0
	s_mov_b32 m0, s21
	v_lshl_add_u64 v[220:221], s[8:9], 0, v[130:131]
	ds_read_b128 v[180:183], v145 offset:32768
	ds_read_b128 v[184:187], v145 offset:33792
	ds_read_b128 v[188:191], v145 offset:34816
	ds_read_b128 v[192:195], v145 offset:35840
	ds_read_b128 v[196:199], v145 offset:36864
	ds_read_b128 v[200:203], v145 offset:37888
	ds_read_b128 v[204:207], v145 offset:38912
	ds_read_b128 v[208:211], v145 offset:39936
	global_load_lds_dwordx4 v[220:221], off
	v_lshl_add_u64 v[220:221], s[8:9], 0, v[134:135]
	s_mov_b32 m0, s23
	s_nop 0
	global_load_lds_dwordx4 v[220:221], off
	s_waitcnt vmcnt(8)
	s_waitcnt lgkmcnt(0)
	s_setprio 1
	s_barrier
	v_mfma_f32_16x16x32_bf16 v[126:129], v[148:151], v[180:183], v[126:129]
	v_mfma_f32_16x16x32_bf16 v[122:125], v[156:159], v[180:183], v[122:125]
	v_mfma_f32_16x16x32_bf16 v[118:121], v[148:151], v[188:191], v[118:121]
	v_mfma_f32_16x16x32_bf16 v[114:117], v[156:159], v[188:191], v[114:117]
	v_mfma_f32_16x16x32_bf16 v[106:109], v[148:151], v[196:199], v[106:109]
	v_mfma_f32_16x16x32_bf16 v[98:101], v[156:159], v[196:199], v[98:101]
	v_mfma_f32_16x16x32_bf16 v[90:93], v[148:151], v[204:207], v[90:93]
	v_mfma_f32_16x16x32_bf16 v[82:85], v[156:159], v[204:207], v[82:85]
	s_setprio 0
	s_setprio 1
	v_mfma_f32_16x16x32_bf16 v[126:129], v[152:155], v[184:187], v[126:129]
	v_mfma_f32_16x16x32_bf16 v[122:125], v[160:163], v[184:187], v[122:125]
	v_mfma_f32_16x16x32_bf16 v[118:121], v[152:155], v[192:195], v[118:121]
	v_mfma_f32_16x16x32_bf16 v[114:117], v[160:163], v[192:195], v[114:117]
	v_mfma_f32_16x16x32_bf16 v[106:109], v[152:155], v[200:203], v[106:109]
	v_mfma_f32_16x16x32_bf16 v[98:101], v[160:163], v[200:203], v[98:101]
	v_mfma_f32_16x16x32_bf16 v[90:93], v[152:155], v[208:211], v[90:93]
	v_mfma_f32_16x16x32_bf16 v[82:85], v[160:163], v[208:211], v[82:85]
	s_setprio 0
	s_setprio 1
	v_mfma_f32_16x16x32_bf16 v[110:113], v[164:167], v[180:183], v[110:113]
	v_mfma_f32_16x16x32_bf16 v[102:105], v[172:175], v[180:183], v[102:105]
	v_mfma_f32_16x16x32_bf16 v[94:97], v[164:167], v[188:191], v[94:97]
	v_mfma_f32_16x16x32_bf16 v[86:89], v[172:175], v[188:191], v[86:89]
	v_mfma_f32_16x16x32_bf16 v[78:81], v[164:167], v[196:199], v[78:81]
	v_mfma_f32_16x16x32_bf16 v[74:77], v[172:175], v[196:199], v[74:77]
	v_mfma_f32_16x16x32_bf16 v[70:73], v[164:167], v[204:207], v[70:73]
	v_mfma_f32_16x16x32_bf16 v[66:69], v[172:175], v[204:207], v[66:69]
	s_setprio 0
	s_setprio 1
	v_mfma_f32_16x16x32_bf16 v[110:113], v[168:171], v[184:187], v[110:113]
	v_mfma_f32_16x16x32_bf16 v[102:105], v[176:179], v[184:187], v[102:105]
	v_mfma_f32_16x16x32_bf16 v[94:97], v[168:171], v[192:195], v[94:97]
	v_mfma_f32_16x16x32_bf16 v[86:89], v[176:179], v[192:195], v[86:89]
	v_mfma_f32_16x16x32_bf16 v[78:81], v[168:171], v[200:203], v[78:81]
	v_mfma_f32_16x16x32_bf16 v[74:77], v[176:179], v[200:203], v[74:77]
	v_mfma_f32_16x16x32_bf16 v[70:73], v[168:171], v[208:211], v[70:73]
	v_mfma_f32_16x16x32_bf16 v[66:69], v[176:179], v[208:211], v[66:69]
	s_barrier
	s_setprio 0
	s_mov_b32 m0, s35
	v_lshl_add_u64 v[212:213], v[212:213], 0, s[6:7]
	s_add_u32 s8, s12, 0x160080
	ds_read_b128 v[180:183], v145 offset:49152
	ds_read_b128 v[184:187], v145 offset:50176
	ds_read_b128 v[188:191], v145 offset:51200
	ds_read_b128 v[192:195], v145 offset:52224
	ds_read_b128 v[196:199], v145 offset:53248
	ds_read_b128 v[200:203], v145 offset:54272
	ds_read_b128 v[204:207], v145 offset:55296
	ds_read_b128 v[208:211], v145 offset:56320
	global_load_lds_dwordx4 v[212:213], off
	v_lshl_add_u64 v[212:213], v[214:215], 0, s[6:7]
	s_mov_b32 m0, s36
	s_addc_u32 s9, s13, 0
	global_load_lds_dwordx4 v[212:213], off
	v_lshl_add_u64 v[212:213], s[8:9], 0, v[132:133]
	s_mov_b32 m0, s37
	s_nop 0
	global_load_lds_dwordx4 v[212:213], off
	v_lshl_add_u64 v[212:213], s[8:9], 0, v[136:137]
	s_mov_b32 m0, s38
	s_nop 0
	global_load_lds_dwordx4 v[212:213], off
	v_lshl_add_u64 v[212:213], v[216:217], 0, s[6:7]
	s_mov_b32 m0, s25
	s_nop 0
	global_load_lds_dwordx4 v[212:213], off
	v_lshl_add_u64 v[212:213], v[218:219], 0, s[6:7]
	s_mov_b32 m0, s26
	s_nop 0
	global_load_lds_dwordx4 v[212:213], off
	s_waitcnt vmcnt(8)
	s_waitcnt lgkmcnt(0)
	s_setprio 1
	s_barrier
	v_mfma_f32_16x16x32_bf16 v[62:65], v[148:151], v[180:183], v[62:65]
	v_mfma_f32_16x16x32_bf16 v[58:61], v[156:159], v[180:183], v[58:61]
	v_mfma_f32_16x16x32_bf16 v[54:57], v[148:151], v[188:191], v[54:57]
	v_mfma_f32_16x16x32_bf16 v[50:53], v[156:159], v[188:191], v[50:53]
	v_mfma_f32_16x16x32_bf16 v[42:45], v[148:151], v[196:199], v[42:45]
	v_mfma_f32_16x16x32_bf16 v[34:37], v[156:159], v[196:199], v[34:37]
	v_mfma_f32_16x16x32_bf16 v[26:29], v[148:151], v[204:207], v[26:29]
	v_mfma_f32_16x16x32_bf16 v[18:21], v[156:159], v[204:207], v[18:21]
	s_setprio 0
	s_setprio 1
	v_mfma_f32_16x16x32_bf16 v[62:65], v[152:155], v[184:187], v[62:65]
	v_mfma_f32_16x16x32_bf16 v[58:61], v[160:163], v[184:187], v[58:61]
	v_mfma_f32_16x16x32_bf16 v[54:57], v[152:155], v[192:195], v[54:57]
	v_mfma_f32_16x16x32_bf16 v[50:53], v[160:163], v[192:195], v[50:53]
	v_mfma_f32_16x16x32_bf16 v[42:45], v[152:155], v[200:203], v[42:45]
	v_mfma_f32_16x16x32_bf16 v[34:37], v[160:163], v[200:203], v[34:37]
	v_mfma_f32_16x16x32_bf16 v[26:29], v[152:155], v[208:211], v[26:29]
	v_mfma_f32_16x16x32_bf16 v[18:21], v[160:163], v[208:211], v[18:21]
	s_setprio 0
	s_setprio 1
	v_mfma_f32_16x16x32_bf16 v[46:49], v[164:167], v[180:183], v[46:49]
	v_mfma_f32_16x16x32_bf16 v[38:41], v[172:175], v[180:183], v[38:41]
	v_mfma_f32_16x16x32_bf16 v[30:33], v[164:167], v[188:191], v[30:33]
	v_mfma_f32_16x16x32_bf16 v[22:25], v[172:175], v[188:191], v[22:25]
	v_mfma_f32_16x16x32_bf16 v[14:17], v[164:167], v[196:199], v[14:17]
	v_mfma_f32_16x16x32_bf16 v[10:13], v[172:175], v[196:199], v[10:13]
	v_mfma_f32_16x16x32_bf16 v[6:9], v[164:167], v[204:207], v[6:9]
	v_mfma_f32_16x16x32_bf16 v[2:5], v[172:175], v[204:207], v[2:5]
	s_setprio 0
	s_setprio 1
	v_mfma_f32_16x16x32_bf16 v[46:49], v[168:171], v[184:187], v[46:49]
	v_mfma_f32_16x16x32_bf16 v[38:41], v[176:179], v[184:187], v[38:41]
	v_mfma_f32_16x16x32_bf16 v[30:33], v[168:171], v[192:195], v[30:33]
	v_mfma_f32_16x16x32_bf16 v[22:25], v[176:179], v[192:195], v[22:25]
	v_mfma_f32_16x16x32_bf16 v[14:17], v[168:171], v[200:203], v[14:17]
	v_mfma_f32_16x16x32_bf16 v[10:13], v[176:179], v[200:203], v[10:13]
	v_mfma_f32_16x16x32_bf16 v[6:9], v[168:171], v[208:211], v[6:9]
	v_mfma_f32_16x16x32_bf16 v[2:5], v[176:179], v[208:211], v[2:5]
	s_barrier
	s_setprio 0
	s_add_i32 s27, s27, 2
	s_cmp_gt_u32 s27, 19
	s_mov_b64 s[8:9], s[10:11]
	s_cbranch_scc0 .LBB0_1945
	s_cmpk_lt_u32 s18, 0x100
	s_cbranch_scc0 .LBB0_1948
	s_barrier
